# v11 + MFMA segments trimmed: middle s_setprio 0/1 flip pair and the already-satisfied lgkmcnt(0) after the barrier removed (3 issue slots per 32-MFMA segment)
# speedup vs baseline: 1.0050x; 1.0050x over previous
.LBB0_472:
	ds_read_b128 v[152:155], v148
	ds_read_b128 v[156:159], v148 offset:1024
	ds_read_b128 v[166:169], v148 offset:2048
	ds_read_b128 v[170:173], v148 offset:3072
	ds_read_b128 v[174:177], v149
	ds_read_b128 v[178:181], v149 offset:1024
	ds_read_b128 v[182:185], v149 offset:2048
	ds_read_b128 v[186:189], v149 offset:3072
	s_add_u32 s44, s54, 0xfff00080
	s_addc_u32 s56, s55, -1
	s_cmp_eq_u32 s72, 60
	s_cselect_b32 s59, s17, s56
	s_cselect_b32 s58, s68, s44
	s_cselect_b32 s57, s15, s71
	s_cselect_b32 s56, s69, s70
	v_lshl_add_u64 v[160:161], s[54:55], 0, v[138:139]
	s_add_i32 m0, s41, 0xc000
	ds_read_b128 v[190:193], v150
	ds_read_b128 v[194:197], v150 offset:1024
	ds_read_b128 v[198:201], v150 offset:2048
	ds_read_b128 v[202:205], v150 offset:3072
	ds_read_b128 v[206:209], v150 offset:4096
	ds_read_b128 v[210:213], v150 offset:5120
	ds_read_b128 v[214:217], v150 offset:6144
	ds_read_b128 v[218:221], v150 offset:7168
	global_load_lds_dwordx4 v[160:161], off
	v_lshl_add_u64 v[160:161], s[54:55], 0, v[140:141]
	s_add_i32 m0, s41, 0xe000
	s_nop 0
	global_load_lds_dwordx4 v[160:161], off
	s_waitcnt vmcnt(8)
	s_waitcnt lgkmcnt(0)
	s_barrier
	s_setprio 1
	v_mfma_f32_16x16x32_bf16 v[126:129], v[152:155], v[190:193], v[126:129]
	v_mfma_f32_16x16x32_bf16 v[126:129], v[156:159], v[194:197], v[126:129]
	v_mfma_f32_16x16x32_bf16 v[122:125], v[170:173], v[194:197], v[122:125]
	v_mfma_f32_16x16x32_bf16 v[122:125], v[166:169], v[190:193], v[122:125]
	v_mfma_f32_16x16x32_bf16 v[110:113], v[166:169], v[198:201], v[110:113]
	v_mfma_f32_16x16x32_bf16 v[110:113], v[170:173], v[202:205], v[110:113]
	v_mfma_f32_16x16x32_bf16 v[118:121], v[156:159], v[202:205], v[118:121]
	v_mfma_f32_16x16x32_bf16 v[118:121], v[152:155], v[198:201], v[118:121]
	v_mfma_f32_16x16x32_bf16 v[102:105], v[152:155], v[206:209], v[102:105]
	v_mfma_f32_16x16x32_bf16 v[102:105], v[156:159], v[210:213], v[102:105]
	v_mfma_f32_16x16x32_bf16 v[94:97], v[170:173], v[210:213], v[94:97]
	v_mfma_f32_16x16x32_bf16 v[94:97], v[166:169], v[206:209], v[94:97]
	v_mfma_f32_16x16x32_bf16 v[78:81], v[166:169], v[214:217], v[78:81]
	v_mfma_f32_16x16x32_bf16 v[78:81], v[170:173], v[218:221], v[78:81]
	v_mfma_f32_16x16x32_bf16 v[86:89], v[156:159], v[218:221], v[86:89]
	v_mfma_f32_16x16x32_bf16 v[86:89], v[152:155], v[214:217], v[86:89]
	v_mfma_f32_16x16x32_bf16 v[114:117], v[174:177], v[190:193], v[114:117]
	v_mfma_f32_16x16x32_bf16 v[114:117], v[178:181], v[194:197], v[114:117]
	v_mfma_f32_16x16x32_bf16 v[106:109], v[186:189], v[194:197], v[106:109]
	v_mfma_f32_16x16x32_bf16 v[106:109], v[182:185], v[190:193], v[106:109]
	v_mfma_f32_16x16x32_bf16 v[90:93], v[182:185], v[198:201], v[90:93]
	v_mfma_f32_16x16x32_bf16 v[90:93], v[186:189], v[202:205], v[90:93]
	v_mfma_f32_16x16x32_bf16 v[98:101], v[178:181], v[202:205], v[98:101]
	v_mfma_f32_16x16x32_bf16 v[98:101], v[174:177], v[198:201], v[98:101]
	v_mfma_f32_16x16x32_bf16 v[82:85], v[174:177], v[206:209], v[82:85]
	v_mfma_f32_16x16x32_bf16 v[82:85], v[178:181], v[210:213], v[82:85]
	v_mfma_f32_16x16x32_bf16 v[74:77], v[186:189], v[210:213], v[74:77]
	v_mfma_f32_16x16x32_bf16 v[74:77], v[182:185], v[206:209], v[74:77]
	v_mfma_f32_16x16x32_bf16 v[66:69], v[182:185], v[214:217], v[66:69]
	v_mfma_f32_16x16x32_bf16 v[66:69], v[186:189], v[218:221], v[66:69]
	v_mfma_f32_16x16x32_bf16 v[70:73], v[178:181], v[218:221], v[70:73]
	v_mfma_f32_16x16x32_bf16 v[70:73], v[174:177], v[214:217], v[70:73]
	s_setprio 0
	s_barrier
	s_add_i32 s44, s64, s27
	v_lshl_add_u64 v[160:161], s[56:57], 0, v[134:135]
	s_mov_b32 m0, s44
	ds_read_b128 v[190:193], v150 offset:16384
	ds_read_b128 v[194:197], v150 offset:17408
	ds_read_b128 v[198:201], v150 offset:18432
	ds_read_b128 v[202:205], v150 offset:19456
	ds_read_b128 v[206:209], v150 offset:20480
	ds_read_b128 v[210:213], v150 offset:21504
	ds_read_b128 v[214:217], v150 offset:22528
	ds_read_b128 v[218:221], v150 offset:23552
	global_load_lds_dwordx4 v[160:161], off
	s_add_i32 m0, s44, 0x2000
	s_add_u32 s74, s56, 0x100000
	v_lshl_add_u64 v[222:223], s[56:57], 0, v[130:131]
	s_addc_u32 s75, s57, 0
	s_add_i32 s44, s65, s27
	global_load_lds_dwordx4 v[222:223], off
	v_lshl_add_u64 v[224:225], s[74:75], 0, v[134:135]
	s_mov_b32 m0, s44
	v_lshl_add_u64 v[226:227], s[58:59], 0, v[132:133]
	global_load_lds_dwordx4 v[224:225], off
	v_lshl_add_u64 v[224:225], s[74:75], 0, v[130:131]
	s_add_i32 m0, s44, 0x2000
	s_nop 0
	global_load_lds_dwordx4 v[224:225], off
	v_lshl_add_u64 v[224:225], s[58:59], 0, v[136:137]
	s_mov_b32 m0, s41
	s_nop 0
	global_load_lds_dwordx4 v[224:225], off
	s_mov_b32 m0, s43
	s_nop 0
	global_load_lds_dwordx4 v[226:227], off
	s_waitcnt vmcnt(8)
	s_waitcnt lgkmcnt(0)
	s_barrier
	s_setprio 1
	v_mfma_f32_16x16x32_bf16 v[62:65], v[152:155], v[190:193], v[62:65]
	v_mfma_f32_16x16x32_bf16 v[62:65], v[156:159], v[194:197], v[62:65]
	v_mfma_f32_16x16x32_bf16 v[58:61], v[170:173], v[194:197], v[58:61]
	v_mfma_f32_16x16x32_bf16 v[58:61], v[166:169], v[190:193], v[58:61]
	v_mfma_f32_16x16x32_bf16 v[46:49], v[166:169], v[198:201], v[46:49]
	v_mfma_f32_16x16x32_bf16 v[46:49], v[170:173], v[202:205], v[46:49]
	v_mfma_f32_16x16x32_bf16 v[54:57], v[156:159], v[202:205], v[54:57]
	v_mfma_f32_16x16x32_bf16 v[54:57], v[152:155], v[198:201], v[54:57]
	v_mfma_f32_16x16x32_bf16 v[38:41], v[152:155], v[206:209], v[38:41]
	v_mfma_f32_16x16x32_bf16 v[38:41], v[156:159], v[210:213], v[38:41]
	v_mfma_f32_16x16x32_bf16 v[30:33], v[170:173], v[210:213], v[30:33]
	v_mfma_f32_16x16x32_bf16 v[30:33], v[166:169], v[206:209], v[30:33]
	v_mfma_f32_16x16x32_bf16 v[14:17], v[166:169], v[214:217], v[14:17]
	v_mfma_f32_16x16x32_bf16 v[14:17], v[170:173], v[218:221], v[14:17]
	v_mfma_f32_16x16x32_bf16 v[22:25], v[156:159], v[218:221], v[22:25]
	v_mfma_f32_16x16x32_bf16 v[22:25], v[152:155], v[214:217], v[22:25]
	v_mfma_f32_16x16x32_bf16 v[50:53], v[174:177], v[190:193], v[50:53]
	v_mfma_f32_16x16x32_bf16 v[50:53], v[178:181], v[194:197], v[50:53]
	v_mfma_f32_16x16x32_bf16 v[42:45], v[186:189], v[194:197], v[42:45]
	v_mfma_f32_16x16x32_bf16 v[42:45], v[182:185], v[190:193], v[42:45]
	v_mfma_f32_16x16x32_bf16 v[26:29], v[182:185], v[198:201], v[26:29]
	v_mfma_f32_16x16x32_bf16 v[26:29], v[186:189], v[202:205], v[26:29]
	v_mfma_f32_16x16x32_bf16 v[34:37], v[178:181], v[202:205], v[34:37]
	v_mfma_f32_16x16x32_bf16 v[34:37], v[174:177], v[198:201], v[34:37]
	v_mfma_f32_16x16x32_bf16 v[18:21], v[174:177], v[206:209], v[18:21]
	v_mfma_f32_16x16x32_bf16 v[18:21], v[178:181], v[210:213], v[18:21]
	v_mfma_f32_16x16x32_bf16 v[10:13], v[186:189], v[210:213], v[10:13]
	v_mfma_f32_16x16x32_bf16 v[10:13], v[182:185], v[206:209], v[10:13]
	v_mfma_f32_16x16x32_bf16 v[2:5], v[182:185], v[214:217], v[2:5]
	v_mfma_f32_16x16x32_bf16 v[2:5], v[186:189], v[218:221], v[2:5]
	v_mfma_f32_16x16x32_bf16 v[6:9], v[178:181], v[218:221], v[6:9]
	v_mfma_f32_16x16x32_bf16 v[6:9], v[174:177], v[214:217], v[6:9]
	s_setprio 0
	s_barrier
	s_add_i32 s44, 0, 0x18000
	v_add_u32_e32 v151, s44, v146
	s_add_i32 s73, 0, 0x1c000
	ds_read_b128 v[152:155], v151
	ds_read_b128 v[156:159], v151 offset:1024
	ds_read_b128 v[166:169], v151 offset:2048
	ds_read_b128 v[170:173], v151 offset:3072
	v_add_u32_e32 v151, s73, v146
	ds_read_b128 v[174:177], v151
	ds_read_b128 v[178:181], v151 offset:1024
	ds_read_b128 v[182:185], v151 offset:2048
	ds_read_b128 v[186:189], v151 offset:3072
	s_add_u32 s58, s58, 0x100000
	s_addc_u32 s59, s59, 0
	s_mov_b32 m0, s45
	v_lshl_add_u64 v[228:229], s[58:59], 0, v[136:137]
	ds_read_b128 v[190:193], v150 offset:32768
	ds_read_b128 v[194:197], v150 offset:33792
	ds_read_b128 v[198:201], v150 offset:34816
	ds_read_b128 v[202:205], v150 offset:35840
	ds_read_b128 v[206:209], v150 offset:36864
	ds_read_b128 v[210:213], v150 offset:37888
	ds_read_b128 v[214:217], v150 offset:38912
	ds_read_b128 v[218:221], v150 offset:39936
	global_load_lds_dwordx4 v[228:229], off
	v_lshl_add_u64 v[228:229], s[58:59], 0, v[132:133]
	s_mov_b32 m0, s53
	s_nop 0
	global_load_lds_dwordx4 v[228:229], off
	s_waitcnt vmcnt(8)
	s_waitcnt lgkmcnt(0)
	s_barrier
	s_setprio 1
	v_mfma_f32_16x16x32_bf16 v[126:129], v[152:155], v[190:193], v[126:129]
	v_mfma_f32_16x16x32_bf16 v[126:129], v[156:159], v[194:197], v[126:129]
	v_mfma_f32_16x16x32_bf16 v[122:125], v[170:173], v[194:197], v[122:125]
	v_mfma_f32_16x16x32_bf16 v[122:125], v[166:169], v[190:193], v[122:125]
	v_mfma_f32_16x16x32_bf16 v[110:113], v[166:169], v[198:201], v[110:113]
	v_mfma_f32_16x16x32_bf16 v[110:113], v[170:173], v[202:205], v[110:113]
	v_mfma_f32_16x16x32_bf16 v[118:121], v[156:159], v[202:205], v[118:121]
	v_mfma_f32_16x16x32_bf16 v[118:121], v[152:155], v[198:201], v[118:121]
	v_mfma_f32_16x16x32_bf16 v[102:105], v[152:155], v[206:209], v[102:105]
	v_mfma_f32_16x16x32_bf16 v[102:105], v[156:159], v[210:213], v[102:105]
	v_mfma_f32_16x16x32_bf16 v[94:97], v[170:173], v[210:213], v[94:97]
	v_mfma_f32_16x16x32_bf16 v[94:97], v[166:169], v[206:209], v[94:97]
	v_mfma_f32_16x16x32_bf16 v[78:81], v[166:169], v[214:217], v[78:81]
	v_mfma_f32_16x16x32_bf16 v[78:81], v[170:173], v[218:221], v[78:81]
	v_mfma_f32_16x16x32_bf16 v[86:89], v[156:159], v[218:221], v[86:89]
	v_mfma_f32_16x16x32_bf16 v[86:89], v[152:155], v[214:217], v[86:89]
	v_mfma_f32_16x16x32_bf16 v[114:117], v[174:177], v[190:193], v[114:117]
	v_mfma_f32_16x16x32_bf16 v[114:117], v[178:181], v[194:197], v[114:117]
	v_mfma_f32_16x16x32_bf16 v[106:109], v[186:189], v[194:197], v[106:109]
	v_mfma_f32_16x16x32_bf16 v[106:109], v[182:185], v[190:193], v[106:109]
	v_mfma_f32_16x16x32_bf16 v[90:93], v[182:185], v[198:201], v[90:93]
	v_mfma_f32_16x16x32_bf16 v[90:93], v[186:189], v[202:205], v[90:93]
	v_mfma_f32_16x16x32_bf16 v[98:101], v[178:181], v[202:205], v[98:101]
	v_mfma_f32_16x16x32_bf16 v[98:101], v[174:177], v[198:201], v[98:101]
	v_mfma_f32_16x16x32_bf16 v[82:85], v[174:177], v[206:209], v[82:85]
	v_mfma_f32_16x16x32_bf16 v[82:85], v[178:181], v[210:213], v[82:85]
	v_mfma_f32_16x16x32_bf16 v[74:77], v[186:189], v[210:213], v[74:77]
	v_mfma_f32_16x16x32_bf16 v[74:77], v[182:185], v[206:209], v[74:77]
	v_mfma_f32_16x16x32_bf16 v[66:69], v[182:185], v[214:217], v[66:69]
	v_mfma_f32_16x16x32_bf16 v[66:69], v[186:189], v[218:221], v[66:69]
	v_mfma_f32_16x16x32_bf16 v[70:73], v[178:181], v[218:221], v[70:73]
	v_mfma_f32_16x16x32_bf16 v[70:73], v[174:177], v[214:217], v[70:73]
	s_setprio 0
	s_barrier
	s_add_i32 s44, s44, s27
	v_lshl_add_u64 v[160:161], v[160:161], 0, s[10:11]
	s_mov_b32 m0, s44
	ds_read_b128 v[190:193], v150 offset:49152
	ds_read_b128 v[194:197], v150 offset:50176
	ds_read_b128 v[198:201], v150 offset:51200
	ds_read_b128 v[202:205], v150 offset:52224
	ds_read_b128 v[206:209], v150 offset:53248
	ds_read_b128 v[210:213], v150 offset:54272
	ds_read_b128 v[214:217], v150 offset:55296
	ds_read_b128 v[218:221], v150 offset:56320
	global_load_lds_dwordx4 v[160:161], off
	s_add_i32 m0, s44, 0x2000
	s_add_u32 s56, s56, 0x100080
	v_lshl_add_u64 v[160:161], v[222:223], 0, s[10:11]
	s_addc_u32 s57, s57, 0
	s_add_i32 s44, s73, s27
	global_load_lds_dwordx4 v[160:161], off
	v_lshl_add_u64 v[160:161], s[56:57], 0, v[134:135]
	s_mov_b32 m0, s44
	s_nop 0
	global_load_lds_dwordx4 v[160:161], off
	v_lshl_add_u64 v[160:161], s[56:57], 0, v[130:131]
	s_add_i32 m0, s44, 0x2000
	s_nop 0
	global_load_lds_dwordx4 v[160:161], off
	v_lshl_add_u64 v[160:161], v[224:225], 0, s[10:11]
	s_mov_b32 m0, s61
	s_nop 0
	global_load_lds_dwordx4 v[160:161], off
	v_lshl_add_u64 v[160:161], v[226:227], 0, s[10:11]
	s_mov_b32 m0, s62
	s_nop 0
	global_load_lds_dwordx4 v[160:161], off
	s_waitcnt vmcnt(8)
	s_waitcnt lgkmcnt(0)
	s_barrier
	s_setprio 1
	v_mfma_f32_16x16x32_bf16 v[62:65], v[152:155], v[190:193], v[62:65]
	v_mfma_f32_16x16x32_bf16 v[62:65], v[156:159], v[194:197], v[62:65]
	v_mfma_f32_16x16x32_bf16 v[58:61], v[170:173], v[194:197], v[58:61]
	v_mfma_f32_16x16x32_bf16 v[58:61], v[166:169], v[190:193], v[58:61]
	v_mfma_f32_16x16x32_bf16 v[46:49], v[166:169], v[198:201], v[46:49]
	v_mfma_f32_16x16x32_bf16 v[46:49], v[170:173], v[202:205], v[46:49]
	v_mfma_f32_16x16x32_bf16 v[54:57], v[156:159], v[202:205], v[54:57]
	v_mfma_f32_16x16x32_bf16 v[54:57], v[152:155], v[198:201], v[54:57]
	v_mfma_f32_16x16x32_bf16 v[38:41], v[152:155], v[206:209], v[38:41]
	v_mfma_f32_16x16x32_bf16 v[38:41], v[156:159], v[210:213], v[38:41]
	v_mfma_f32_16x16x32_bf16 v[30:33], v[170:173], v[210:213], v[30:33]
	v_mfma_f32_16x16x32_bf16 v[30:33], v[166:169], v[206:209], v[30:33]
	v_mfma_f32_16x16x32_bf16 v[14:17], v[166:169], v[214:217], v[14:17]
	v_mfma_f32_16x16x32_bf16 v[14:17], v[170:173], v[218:221], v[14:17]
	v_mfma_f32_16x16x32_bf16 v[22:25], v[156:159], v[218:221], v[22:25]
	v_mfma_f32_16x16x32_bf16 v[22:25], v[152:155], v[214:217], v[22:25]
	v_mfma_f32_16x16x32_bf16 v[50:53], v[174:177], v[190:193], v[50:53]
	v_mfma_f32_16x16x32_bf16 v[50:53], v[178:181], v[194:197], v[50:53]
	v_mfma_f32_16x16x32_bf16 v[42:45], v[186:189], v[194:197], v[42:45]
	v_mfma_f32_16x16x32_bf16 v[42:45], v[182:185], v[190:193], v[42:45]
	v_mfma_f32_16x16x32_bf16 v[26:29], v[182:185], v[198:201], v[26:29]
	v_mfma_f32_16x16x32_bf16 v[26:29], v[186:189], v[202:205], v[26:29]
	v_mfma_f32_16x16x32_bf16 v[34:37], v[178:181], v[202:205], v[34:37]
	v_mfma_f32_16x16x32_bf16 v[34:37], v[174:177], v[198:201], v[34:37]
	v_mfma_f32_16x16x32_bf16 v[18:21], v[174:177], v[206:209], v[18:21]
	v_mfma_f32_16x16x32_bf16 v[18:21], v[178:181], v[210:213], v[18:21]
	v_mfma_f32_16x16x32_bf16 v[10:13], v[186:189], v[210:213], v[10:13]
	v_mfma_f32_16x16x32_bf16 v[10:13], v[182:185], v[206:209], v[10:13]
	v_mfma_f32_16x16x32_bf16 v[2:5], v[182:185], v[214:217], v[2:5]
	v_mfma_f32_16x16x32_bf16 v[2:5], v[186:189], v[218:221], v[2:5]
	v_mfma_f32_16x16x32_bf16 v[6:9], v[178:181], v[218:221], v[6:9]
	v_mfma_f32_16x16x32_bf16 v[6:9], v[174:177], v[214:217], v[6:9]
	s_setprio 0
	s_barrier
	s_add_i32 s72, s72, 2
	s_add_u32 s54, s54, 0x100
	s_addc_u32 s55, s55, 0
	s_add_u32 s70, s70, 0x100
	s_addc_u32 s71, s71, 0
	s_cmp_gt_u32 s72, 61
	s_cbranch_scc0 .LBB0_472
	s_and_b64 vcc, exec, s[12:13]
	s_cbranch_vccz .LBB0_475
	s_barrier

.LBB0_706:
	s_add_u32 s72, s60, s44
	s_addc_u32 s73, s61, 0
	s_add_u32 s68, s72, 0x100
	s_addc_u32 s69, s73, 0
	s_and_b64 s[66:67], s[64:65], exec
	s_cselect_b32 s69, s17, s69
	s_cselect_b32 s68, s86, s68
	s_add_u32 s44, s56, s44
	s_addc_u32 s66, s57, 0
	s_add_u32 s44, s44, 0x100
	s_addc_u32 s66, s66, 0
	s_and_b64 s[64:65], s[64:65], exec
	s_cselect_b32 s71, s15, s66
	s_cselect_b32 s70, s87, s44
	s_add_u32 s74, s72, 0x10080
	s_addc_u32 s75, s73, 0
	s_add_i32 vcc_hi, s82, s27
	ds_read_b128 v[150:153], v147
	ds_read_b128 v[154:157], v147 offset:1024
	ds_read_b128 v[158:161], v147 offset:2048
	ds_read_b128 v[166:169], v147 offset:3072
	ds_read_b128 v[170:173], v148
	ds_read_b128 v[174:177], v148 offset:1024
	ds_read_b128 v[178:181], v148 offset:2048
	ds_read_b128 v[182:185], v148 offset:3072
	s_add_i32 m0, s36, 0xc000
	s_add_i32 s45, s36, 0xe000
	s_add_i32 s96, vcc_hi, 0x2000
	s_add_u32 s72, s70, 0x10000
	s_addc_u32 s73, s71, 0
	s_add_i32 vcc_lo, s83, s27
	s_add_i32 s97, vcc_lo, 0x2000
	s_add_i32 s95, 0, 0x18000
	s_add_i32 s94, 0, 0x1c000
	s_add_u32 s66, s68, 0x10000
	s_addc_u32 s67, s69, 0
	s_add_i32 s93, s95, s27
	s_add_i32 s89, s93, 0x2000
	s_add_u32 s64, s70, 0x10080
	s_addc_u32 s65, s71, 0
	s_add_i32 s92, s94, s27
	s_add_i32 s44, s92, 0x2000
	v_lshl_add_u64 v[198:199], s[74:75], 0, v[130:131]
	ds_read_b128 v[186:189], v149
	ds_read_b128 v[190:193], v149 offset:1024
	ds_read_b128 v[194:197], v149 offset:2048
	ds_read_b128 v[202:205], v149 offset:3072
	ds_read_b128 v[206:209], v149 offset:4096
	ds_read_b128 v[210:213], v149 offset:5120
	ds_read_b128 v[214:217], v149 offset:6144
	ds_read_b128 v[218:221], v149 offset:7168
	global_load_lds_dwordx4 v[198:199], off
	v_lshl_add_u64 v[198:199], s[74:75], 0, v[134:135]
	s_mov_b32 m0, s45
	s_nop 0
	global_load_lds_dwordx4 v[198:199], off
	s_waitcnt vmcnt(8)
	s_waitcnt lgkmcnt(0)
	s_barrier
	s_setprio 1
	v_mfma_f32_16x16x32_bf16 v[126:129], v[150:153], v[186:189], v[126:129]
	v_mfma_f32_16x16x32_bf16 v[126:129], v[154:157], v[190:193], v[126:129]
	v_mfma_f32_16x16x32_bf16 v[122:125], v[166:169], v[190:193], v[122:125]
	v_mfma_f32_16x16x32_bf16 v[122:125], v[158:161], v[186:189], v[122:125]
	v_mfma_f32_16x16x32_bf16 v[110:113], v[158:161], v[194:197], v[110:113]
	v_mfma_f32_16x16x32_bf16 v[110:113], v[166:169], v[202:205], v[110:113]
	v_mfma_f32_16x16x32_bf16 v[118:121], v[154:157], v[202:205], v[118:121]
	v_mfma_f32_16x16x32_bf16 v[118:121], v[150:153], v[194:197], v[118:121]
	v_mfma_f32_16x16x32_bf16 v[102:105], v[150:153], v[206:209], v[102:105]
	v_mfma_f32_16x16x32_bf16 v[102:105], v[154:157], v[210:213], v[102:105]
	v_mfma_f32_16x16x32_bf16 v[94:97], v[166:169], v[210:213], v[94:97]
	v_mfma_f32_16x16x32_bf16 v[94:97], v[158:161], v[206:209], v[94:97]
	v_mfma_f32_16x16x32_bf16 v[78:81], v[158:161], v[214:217], v[78:81]
	v_mfma_f32_16x16x32_bf16 v[78:81], v[166:169], v[218:221], v[78:81]
	v_mfma_f32_16x16x32_bf16 v[86:89], v[154:157], v[218:221], v[86:89]
	v_mfma_f32_16x16x32_bf16 v[86:89], v[150:153], v[214:217], v[86:89]
	v_mfma_f32_16x16x32_bf16 v[114:117], v[170:173], v[186:189], v[114:117]
	v_mfma_f32_16x16x32_bf16 v[114:117], v[174:177], v[190:193], v[114:117]
	v_mfma_f32_16x16x32_bf16 v[106:109], v[182:185], v[190:193], v[106:109]
	v_mfma_f32_16x16x32_bf16 v[106:109], v[178:181], v[186:189], v[106:109]
	v_mfma_f32_16x16x32_bf16 v[90:93], v[178:181], v[194:197], v[90:93]
	v_mfma_f32_16x16x32_bf16 v[90:93], v[182:185], v[202:205], v[90:93]
	v_mfma_f32_16x16x32_bf16 v[98:101], v[174:177], v[202:205], v[98:101]
	v_mfma_f32_16x16x32_bf16 v[98:101], v[170:173], v[194:197], v[98:101]
	v_mfma_f32_16x16x32_bf16 v[82:85], v[170:173], v[206:209], v[82:85]
	v_mfma_f32_16x16x32_bf16 v[82:85], v[174:177], v[210:213], v[82:85]
	v_mfma_f32_16x16x32_bf16 v[74:77], v[182:185], v[210:213], v[74:77]
	v_mfma_f32_16x16x32_bf16 v[74:77], v[178:181], v[206:209], v[74:77]
	v_mfma_f32_16x16x32_bf16 v[66:69], v[178:181], v[214:217], v[66:69]
	v_mfma_f32_16x16x32_bf16 v[66:69], v[182:185], v[218:221], v[66:69]
	v_mfma_f32_16x16x32_bf16 v[70:73], v[174:177], v[218:221], v[70:73]
	v_mfma_f32_16x16x32_bf16 v[70:73], v[170:173], v[214:217], v[70:73]
	s_setprio 0
	s_barrier
	s_mov_b32 m0, vcc_hi
	v_lshl_add_u64 v[198:199], s[70:71], 0, v[132:133]
	ds_read_b128 v[186:189], v149 offset:16384
	ds_read_b128 v[190:193], v149 offset:17408
	ds_read_b128 v[194:197], v149 offset:18432
	ds_read_b128 v[202:205], v149 offset:19456
	ds_read_b128 v[206:209], v149 offset:20480
	ds_read_b128 v[210:213], v149 offset:21504
	ds_read_b128 v[214:217], v149 offset:22528
	ds_read_b128 v[218:221], v149 offset:23552
	global_load_lds_dwordx4 v[198:199], off
	v_lshl_add_u64 v[222:223], s[70:71], 0, v[136:137]
	s_mov_b32 m0, s96
	v_lshl_add_u64 v[224:225], s[72:73], 0, v[132:133]
	global_load_lds_dwordx4 v[222:223], off
	s_mov_b32 m0, vcc_lo
	v_lshl_add_u64 v[226:227], s[68:69], 0, v[134:135]
	global_load_lds_dwordx4 v[224:225], off
	v_lshl_add_u64 v[224:225], s[72:73], 0, v[136:137]
	s_mov_b32 m0, s97
	s_nop 0
	global_load_lds_dwordx4 v[224:225], off
	v_lshl_add_u64 v[224:225], s[68:69], 0, v[130:131]
	s_mov_b32 m0, s36
	s_nop 0
	global_load_lds_dwordx4 v[224:225], off
	s_mov_b32 m0, s55
	s_nop 0
	global_load_lds_dwordx4 v[226:227], off
	s_waitcnt vmcnt(8)
	s_waitcnt lgkmcnt(0)
	s_barrier
	s_setprio 1
	v_mfma_f32_16x16x32_bf16 v[62:65], v[150:153], v[186:189], v[62:65]
	v_mfma_f32_16x16x32_bf16 v[62:65], v[154:157], v[190:193], v[62:65]
	v_mfma_f32_16x16x32_bf16 v[58:61], v[166:169], v[190:193], v[58:61]
	v_mfma_f32_16x16x32_bf16 v[58:61], v[158:161], v[186:189], v[58:61]
	v_mfma_f32_16x16x32_bf16 v[46:49], v[158:161], v[194:197], v[46:49]
	v_mfma_f32_16x16x32_bf16 v[46:49], v[166:169], v[202:205], v[46:49]
	v_mfma_f32_16x16x32_bf16 v[54:57], v[154:157], v[202:205], v[54:57]
	v_mfma_f32_16x16x32_bf16 v[54:57], v[150:153], v[194:197], v[54:57]
	v_mfma_f32_16x16x32_bf16 v[38:41], v[150:153], v[206:209], v[38:41]
	v_mfma_f32_16x16x32_bf16 v[38:41], v[154:157], v[210:213], v[38:41]
	v_mfma_f32_16x16x32_bf16 v[30:33], v[166:169], v[210:213], v[30:33]
	v_mfma_f32_16x16x32_bf16 v[30:33], v[158:161], v[206:209], v[30:33]
	v_mfma_f32_16x16x32_bf16 v[14:17], v[158:161], v[214:217], v[14:17]
	v_mfma_f32_16x16x32_bf16 v[14:17], v[166:169], v[218:221], v[14:17]
	v_mfma_f32_16x16x32_bf16 v[22:25], v[154:157], v[218:221], v[22:25]
	v_mfma_f32_16x16x32_bf16 v[22:25], v[150:153], v[214:217], v[22:25]
	v_mfma_f32_16x16x32_bf16 v[50:53], v[170:173], v[186:189], v[50:53]
	v_mfma_f32_16x16x32_bf16 v[50:53], v[174:177], v[190:193], v[50:53]
	v_mfma_f32_16x16x32_bf16 v[42:45], v[182:185], v[190:193], v[42:45]
	v_mfma_f32_16x16x32_bf16 v[42:45], v[178:181], v[186:189], v[42:45]
	v_mfma_f32_16x16x32_bf16 v[26:29], v[178:181], v[194:197], v[26:29]
	v_mfma_f32_16x16x32_bf16 v[26:29], v[182:185], v[202:205], v[26:29]
	v_mfma_f32_16x16x32_bf16 v[34:37], v[174:177], v[202:205], v[34:37]
	v_mfma_f32_16x16x32_bf16 v[34:37], v[170:173], v[194:197], v[34:37]
	v_mfma_f32_16x16x32_bf16 v[18:21], v[170:173], v[206:209], v[18:21]
	v_mfma_f32_16x16x32_bf16 v[18:21], v[174:177], v[210:213], v[18:21]
	v_mfma_f32_16x16x32_bf16 v[10:13], v[182:185], v[210:213], v[10:13]
	v_mfma_f32_16x16x32_bf16 v[10:13], v[178:181], v[206:209], v[10:13]
	v_mfma_f32_16x16x32_bf16 v[2:5], v[178:181], v[214:217], v[2:5]
	v_mfma_f32_16x16x32_bf16 v[2:5], v[182:185], v[218:221], v[2:5]
	v_mfma_f32_16x16x32_bf16 v[6:9], v[174:177], v[218:221], v[6:9]
	v_mfma_f32_16x16x32_bf16 v[6:9], v[170:173], v[214:217], v[6:9]
	s_setprio 0
	s_barrier
	v_add_u32_e32 v166, s95, v145
	v_add_u32_e32 v182, s94, v145
	ds_read_b128 v[150:153], v166
	ds_read_b128 v[154:157], v166 offset:1024
	ds_read_b128 v[158:161], v166 offset:2048
	ds_read_b128 v[166:169], v166 offset:3072
	ds_read_b128 v[170:173], v182
	ds_read_b128 v[174:177], v182 offset:1024
	ds_read_b128 v[178:181], v182 offset:2048
	ds_read_b128 v[182:185], v182 offset:3072
	s_mov_b32 m0, s76
	v_lshl_add_u64 v[228:229], s[66:67], 0, v[130:131]
	ds_read_b128 v[186:189], v149 offset:32768
	ds_read_b128 v[190:193], v149 offset:33792
	ds_read_b128 v[194:197], v149 offset:34816
	ds_read_b128 v[202:205], v149 offset:35840
	ds_read_b128 v[206:209], v149 offset:36864
	ds_read_b128 v[210:213], v149 offset:37888
	ds_read_b128 v[214:217], v149 offset:38912
	ds_read_b128 v[218:221], v149 offset:39936
	global_load_lds_dwordx4 v[228:229], off
	v_lshl_add_u64 v[228:229], s[66:67], 0, v[134:135]
	s_mov_b32 m0, s77
	s_nop 0
	global_load_lds_dwordx4 v[228:229], off
	s_waitcnt vmcnt(8)
	s_waitcnt lgkmcnt(0)
	s_barrier
	s_setprio 1
	v_mfma_f32_16x16x32_bf16 v[126:129], v[150:153], v[186:189], v[126:129]
	v_mfma_f32_16x16x32_bf16 v[126:129], v[154:157], v[190:193], v[126:129]
	v_mfma_f32_16x16x32_bf16 v[122:125], v[166:169], v[190:193], v[122:125]
	v_mfma_f32_16x16x32_bf16 v[122:125], v[158:161], v[186:189], v[122:125]
	v_mfma_f32_16x16x32_bf16 v[110:113], v[158:161], v[194:197], v[110:113]
	v_mfma_f32_16x16x32_bf16 v[110:113], v[166:169], v[202:205], v[110:113]
	v_mfma_f32_16x16x32_bf16 v[118:121], v[154:157], v[202:205], v[118:121]
	v_mfma_f32_16x16x32_bf16 v[118:121], v[150:153], v[194:197], v[118:121]
	v_mfma_f32_16x16x32_bf16 v[102:105], v[150:153], v[206:209], v[102:105]
	v_mfma_f32_16x16x32_bf16 v[102:105], v[154:157], v[210:213], v[102:105]
	v_mfma_f32_16x16x32_bf16 v[94:97], v[166:169], v[210:213], v[94:97]
	v_mfma_f32_16x16x32_bf16 v[94:97], v[158:161], v[206:209], v[94:97]
	v_mfma_f32_16x16x32_bf16 v[78:81], v[158:161], v[214:217], v[78:81]
	v_mfma_f32_16x16x32_bf16 v[78:81], v[166:169], v[218:221], v[78:81]
	v_mfma_f32_16x16x32_bf16 v[86:89], v[154:157], v[218:221], v[86:89]
	v_mfma_f32_16x16x32_bf16 v[86:89], v[150:153], v[214:217], v[86:89]
	v_mfma_f32_16x16x32_bf16 v[114:117], v[170:173], v[186:189], v[114:117]
	v_mfma_f32_16x16x32_bf16 v[114:117], v[174:177], v[190:193], v[114:117]
	v_mfma_f32_16x16x32_bf16 v[106:109], v[182:185], v[190:193], v[106:109]
	v_mfma_f32_16x16x32_bf16 v[106:109], v[178:181], v[186:189], v[106:109]
	v_mfma_f32_16x16x32_bf16 v[90:93], v[178:181], v[194:197], v[90:93]
	v_mfma_f32_16x16x32_bf16 v[90:93], v[182:185], v[202:205], v[90:93]
	v_mfma_f32_16x16x32_bf16 v[98:101], v[174:177], v[202:205], v[98:101]
	v_mfma_f32_16x16x32_bf16 v[98:101], v[170:173], v[194:197], v[98:101]
	v_mfma_f32_16x16x32_bf16 v[82:85], v[170:173], v[206:209], v[82:85]
	v_mfma_f32_16x16x32_bf16 v[82:85], v[174:177], v[210:213], v[82:85]
	v_mfma_f32_16x16x32_bf16 v[74:77], v[182:185], v[210:213], v[74:77]
	v_mfma_f32_16x16x32_bf16 v[74:77], v[178:181], v[206:209], v[74:77]
	v_mfma_f32_16x16x32_bf16 v[66:69], v[178:181], v[214:217], v[66:69]
	v_mfma_f32_16x16x32_bf16 v[66:69], v[182:185], v[218:221], v[66:69]
	v_mfma_f32_16x16x32_bf16 v[70:73], v[174:177], v[218:221], v[70:73]
	v_mfma_f32_16x16x32_bf16 v[70:73], v[170:173], v[214:217], v[70:73]
	s_setprio 0
	s_barrier
	s_mov_b32 m0, s93
	v_lshl_add_u64 v[198:199], v[198:199], 0, s[10:11]
	ds_read_b128 v[186:189], v149 offset:49152
	ds_read_b128 v[190:193], v149 offset:50176
	ds_read_b128 v[194:197], v149 offset:51200
	ds_read_b128 v[202:205], v149 offset:52224
	ds_read_b128 v[206:209], v149 offset:53248
	ds_read_b128 v[210:213], v149 offset:54272
	ds_read_b128 v[214:217], v149 offset:55296
	ds_read_b128 v[218:221], v149 offset:56320
	global_load_lds_dwordx4 v[198:199], off
	v_lshl_add_u64 v[198:199], v[222:223], 0, s[10:11]
	s_mov_b32 m0, s89
	s_nop 0
	global_load_lds_dwordx4 v[198:199], off
	v_lshl_add_u64 v[198:199], s[64:65], 0, v[132:133]
	s_mov_b32 m0, s92
	s_nop 0
	global_load_lds_dwordx4 v[198:199], off
	v_lshl_add_u64 v[198:199], s[64:65], 0, v[136:137]
	s_mov_b32 m0, s44
	s_nop 0
	global_load_lds_dwordx4 v[198:199], off
	v_lshl_add_u64 v[198:199], v[224:225], 0, s[10:11]
	s_mov_b32 m0, s79
	s_nop 0
	global_load_lds_dwordx4 v[198:199], off
	v_lshl_add_u64 v[198:199], v[226:227], 0, s[10:11]
	s_mov_b32 m0, s80
	s_nop 0
	global_load_lds_dwordx4 v[198:199], off
	s_waitcnt vmcnt(8)
	s_waitcnt lgkmcnt(0)
	s_barrier
	s_setprio 1
	v_mfma_f32_16x16x32_bf16 v[62:65], v[150:153], v[186:189], v[62:65]
	v_mfma_f32_16x16x32_bf16 v[62:65], v[154:157], v[190:193], v[62:65]
	v_mfma_f32_16x16x32_bf16 v[58:61], v[166:169], v[190:193], v[58:61]
	v_mfma_f32_16x16x32_bf16 v[58:61], v[158:161], v[186:189], v[58:61]
	v_mfma_f32_16x16x32_bf16 v[46:49], v[158:161], v[194:197], v[46:49]
	v_mfma_f32_16x16x32_bf16 v[46:49], v[166:169], v[202:205], v[46:49]
	v_mfma_f32_16x16x32_bf16 v[54:57], v[154:157], v[202:205], v[54:57]
	v_mfma_f32_16x16x32_bf16 v[54:57], v[150:153], v[194:197], v[54:57]
	v_mfma_f32_16x16x32_bf16 v[38:41], v[150:153], v[206:209], v[38:41]
	v_mfma_f32_16x16x32_bf16 v[38:41], v[154:157], v[210:213], v[38:41]
	v_mfma_f32_16x16x32_bf16 v[30:33], v[166:169], v[210:213], v[30:33]
	v_mfma_f32_16x16x32_bf16 v[30:33], v[158:161], v[206:209], v[30:33]
	v_mfma_f32_16x16x32_bf16 v[14:17], v[158:161], v[214:217], v[14:17]
	v_mfma_f32_16x16x32_bf16 v[14:17], v[166:169], v[218:221], v[14:17]
	v_mfma_f32_16x16x32_bf16 v[22:25], v[154:157], v[218:221], v[22:25]
	v_mfma_f32_16x16x32_bf16 v[22:25], v[150:153], v[214:217], v[22:25]
	v_mfma_f32_16x16x32_bf16 v[50:53], v[170:173], v[186:189], v[50:53]
	v_mfma_f32_16x16x32_bf16 v[50:53], v[174:177], v[190:193], v[50:53]
	v_mfma_f32_16x16x32_bf16 v[42:45], v[182:185], v[190:193], v[42:45]
	v_mfma_f32_16x16x32_bf16 v[42:45], v[178:181], v[186:189], v[42:45]
	v_mfma_f32_16x16x32_bf16 v[26:29], v[178:181], v[194:197], v[26:29]
	v_mfma_f32_16x16x32_bf16 v[26:29], v[182:185], v[202:205], v[26:29]
	v_mfma_f32_16x16x32_bf16 v[34:37], v[174:177], v[202:205], v[34:37]
	v_mfma_f32_16x16x32_bf16 v[34:37], v[170:173], v[194:197], v[34:37]
	v_mfma_f32_16x16x32_bf16 v[18:21], v[170:173], v[206:209], v[18:21]
	v_mfma_f32_16x16x32_bf16 v[18:21], v[174:177], v[210:213], v[18:21]
	v_mfma_f32_16x16x32_bf16 v[10:13], v[182:185], v[210:213], v[10:13]
	v_mfma_f32_16x16x32_bf16 v[10:13], v[178:181], v[206:209], v[10:13]
	v_mfma_f32_16x16x32_bf16 v[2:5], v[178:181], v[214:217], v[2:5]
	v_mfma_f32_16x16x32_bf16 v[2:5], v[182:185], v[218:221], v[2:5]
	v_mfma_f32_16x16x32_bf16 v[6:9], v[174:177], v[218:221], v[6:9]
	v_mfma_f32_16x16x32_bf16 v[6:9], v[170:173], v[214:217], v[6:9]
	s_setprio 0
	s_barrier
	s_movk_i32 s44, 0x100
	s_andn2_b64 vcc, exec, s[62:63]
	s_mov_b64 s[64:65], -1
	s_mov_b64 s[62:63], 0
	s_cbranch_vccz .LBB0_706
	s_and_b64 vcc, exec, s[12:13]
	s_cbranch_vccz .LBB0_709
	s_barrier

.LBB0_722:
	s_add_u32 s36, s56, s44
	s_addc_u32 s37, s57, 0
	s_add_u32 s66, s36, 0x100
	s_addc_u32 s67, s37, 0
	s_and_b64 s[64:65], s[62:63], exec
	s_cselect_b32 s67, s17, s67
	s_cselect_b32 s66, s83, s66
	s_add_u32 s44, s54, s44
	s_addc_u32 s64, s55, 0
	s_add_u32 s44, s44, 0x100
	s_addc_u32 s64, s64, 0
	s_and_b64 s[62:63], s[62:63], exec
	s_cselect_b32 s69, s15, s64
	s_cselect_b32 s68, s84, s44
	s_add_u32 s72, s36, 0x10080
	s_addc_u32 s73, s37, 0
	s_add_i32 s96, s79, s27
	ds_read_b128 v[148:151], v143
	ds_read_b128 v[152:155], v143 offset:1024
	ds_read_b128 v[156:159], v143 offset:2048
	ds_read_b128 v[166:169], v143 offset:3072
	ds_read_b128 v[170:173], v145
	ds_read_b128 v[174:177], v145 offset:1024
	ds_read_b128 v[178:181], v145 offset:2048
	ds_read_b128 v[182:185], v145 offset:3072
	s_add_i32 m0, s43, 0xc000
	s_add_i32 s97, s43, 0xe000
	s_add_i32 s93, s96, 0x2000
	s_add_u32 s70, s68, 0x10000
	s_addc_u32 s71, s69, 0
	s_add_i32 s95, s80, s27
	s_add_i32 s94, s95, 0x2000
	s_add_i32 s92, 0, 0x18000
	s_add_i32 s89, 0, 0x1c000
	s_add_u32 s64, s66, 0x10000
	s_addc_u32 s65, s67, 0
	s_add_i32 s87, s92, s27
	s_add_i32 s85, s87, 0x2000
	s_add_u32 s62, s68, 0x10080
	s_addc_u32 s63, s69, 0
	s_add_i32 s86, s89, s27
	s_add_i32 s44, s86, 0x2000
	v_lshl_add_u64 v[160:161], s[72:73], 0, v[130:131]
	ds_read_b128 v[186:189], v146
	ds_read_b128 v[190:193], v146 offset:1024
	ds_read_b128 v[194:197], v146 offset:2048
	ds_read_b128 v[202:205], v146 offset:3072
	ds_read_b128 v[206:209], v146 offset:4096
	ds_read_b128 v[210:213], v146 offset:5120
	ds_read_b128 v[214:217], v146 offset:6144
	ds_read_b128 v[218:221], v146 offset:7168
	global_load_lds_dwordx4 v[160:161], off
	v_lshl_add_u64 v[160:161], s[72:73], 0, v[134:135]
	s_mov_b32 m0, s97
	s_nop 0
	global_load_lds_dwordx4 v[160:161], off
	s_waitcnt vmcnt(8)
	s_waitcnt lgkmcnt(0)
	s_barrier
	s_setprio 1
	v_mfma_f32_16x16x32_bf16 v[126:129], v[148:151], v[186:189], v[126:129]
	v_mfma_f32_16x16x32_bf16 v[126:129], v[152:155], v[190:193], v[126:129]
	v_mfma_f32_16x16x32_bf16 v[122:125], v[166:169], v[190:193], v[122:125]
	v_mfma_f32_16x16x32_bf16 v[122:125], v[156:159], v[186:189], v[122:125]
	v_mfma_f32_16x16x32_bf16 v[110:113], v[156:159], v[194:197], v[110:113]
	v_mfma_f32_16x16x32_bf16 v[110:113], v[166:169], v[202:205], v[110:113]
	v_mfma_f32_16x16x32_bf16 v[118:121], v[152:155], v[202:205], v[118:121]
	v_mfma_f32_16x16x32_bf16 v[118:121], v[148:151], v[194:197], v[118:121]
	v_mfma_f32_16x16x32_bf16 v[102:105], v[148:151], v[206:209], v[102:105]
	v_mfma_f32_16x16x32_bf16 v[102:105], v[152:155], v[210:213], v[102:105]
	v_mfma_f32_16x16x32_bf16 v[94:97], v[166:169], v[210:213], v[94:97]
	v_mfma_f32_16x16x32_bf16 v[94:97], v[156:159], v[206:209], v[94:97]
	v_mfma_f32_16x16x32_bf16 v[78:81], v[156:159], v[214:217], v[78:81]
	v_mfma_f32_16x16x32_bf16 v[78:81], v[166:169], v[218:221], v[78:81]
	v_mfma_f32_16x16x32_bf16 v[86:89], v[152:155], v[218:221], v[86:89]
	v_mfma_f32_16x16x32_bf16 v[86:89], v[148:151], v[214:217], v[86:89]
	v_mfma_f32_16x16x32_bf16 v[114:117], v[170:173], v[186:189], v[114:117]
	v_mfma_f32_16x16x32_bf16 v[114:117], v[174:177], v[190:193], v[114:117]
	v_mfma_f32_16x16x32_bf16 v[106:109], v[182:185], v[190:193], v[106:109]
	v_mfma_f32_16x16x32_bf16 v[106:109], v[178:181], v[186:189], v[106:109]
	v_mfma_f32_16x16x32_bf16 v[90:93], v[178:181], v[194:197], v[90:93]
	v_mfma_f32_16x16x32_bf16 v[90:93], v[182:185], v[202:205], v[90:93]
	v_mfma_f32_16x16x32_bf16 v[98:101], v[174:177], v[202:205], v[98:101]
	v_mfma_f32_16x16x32_bf16 v[98:101], v[170:173], v[194:197], v[98:101]
	v_mfma_f32_16x16x32_bf16 v[82:85], v[170:173], v[206:209], v[82:85]
	v_mfma_f32_16x16x32_bf16 v[82:85], v[174:177], v[210:213], v[82:85]
	v_mfma_f32_16x16x32_bf16 v[74:77], v[182:185], v[210:213], v[74:77]
	v_mfma_f32_16x16x32_bf16 v[74:77], v[178:181], v[206:209], v[74:77]
	v_mfma_f32_16x16x32_bf16 v[66:69], v[178:181], v[214:217], v[66:69]
	v_mfma_f32_16x16x32_bf16 v[66:69], v[182:185], v[218:221], v[66:69]
	v_mfma_f32_16x16x32_bf16 v[70:73], v[174:177], v[218:221], v[70:73]
	v_mfma_f32_16x16x32_bf16 v[70:73], v[170:173], v[214:217], v[70:73]
	s_setprio 0
	s_barrier
	s_mov_b32 m0, s96
	v_lshl_add_u64 v[160:161], s[68:69], 0, v[132:133]
	ds_read_b128 v[186:189], v146 offset:16384
	ds_read_b128 v[190:193], v146 offset:17408
	ds_read_b128 v[194:197], v146 offset:18432
	ds_read_b128 v[202:205], v146 offset:19456
	ds_read_b128 v[206:209], v146 offset:20480
	ds_read_b128 v[210:213], v146 offset:21504
	ds_read_b128 v[214:217], v146 offset:22528
	ds_read_b128 v[218:221], v146 offset:23552
	global_load_lds_dwordx4 v[160:161], off
	v_lshl_add_u64 v[198:199], s[68:69], 0, v[136:137]
	s_mov_b32 m0, s93
	v_lshl_add_u64 v[222:223], s[70:71], 0, v[132:133]
	global_load_lds_dwordx4 v[198:199], off
	s_mov_b32 m0, s95
	v_lshl_add_u64 v[224:225], s[66:67], 0, v[134:135]
	global_load_lds_dwordx4 v[222:223], off
	v_lshl_add_u64 v[222:223], s[70:71], 0, v[136:137]
	s_mov_b32 m0, s94
	s_nop 0
	global_load_lds_dwordx4 v[222:223], off
	v_lshl_add_u64 v[222:223], s[66:67], 0, v[130:131]
	s_mov_b32 m0, s43
	s_nop 0
	global_load_lds_dwordx4 v[222:223], off
	s_mov_b32 m0, s45
	s_nop 0
	global_load_lds_dwordx4 v[224:225], off
	s_waitcnt vmcnt(8)
	s_waitcnt lgkmcnt(0)
	s_barrier
	s_setprio 1
	v_mfma_f32_16x16x32_bf16 v[62:65], v[148:151], v[186:189], v[62:65]
	v_mfma_f32_16x16x32_bf16 v[62:65], v[152:155], v[190:193], v[62:65]
	v_mfma_f32_16x16x32_bf16 v[58:61], v[166:169], v[190:193], v[58:61]
	v_mfma_f32_16x16x32_bf16 v[58:61], v[156:159], v[186:189], v[58:61]
	v_mfma_f32_16x16x32_bf16 v[46:49], v[156:159], v[194:197], v[46:49]
	v_mfma_f32_16x16x32_bf16 v[46:49], v[166:169], v[202:205], v[46:49]
	v_mfma_f32_16x16x32_bf16 v[54:57], v[152:155], v[202:205], v[54:57]
	v_mfma_f32_16x16x32_bf16 v[54:57], v[148:151], v[194:197], v[54:57]
	v_mfma_f32_16x16x32_bf16 v[38:41], v[148:151], v[206:209], v[38:41]
	v_mfma_f32_16x16x32_bf16 v[38:41], v[152:155], v[210:213], v[38:41]
	v_mfma_f32_16x16x32_bf16 v[30:33], v[166:169], v[210:213], v[30:33]
	v_mfma_f32_16x16x32_bf16 v[30:33], v[156:159], v[206:209], v[30:33]
	v_mfma_f32_16x16x32_bf16 v[14:17], v[156:159], v[214:217], v[14:17]
	v_mfma_f32_16x16x32_bf16 v[14:17], v[166:169], v[218:221], v[14:17]
	v_mfma_f32_16x16x32_bf16 v[22:25], v[152:155], v[218:221], v[22:25]
	v_mfma_f32_16x16x32_bf16 v[22:25], v[148:151], v[214:217], v[22:25]
	v_mfma_f32_16x16x32_bf16 v[50:53], v[170:173], v[186:189], v[50:53]
	v_mfma_f32_16x16x32_bf16 v[50:53], v[174:177], v[190:193], v[50:53]
	v_mfma_f32_16x16x32_bf16 v[42:45], v[182:185], v[190:193], v[42:45]
	v_mfma_f32_16x16x32_bf16 v[42:45], v[178:181], v[186:189], v[42:45]
	v_mfma_f32_16x16x32_bf16 v[26:29], v[178:181], v[194:197], v[26:29]
	v_mfma_f32_16x16x32_bf16 v[26:29], v[182:185], v[202:205], v[26:29]
	v_mfma_f32_16x16x32_bf16 v[34:37], v[174:177], v[202:205], v[34:37]
	v_mfma_f32_16x16x32_bf16 v[34:37], v[170:173], v[194:197], v[34:37]
	v_mfma_f32_16x16x32_bf16 v[18:21], v[170:173], v[206:209], v[18:21]
	v_mfma_f32_16x16x32_bf16 v[18:21], v[174:177], v[210:213], v[18:21]
	v_mfma_f32_16x16x32_bf16 v[10:13], v[182:185], v[210:213], v[10:13]
	v_mfma_f32_16x16x32_bf16 v[10:13], v[178:181], v[206:209], v[10:13]
	v_mfma_f32_16x16x32_bf16 v[2:5], v[178:181], v[214:217], v[2:5]
	v_mfma_f32_16x16x32_bf16 v[2:5], v[182:185], v[218:221], v[2:5]
	v_mfma_f32_16x16x32_bf16 v[6:9], v[174:177], v[218:221], v[6:9]
	v_mfma_f32_16x16x32_bf16 v[6:9], v[170:173], v[214:217], v[6:9]
	s_setprio 0
	s_barrier
	v_add_u32_e32 v147, s92, v142
	ds_read_b128 v[148:151], v147
	ds_read_b128 v[152:155], v147 offset:1024
	ds_read_b128 v[156:159], v147 offset:2048
	ds_read_b128 v[166:169], v147 offset:3072
	v_add_u32_e32 v147, s89, v142
	ds_read_b128 v[170:173], v147
	ds_read_b128 v[174:177], v147 offset:1024
	ds_read_b128 v[178:181], v147 offset:2048
	ds_read_b128 v[182:185], v147 offset:3072
	s_mov_b32 m0, s49
	v_lshl_add_u64 v[226:227], s[64:65], 0, v[130:131]
	ds_read_b128 v[186:189], v146 offset:32768
	ds_read_b128 v[190:193], v146 offset:33792
	ds_read_b128 v[194:197], v146 offset:34816
	ds_read_b128 v[202:205], v146 offset:35840
	ds_read_b128 v[206:209], v146 offset:36864
	ds_read_b128 v[210:213], v146 offset:37888
	ds_read_b128 v[214:217], v146 offset:38912
	ds_read_b128 v[218:221], v146 offset:39936
	global_load_lds_dwordx4 v[226:227], off
	v_lshl_add_u64 v[226:227], s[64:65], 0, v[134:135]
	s_mov_b32 m0, s74
	s_nop 0
	global_load_lds_dwordx4 v[226:227], off
	s_waitcnt vmcnt(8)
	s_waitcnt lgkmcnt(0)
	s_barrier
	s_setprio 1
	v_mfma_f32_16x16x32_bf16 v[126:129], v[148:151], v[186:189], v[126:129]
	v_mfma_f32_16x16x32_bf16 v[126:129], v[152:155], v[190:193], v[126:129]
	v_mfma_f32_16x16x32_bf16 v[122:125], v[166:169], v[190:193], v[122:125]
	v_mfma_f32_16x16x32_bf16 v[122:125], v[156:159], v[186:189], v[122:125]
	v_mfma_f32_16x16x32_bf16 v[110:113], v[156:159], v[194:197], v[110:113]
	v_mfma_f32_16x16x32_bf16 v[110:113], v[166:169], v[202:205], v[110:113]
	v_mfma_f32_16x16x32_bf16 v[118:121], v[152:155], v[202:205], v[118:121]
	v_mfma_f32_16x16x32_bf16 v[118:121], v[148:151], v[194:197], v[118:121]
	v_mfma_f32_16x16x32_bf16 v[102:105], v[148:151], v[206:209], v[102:105]
	v_mfma_f32_16x16x32_bf16 v[102:105], v[152:155], v[210:213], v[102:105]
	v_mfma_f32_16x16x32_bf16 v[94:97], v[166:169], v[210:213], v[94:97]
	v_mfma_f32_16x16x32_bf16 v[94:97], v[156:159], v[206:209], v[94:97]
	v_mfma_f32_16x16x32_bf16 v[78:81], v[156:159], v[214:217], v[78:81]
	v_mfma_f32_16x16x32_bf16 v[78:81], v[166:169], v[218:221], v[78:81]
	v_mfma_f32_16x16x32_bf16 v[86:89], v[152:155], v[218:221], v[86:89]
	v_mfma_f32_16x16x32_bf16 v[86:89], v[148:151], v[214:217], v[86:89]
	v_mfma_f32_16x16x32_bf16 v[114:117], v[170:173], v[186:189], v[114:117]
	v_mfma_f32_16x16x32_bf16 v[114:117], v[174:177], v[190:193], v[114:117]
	v_mfma_f32_16x16x32_bf16 v[106:109], v[182:185], v[190:193], v[106:109]
	v_mfma_f32_16x16x32_bf16 v[106:109], v[178:181], v[186:189], v[106:109]
	v_mfma_f32_16x16x32_bf16 v[90:93], v[178:181], v[194:197], v[90:93]
	v_mfma_f32_16x16x32_bf16 v[90:93], v[182:185], v[202:205], v[90:93]
	v_mfma_f32_16x16x32_bf16 v[98:101], v[174:177], v[202:205], v[98:101]
	v_mfma_f32_16x16x32_bf16 v[98:101], v[170:173], v[194:197], v[98:101]
	v_mfma_f32_16x16x32_bf16 v[82:85], v[170:173], v[206:209], v[82:85]
	v_mfma_f32_16x16x32_bf16 v[82:85], v[174:177], v[210:213], v[82:85]
	v_mfma_f32_16x16x32_bf16 v[74:77], v[182:185], v[210:213], v[74:77]
	v_mfma_f32_16x16x32_bf16 v[74:77], v[178:181], v[206:209], v[74:77]
	v_mfma_f32_16x16x32_bf16 v[66:69], v[178:181], v[214:217], v[66:69]
	v_mfma_f32_16x16x32_bf16 v[66:69], v[182:185], v[218:221], v[66:69]
	v_mfma_f32_16x16x32_bf16 v[70:73], v[174:177], v[218:221], v[70:73]
	v_mfma_f32_16x16x32_bf16 v[70:73], v[170:173], v[214:217], v[70:73]
	s_setprio 0
	s_barrier
	s_mov_b32 m0, s87
	v_lshl_add_u64 v[160:161], v[160:161], 0, s[10:11]
	ds_read_b128 v[186:189], v146 offset:49152
	ds_read_b128 v[190:193], v146 offset:50176
	ds_read_b128 v[194:197], v146 offset:51200
	ds_read_b128 v[202:205], v146 offset:52224
	ds_read_b128 v[206:209], v146 offset:53248
	ds_read_b128 v[210:213], v146 offset:54272
	ds_read_b128 v[214:217], v146 offset:55296
	ds_read_b128 v[218:221], v146 offset:56320
	global_load_lds_dwordx4 v[160:161], off
	v_lshl_add_u64 v[160:161], v[198:199], 0, s[10:11]
	s_mov_b32 m0, s85
	s_nop 0
	global_load_lds_dwordx4 v[160:161], off
	v_lshl_add_u64 v[160:161], s[62:63], 0, v[132:133]
	s_mov_b32 m0, s86
	s_nop 0
	global_load_lds_dwordx4 v[160:161], off
	v_lshl_add_u64 v[160:161], s[62:63], 0, v[136:137]
	s_mov_b32 m0, s44
	s_nop 0
	global_load_lds_dwordx4 v[160:161], off
	v_lshl_add_u64 v[160:161], v[222:223], 0, s[10:11]
	s_mov_b32 m0, s76
	s_nop 0
	global_load_lds_dwordx4 v[160:161], off
	v_lshl_add_u64 v[160:161], v[224:225], 0, s[10:11]
	s_mov_b32 m0, s77
	s_nop 0
	global_load_lds_dwordx4 v[160:161], off
	s_waitcnt vmcnt(8)
	s_waitcnt lgkmcnt(0)
	s_barrier
	s_setprio 1
	v_mfma_f32_16x16x32_bf16 v[62:65], v[148:151], v[186:189], v[62:65]
	v_mfma_f32_16x16x32_bf16 v[62:65], v[152:155], v[190:193], v[62:65]
	v_mfma_f32_16x16x32_bf16 v[58:61], v[166:169], v[190:193], v[58:61]
	v_mfma_f32_16x16x32_bf16 v[58:61], v[156:159], v[186:189], v[58:61]
	v_mfma_f32_16x16x32_bf16 v[46:49], v[156:159], v[194:197], v[46:49]
	v_mfma_f32_16x16x32_bf16 v[46:49], v[166:169], v[202:205], v[46:49]
	v_mfma_f32_16x16x32_bf16 v[54:57], v[152:155], v[202:205], v[54:57]
	v_mfma_f32_16x16x32_bf16 v[54:57], v[148:151], v[194:197], v[54:57]
	v_mfma_f32_16x16x32_bf16 v[38:41], v[148:151], v[206:209], v[38:41]
	v_mfma_f32_16x16x32_bf16 v[38:41], v[152:155], v[210:213], v[38:41]
	v_mfma_f32_16x16x32_bf16 v[30:33], v[166:169], v[210:213], v[30:33]
	v_mfma_f32_16x16x32_bf16 v[30:33], v[156:159], v[206:209], v[30:33]
	v_mfma_f32_16x16x32_bf16 v[14:17], v[156:159], v[214:217], v[14:17]
	v_mfma_f32_16x16x32_bf16 v[14:17], v[166:169], v[218:221], v[14:17]
	v_mfma_f32_16x16x32_bf16 v[22:25], v[152:155], v[218:221], v[22:25]
	v_mfma_f32_16x16x32_bf16 v[22:25], v[148:151], v[214:217], v[22:25]
	v_mfma_f32_16x16x32_bf16 v[50:53], v[170:173], v[186:189], v[50:53]
	v_mfma_f32_16x16x32_bf16 v[50:53], v[174:177], v[190:193], v[50:53]
	v_mfma_f32_16x16x32_bf16 v[42:45], v[182:185], v[190:193], v[42:45]
	v_mfma_f32_16x16x32_bf16 v[42:45], v[178:181], v[186:189], v[42:45]
	v_mfma_f32_16x16x32_bf16 v[26:29], v[178:181], v[194:197], v[26:29]
	v_mfma_f32_16x16x32_bf16 v[26:29], v[182:185], v[202:205], v[26:29]
	v_mfma_f32_16x16x32_bf16 v[34:37], v[174:177], v[202:205], v[34:37]
	v_mfma_f32_16x16x32_bf16 v[34:37], v[170:173], v[194:197], v[34:37]
	v_mfma_f32_16x16x32_bf16 v[18:21], v[170:173], v[206:209], v[18:21]
	v_mfma_f32_16x16x32_bf16 v[18:21], v[174:177], v[210:213], v[18:21]
	v_mfma_f32_16x16x32_bf16 v[10:13], v[182:185], v[210:213], v[10:13]
	v_mfma_f32_16x16x32_bf16 v[10:13], v[178:181], v[206:209], v[10:13]
	v_mfma_f32_16x16x32_bf16 v[2:5], v[178:181], v[214:217], v[2:5]
	v_mfma_f32_16x16x32_bf16 v[2:5], v[182:185], v[218:221], v[2:5]
	v_mfma_f32_16x16x32_bf16 v[6:9], v[174:177], v[218:221], v[6:9]
	v_mfma_f32_16x16x32_bf16 v[6:9], v[170:173], v[214:217], v[6:9]
	s_setprio 0
	s_barrier
	s_movk_i32 s44, 0x100
	s_andn2_b64 vcc, exec, s[60:61]
	s_mov_b64 s[62:63], -1
	s_mov_b64 s[60:61], 0
	s_cbranch_vccz .LBB0_722
	s_and_b64 vcc, exec, s[12:13]
	s_cbranch_vccz .LBB0_725
	s_barrier

.LBB0_1226:
	v_add_u32_e32 v3, s71, v165
	ds_read_b128 v[150:153], v3
	ds_read_b128 v[154:157], v3 offset:1024
	ds_read_b128 v[158:161], v3 offset:2048
	ds_read_b128 v[170:173], v3 offset:3072
	v_add_u32_e32 v3, s72, v165
	ds_read_b128 v[174:177], v3
	ds_read_b128 v[178:181], v3 offset:1024
	ds_read_b128 v[182:185], v3 offset:2048
	ds_read_b128 v[186:189], v3 offset:3072
	s_add_u32 s36, s52, 0xfff80080
	s_addc_u32 s37, s53, -1
	s_cmp_eq_u32 s78, 28
	s_cselect_b32 s59, s21, s37
	s_cselect_b32 s58, s44, s36
	s_cselect_b32 s57, s19, s77
	s_cselect_b32 s56, s55, s76
	v_lshl_add_u64 v[4:5], s[52:53], 0, v[142:143]
	s_add_i32 m0, s63, 0xc000
	ds_read_b128 v[190:193], v169
	ds_read_b128 v[194:197], v169 offset:1024
	ds_read_b128 v[202:205], v169 offset:2048
	ds_read_b128 v[206:209], v169 offset:3072
	ds_read_b128 v[210:213], v169 offset:4096
	ds_read_b128 v[214:217], v169 offset:5120
	ds_read_b128 v[218:221], v169 offset:6144
	ds_read_b128 v[222:225], v169 offset:7168
	global_load_lds_dwordx4 v[4:5], off
	v_lshl_add_u64 v[4:5], s[52:53], 0, v[144:145]
	s_add_i32 m0, s63, 0xe000
	s_nop 0
	global_load_lds_dwordx4 v[4:5], off
	s_waitcnt vmcnt(8)
	s_waitcnt lgkmcnt(0)
	s_barrier
	s_setprio 1
	v_mfma_f32_16x16x32_bf16 v[130:133], v[150:153], v[190:193], v[130:133]
	v_mfma_f32_16x16x32_bf16 v[130:133], v[154:157], v[194:197], v[130:133]
	v_mfma_f32_16x16x32_bf16 v[126:129], v[170:173], v[194:197], v[126:129]
	v_mfma_f32_16x16x32_bf16 v[126:129], v[158:161], v[190:193], v[126:129]
	v_mfma_f32_16x16x32_bf16 v[118:121], v[158:161], v[202:205], v[118:121]
	v_mfma_f32_16x16x32_bf16 v[118:121], v[170:173], v[206:209], v[118:121]
	v_mfma_f32_16x16x32_bf16 v[122:125], v[154:157], v[206:209], v[122:125]
	v_mfma_f32_16x16x32_bf16 v[122:125], v[150:153], v[202:205], v[122:125]
	v_mfma_f32_16x16x32_bf16 v[114:117], v[150:153], v[210:213], v[114:117]
	v_mfma_f32_16x16x32_bf16 v[114:117], v[154:157], v[214:217], v[114:117]
	v_mfma_f32_16x16x32_bf16 v[110:113], v[170:173], v[214:217], v[110:113]
	v_mfma_f32_16x16x32_bf16 v[110:113], v[158:161], v[210:213], v[110:113]
	v_mfma_f32_16x16x32_bf16 v[102:105], v[158:161], v[218:221], v[102:105]
	v_mfma_f32_16x16x32_bf16 v[102:105], v[170:173], v[222:225], v[102:105]
	v_mfma_f32_16x16x32_bf16 v[106:109], v[154:157], v[222:225], v[106:109]
	v_mfma_f32_16x16x32_bf16 v[106:109], v[150:153], v[218:221], v[106:109]
	v_mfma_f32_16x16x32_bf16 v[98:101], v[174:177], v[190:193], v[98:101]
	v_mfma_f32_16x16x32_bf16 v[98:101], v[178:181], v[194:197], v[98:101]
	v_mfma_f32_16x16x32_bf16 v[94:97], v[186:189], v[194:197], v[94:97]
	v_mfma_f32_16x16x32_bf16 v[94:97], v[182:185], v[190:193], v[94:97]
	v_mfma_f32_16x16x32_bf16 v[86:89], v[182:185], v[202:205], v[86:89]
	v_mfma_f32_16x16x32_bf16 v[86:89], v[186:189], v[206:209], v[86:89]
	v_mfma_f32_16x16x32_bf16 v[90:93], v[178:181], v[206:209], v[90:93]
	v_mfma_f32_16x16x32_bf16 v[90:93], v[174:177], v[202:205], v[90:93]
	v_mfma_f32_16x16x32_bf16 v[82:85], v[174:177], v[210:213], v[82:85]
	v_mfma_f32_16x16x32_bf16 v[82:85], v[178:181], v[214:217], v[82:85]
	v_mfma_f32_16x16x32_bf16 v[78:81], v[186:189], v[214:217], v[78:81]
	v_mfma_f32_16x16x32_bf16 v[78:81], v[182:185], v[210:213], v[78:81]
	v_mfma_f32_16x16x32_bf16 v[70:73], v[182:185], v[218:221], v[70:73]
	v_mfma_f32_16x16x32_bf16 v[70:73], v[186:189], v[222:225], v[70:73]
	v_mfma_f32_16x16x32_bf16 v[74:77], v[178:181], v[222:225], v[74:77]
	v_mfma_f32_16x16x32_bf16 v[74:77], v[174:177], v[218:221], v[74:77]
	s_setprio 0
	s_barrier
	s_add_i32 s36, s71, s43
	v_lshl_add_u64 v[166:167], s[56:57], 0, v[138:139]
	s_mov_b32 m0, s36
	ds_read_b128 v[190:193], v169 offset:16384
	ds_read_b128 v[194:197], v169 offset:17408
	ds_read_b128 v[202:205], v169 offset:18432
	ds_read_b128 v[206:209], v169 offset:19456
	ds_read_b128 v[210:213], v169 offset:20480
	ds_read_b128 v[214:217], v169 offset:21504
	ds_read_b128 v[218:221], v169 offset:22528
	ds_read_b128 v[222:225], v169 offset:23552
	global_load_lds_dwordx4 v[166:167], off
	s_add_i32 m0, s36, 0x2000
	s_add_u32 s80, s56, 0x80000
	v_lshl_add_u64 v[198:199], s[56:57], 0, v[134:135]
	s_addc_u32 s81, s57, 0
	s_add_i32 s36, s72, s43
	global_load_lds_dwordx4 v[198:199], off
	v_lshl_add_u64 v[4:5], s[80:81], 0, v[138:139]
	s_mov_b32 m0, s36
	v_lshl_add_u64 v[226:227], s[58:59], 0, v[140:141]
	global_load_lds_dwordx4 v[4:5], off
	v_lshl_add_u64 v[4:5], s[80:81], 0, v[134:135]
	s_add_i32 m0, s36, 0x2000
	v_lshl_add_u64 v[228:229], s[58:59], 0, v[136:137]
	global_load_lds_dwordx4 v[4:5], off
	s_mov_b32 m0, s63
	s_nop 0
	global_load_lds_dwordx4 v[226:227], off
	s_mov_b32 m0, s64
	s_nop 0
	global_load_lds_dwordx4 v[228:229], off
	s_waitcnt vmcnt(8)
	s_waitcnt lgkmcnt(0)
	s_barrier
	s_setprio 1
	v_mfma_f32_16x16x32_bf16 v[66:69], v[150:153], v[190:193], v[66:69]
	v_mfma_f32_16x16x32_bf16 v[66:69], v[154:157], v[194:197], v[66:69]
	v_mfma_f32_16x16x32_bf16 v[62:65], v[170:173], v[194:197], v[62:65]
	v_mfma_f32_16x16x32_bf16 v[62:65], v[158:161], v[190:193], v[62:65]
	v_mfma_f32_16x16x32_bf16 v[54:57], v[158:161], v[202:205], v[54:57]
	v_mfma_f32_16x16x32_bf16 v[54:57], v[170:173], v[206:209], v[54:57]
	v_mfma_f32_16x16x32_bf16 v[58:61], v[154:157], v[206:209], v[58:61]
	v_mfma_f32_16x16x32_bf16 v[58:61], v[150:153], v[202:205], v[58:61]
	v_mfma_f32_16x16x32_bf16 v[50:53], v[150:153], v[210:213], v[50:53]
	v_mfma_f32_16x16x32_bf16 v[50:53], v[154:157], v[214:217], v[50:53]
	v_mfma_f32_16x16x32_bf16 v[46:49], v[170:173], v[214:217], v[46:49]
	v_mfma_f32_16x16x32_bf16 v[46:49], v[158:161], v[210:213], v[46:49]
	v_mfma_f32_16x16x32_bf16 v[38:41], v[158:161], v[218:221], v[38:41]
	v_mfma_f32_16x16x32_bf16 v[38:41], v[170:173], v[222:225], v[38:41]
	v_mfma_f32_16x16x32_bf16 v[42:45], v[154:157], v[222:225], v[42:45]
	v_mfma_f32_16x16x32_bf16 v[42:45], v[150:153], v[218:221], v[42:45]
	v_mfma_f32_16x16x32_bf16 v[34:37], v[174:177], v[190:193], v[34:37]
	v_mfma_f32_16x16x32_bf16 v[30:33], v[182:185], v[190:193], v[30:33]
	v_mfma_f32_16x16x32_bf16 v[26:29], v[174:177], v[202:205], v[26:29]
	v_mfma_f32_16x16x32_bf16 v[22:25], v[182:185], v[202:205], v[22:25]
	v_mfma_f32_16x16x32_bf16 v[18:21], v[174:177], v[210:213], v[18:21]
	v_mfma_f32_16x16x32_bf16 v[14:17], v[182:185], v[210:213], v[14:17]
	v_mfma_f32_16x16x32_bf16 v[10:13], v[174:177], v[218:221], v[10:13]
	v_mfma_f32_16x16x32_bf16 v[4:7], v[182:185], v[218:221], v[6:9]
	v_mfma_f32_16x16x32_bf16 v[34:37], v[178:181], v[194:197], v[34:37]
	v_mfma_f32_16x16x32_bf16 v[30:33], v[186:189], v[194:197], v[30:33]
	v_mfma_f32_16x16x32_bf16 v[26:29], v[178:181], v[206:209], v[26:29]
	v_mfma_f32_16x16x32_bf16 v[22:25], v[186:189], v[206:209], v[22:25]
	v_mfma_f32_16x16x32_bf16 v[18:21], v[178:181], v[214:217], v[18:21]
	v_mfma_f32_16x16x32_bf16 v[14:17], v[186:189], v[214:217], v[14:17]
	v_mfma_f32_16x16x32_bf16 v[10:13], v[178:181], v[222:225], v[10:13]
	v_mfma_f32_16x16x32_bf16 v[4:7], v[186:189], v[222:225], v[4:7]
	s_setprio 0
	s_barrier
	s_add_i32 s36, 0, 0x18000
	v_add_u32_e32 v3, s36, v165
	s_add_i32 s37, 0, 0x1c000
	ds_read_b128 v[150:153], v3
	ds_read_b128 v[154:157], v3 offset:1024
	ds_read_b128 v[158:161], v3 offset:2048
	ds_read_b128 v[170:173], v3 offset:3072
	v_add_u32_e32 v3, s37, v165
	ds_read_b128 v[174:177], v3
	ds_read_b128 v[178:181], v3 offset:1024
	ds_read_b128 v[182:185], v3 offset:2048
	ds_read_b128 v[186:189], v3 offset:3072
	s_add_u32 s58, s58, 0x80000
	s_addc_u32 s59, s59, 0
	s_mov_b32 m0, s65
	v_lshl_add_u64 v[8:9], s[58:59], 0, v[140:141]
	ds_read_b128 v[190:193], v169 offset:32768
	ds_read_b128 v[194:197], v169 offset:33792
	ds_read_b128 v[202:205], v169 offset:34816
	ds_read_b128 v[206:209], v169 offset:35840
	ds_read_b128 v[210:213], v169 offset:36864
	ds_read_b128 v[214:217], v169 offset:37888
	ds_read_b128 v[218:221], v169 offset:38912
	ds_read_b128 v[222:225], v169 offset:39936
	global_load_lds_dwordx4 v[8:9], off
	v_lshl_add_u64 v[8:9], s[58:59], 0, v[136:137]
	s_mov_b32 m0, s66
	s_nop 0
	global_load_lds_dwordx4 v[8:9], off
	s_waitcnt vmcnt(8)
	s_waitcnt lgkmcnt(0)
	s_barrier
	s_setprio 1
	v_mfma_f32_16x16x32_bf16 v[130:133], v[150:153], v[190:193], v[130:133]
	v_mfma_f32_16x16x32_bf16 v[130:133], v[154:157], v[194:197], v[130:133]
	v_mfma_f32_16x16x32_bf16 v[126:129], v[170:173], v[194:197], v[126:129]
	v_mfma_f32_16x16x32_bf16 v[126:129], v[158:161], v[190:193], v[126:129]
	v_mfma_f32_16x16x32_bf16 v[118:121], v[158:161], v[202:205], v[118:121]
	v_mfma_f32_16x16x32_bf16 v[118:121], v[170:173], v[206:209], v[118:121]
	v_mfma_f32_16x16x32_bf16 v[122:125], v[154:157], v[206:209], v[122:125]
	v_mfma_f32_16x16x32_bf16 v[122:125], v[150:153], v[202:205], v[122:125]
	v_mfma_f32_16x16x32_bf16 v[114:117], v[150:153], v[210:213], v[114:117]
	v_mfma_f32_16x16x32_bf16 v[114:117], v[154:157], v[214:217], v[114:117]
	v_mfma_f32_16x16x32_bf16 v[110:113], v[170:173], v[214:217], v[110:113]
	v_mfma_f32_16x16x32_bf16 v[110:113], v[158:161], v[210:213], v[110:113]
	v_mfma_f32_16x16x32_bf16 v[102:105], v[158:161], v[218:221], v[102:105]
	v_mfma_f32_16x16x32_bf16 v[102:105], v[170:173], v[222:225], v[102:105]
	v_mfma_f32_16x16x32_bf16 v[106:109], v[154:157], v[222:225], v[106:109]
	v_mfma_f32_16x16x32_bf16 v[106:109], v[150:153], v[218:221], v[106:109]
	v_mfma_f32_16x16x32_bf16 v[98:101], v[174:177], v[190:193], v[98:101]
	v_mfma_f32_16x16x32_bf16 v[98:101], v[178:181], v[194:197], v[98:101]
	v_mfma_f32_16x16x32_bf16 v[94:97], v[186:189], v[194:197], v[94:97]
	v_mfma_f32_16x16x32_bf16 v[94:97], v[182:185], v[190:193], v[94:97]
	v_mfma_f32_16x16x32_bf16 v[86:89], v[182:185], v[202:205], v[86:89]
	v_mfma_f32_16x16x32_bf16 v[86:89], v[186:189], v[206:209], v[86:89]
	v_mfma_f32_16x16x32_bf16 v[90:93], v[178:181], v[206:209], v[90:93]
	v_mfma_f32_16x16x32_bf16 v[90:93], v[174:177], v[202:205], v[90:93]
	v_mfma_f32_16x16x32_bf16 v[82:85], v[174:177], v[210:213], v[82:85]
	v_mfma_f32_16x16x32_bf16 v[82:85], v[178:181], v[214:217], v[82:85]
	v_mfma_f32_16x16x32_bf16 v[78:81], v[186:189], v[214:217], v[78:81]
	v_mfma_f32_16x16x32_bf16 v[78:81], v[182:185], v[210:213], v[78:81]
	v_mfma_f32_16x16x32_bf16 v[70:73], v[182:185], v[218:221], v[70:73]
	v_mfma_f32_16x16x32_bf16 v[70:73], v[186:189], v[222:225], v[70:73]
	v_mfma_f32_16x16x32_bf16 v[74:77], v[178:181], v[222:225], v[74:77]
	v_mfma_f32_16x16x32_bf16 v[74:77], v[174:177], v[218:221], v[74:77]
	s_setprio 0
	s_barrier
	s_add_i32 s36, s36, s43
	v_lshl_add_u64 v[8:9], v[166:167], 0, s[10:11]
	s_mov_b32 m0, s36
	ds_read_b128 v[190:193], v169 offset:49152
	ds_read_b128 v[194:197], v169 offset:50176
	ds_read_b128 v[202:205], v169 offset:51200
	ds_read_b128 v[206:209], v169 offset:52224
	ds_read_b128 v[210:213], v169 offset:53248
	ds_read_b128 v[214:217], v169 offset:54272
	ds_read_b128 v[218:221], v169 offset:55296
	ds_read_b128 v[222:225], v169 offset:56320
	global_load_lds_dwordx4 v[8:9], off
	s_add_i32 m0, s36, 0x2000
	s_add_u32 s56, s56, 0x80080
	v_lshl_add_u64 v[8:9], v[198:199], 0, s[10:11]
	s_addc_u32 s57, s57, 0
	s_add_i32 s36, s37, s43
	global_load_lds_dwordx4 v[8:9], off
	v_lshl_add_u64 v[8:9], s[56:57], 0, v[138:139]
	s_mov_b32 m0, s36
	s_nop 0
	global_load_lds_dwordx4 v[8:9], off
	v_lshl_add_u64 v[8:9], s[56:57], 0, v[134:135]
	s_add_i32 m0, s36, 0x2000
	s_nop 0
	global_load_lds_dwordx4 v[8:9], off
	v_lshl_add_u64 v[8:9], v[226:227], 0, s[10:11]
	s_mov_b32 m0, s69
	s_nop 0
	global_load_lds_dwordx4 v[8:9], off
	v_lshl_add_u64 v[8:9], v[228:229], 0, s[10:11]
	s_mov_b32 m0, s70
	s_nop 0
	global_load_lds_dwordx4 v[8:9], off
	s_waitcnt vmcnt(8)
	s_waitcnt lgkmcnt(0)
	s_barrier
	s_setprio 1
	v_mfma_f32_16x16x32_bf16 v[66:69], v[150:153], v[190:193], v[66:69]
	v_mfma_f32_16x16x32_bf16 v[66:69], v[154:157], v[194:197], v[66:69]
	v_mfma_f32_16x16x32_bf16 v[62:65], v[170:173], v[194:197], v[62:65]
	v_mfma_f32_16x16x32_bf16 v[62:65], v[158:161], v[190:193], v[62:65]
	v_mfma_f32_16x16x32_bf16 v[54:57], v[158:161], v[202:205], v[54:57]
	v_mfma_f32_16x16x32_bf16 v[54:57], v[170:173], v[206:209], v[54:57]
	v_mfma_f32_16x16x32_bf16 v[58:61], v[154:157], v[206:209], v[58:61]
	v_mfma_f32_16x16x32_bf16 v[58:61], v[150:153], v[202:205], v[58:61]
	v_mfma_f32_16x16x32_bf16 v[50:53], v[150:153], v[210:213], v[50:53]
	v_mfma_f32_16x16x32_bf16 v[50:53], v[154:157], v[214:217], v[50:53]
	v_mfma_f32_16x16x32_bf16 v[46:49], v[170:173], v[214:217], v[46:49]
	v_mfma_f32_16x16x32_bf16 v[46:49], v[158:161], v[210:213], v[46:49]
	v_mfma_f32_16x16x32_bf16 v[38:41], v[158:161], v[218:221], v[38:41]
	v_mfma_f32_16x16x32_bf16 v[38:41], v[170:173], v[222:225], v[38:41]
	v_mfma_f32_16x16x32_bf16 v[42:45], v[154:157], v[222:225], v[42:45]
	v_mfma_f32_16x16x32_bf16 v[42:45], v[150:153], v[218:221], v[42:45]
	v_mfma_f32_16x16x32_bf16 v[34:37], v[174:177], v[190:193], v[34:37]
	v_mfma_f32_16x16x32_bf16 v[30:33], v[182:185], v[190:193], v[30:33]
	v_mfma_f32_16x16x32_bf16 v[26:29], v[174:177], v[202:205], v[26:29]
	v_mfma_f32_16x16x32_bf16 v[22:25], v[182:185], v[202:205], v[22:25]
	v_mfma_f32_16x16x32_bf16 v[18:21], v[174:177], v[210:213], v[18:21]
	v_mfma_f32_16x16x32_bf16 v[14:17], v[182:185], v[210:213], v[14:17]
	v_mfma_f32_16x16x32_bf16 v[8:11], v[174:177], v[218:221], v[10:13]
	v_mfma_f32_16x16x32_bf16 v[4:7], v[182:185], v[218:221], v[4:7]
	v_mfma_f32_16x16x32_bf16 v[34:37], v[178:181], v[194:197], v[34:37]
	v_mfma_f32_16x16x32_bf16 v[30:33], v[186:189], v[194:197], v[30:33]
	v_mfma_f32_16x16x32_bf16 v[26:29], v[178:181], v[206:209], v[26:29]
	v_mfma_f32_16x16x32_bf16 v[22:25], v[186:189], v[206:209], v[22:25]
	v_mfma_f32_16x16x32_bf16 v[18:21], v[178:181], v[214:217], v[18:21]
	v_mfma_f32_16x16x32_bf16 v[14:17], v[186:189], v[214:217], v[14:17]
	v_mfma_f32_16x16x32_bf16 v[10:13], v[178:181], v[222:225], v[8:11]
	v_mfma_f32_16x16x32_bf16 v[6:9], v[186:189], v[222:225], v[4:7]
	s_setprio 0
	s_barrier
	s_add_i32 s78, s78, 2
	s_add_u32 s52, s52, 0x100
	s_addc_u32 s53, s53, 0
	s_add_u32 s76, s76, 0x100
	s_addc_u32 s77, s77, 0
	s_cmp_gt_u32 s78, 29
	s_cbranch_scc0 .LBB0_1226
	s_and_b64 vcc, exec, s[12:13]
	s_cbranch_vccz .LBB0_1229
	s_barrier

.LBB0_1397:
	ds_read_b128 v[146:149], v154
	ds_read_b128 v[158:161], v154 offset:1024
	ds_read_b128 v[166:169], v154 offset:2048
	ds_read_b128 v[170:173], v154 offset:3072
	ds_read_b128 v[174:177], v155
	ds_read_b128 v[178:181], v155 offset:1024
	ds_read_b128 v[182:185], v155 offset:2048
	ds_read_b128 v[186:189], v155 offset:3072
	s_add_i32 s93, s44, 2
	s_add_u32 s36, s62, 0xfff00080
	s_addc_u32 s37, s63, -1
	s_cmp_eq_u32 s59, s44
	s_cselect_b32 s67, s38, s37
	s_cselect_b32 s66, s39, s36
	s_cselect_b32 s65, s51, s92
	s_cselect_b32 s64, s53, s61
	v_lshl_add_u64 v[150:151], s[62:63], 0, v[140:141]
	s_add_i32 m0, s72, 0xc000
	ds_read_b128 v[190:193], v156
	ds_read_b128 v[194:197], v156 offset:1024
	ds_read_b128 v[202:205], v156 offset:2048
	ds_read_b128 v[206:209], v156 offset:3072
	ds_read_b128 v[210:213], v156 offset:4096
	ds_read_b128 v[214:217], v156 offset:5120
	ds_read_b128 v[218:221], v156 offset:6144
	ds_read_b128 v[222:225], v156 offset:7168
	global_load_lds_dwordx4 v[150:151], off
	v_lshl_add_u64 v[150:151], s[62:63], 0, v[142:143]
	s_add_i32 m0, s72, 0xe000
	s_nop 0
	global_load_lds_dwordx4 v[150:151], off
	s_waitcnt vmcnt(8)
	s_waitcnt lgkmcnt(0)
	s_barrier
	s_setprio 1
	v_mfma_f32_16x16x32_bf16 v[126:129], v[146:149], v[190:193], v[126:129]
	v_mfma_f32_16x16x32_bf16 v[126:129], v[158:161], v[194:197], v[126:129]
	v_mfma_f32_16x16x32_bf16 v[122:125], v[170:173], v[194:197], v[122:125]
	v_mfma_f32_16x16x32_bf16 v[122:125], v[166:169], v[190:193], v[122:125]
	v_mfma_f32_16x16x32_bf16 v[106:109], v[166:169], v[202:205], v[106:109]
	v_mfma_f32_16x16x32_bf16 v[106:109], v[170:173], v[206:209], v[106:109]
	v_mfma_f32_16x16x32_bf16 v[110:113], v[158:161], v[206:209], v[110:113]
	v_mfma_f32_16x16x32_bf16 v[110:113], v[146:149], v[202:205], v[110:113]
	v_mfma_f32_16x16x32_bf16 v[94:97], v[146:149], v[210:213], v[94:97]
	v_mfma_f32_16x16x32_bf16 v[94:97], v[158:161], v[214:217], v[94:97]
	v_mfma_f32_16x16x32_bf16 v[90:93], v[170:173], v[214:217], v[90:93]
	v_mfma_f32_16x16x32_bf16 v[90:93], v[166:169], v[210:213], v[90:93]
	v_mfma_f32_16x16x32_bf16 v[74:77], v[166:169], v[218:221], v[74:77]
	v_mfma_f32_16x16x32_bf16 v[74:77], v[170:173], v[222:225], v[74:77]
	v_mfma_f32_16x16x32_bf16 v[78:81], v[158:161], v[222:225], v[78:81]
	v_mfma_f32_16x16x32_bf16 v[78:81], v[146:149], v[218:221], v[78:81]
	v_mfma_f32_16x16x32_bf16 v[118:121], v[174:177], v[190:193], v[118:121]
	v_mfma_f32_16x16x32_bf16 v[118:121], v[178:181], v[194:197], v[118:121]
	v_mfma_f32_16x16x32_bf16 v[114:117], v[186:189], v[194:197], v[114:117]
	v_mfma_f32_16x16x32_bf16 v[114:117], v[182:185], v[190:193], v[114:117]
	v_mfma_f32_16x16x32_bf16 v[98:101], v[182:185], v[202:205], v[98:101]
	v_mfma_f32_16x16x32_bf16 v[98:101], v[186:189], v[206:209], v[98:101]
	v_mfma_f32_16x16x32_bf16 v[102:105], v[178:181], v[206:209], v[102:105]
	v_mfma_f32_16x16x32_bf16 v[102:105], v[174:177], v[202:205], v[102:105]
	v_mfma_f32_16x16x32_bf16 v[86:89], v[174:177], v[210:213], v[86:89]
	v_mfma_f32_16x16x32_bf16 v[86:89], v[178:181], v[214:217], v[86:89]
	v_mfma_f32_16x16x32_bf16 v[82:85], v[186:189], v[214:217], v[82:85]
	v_mfma_f32_16x16x32_bf16 v[82:85], v[182:185], v[210:213], v[82:85]
	v_mfma_f32_16x16x32_bf16 v[66:69], v[182:185], v[218:221], v[66:69]
	v_mfma_f32_16x16x32_bf16 v[66:69], v[186:189], v[222:225], v[66:69]
	v_mfma_f32_16x16x32_bf16 v[70:73], v[178:181], v[222:225], v[70:73]
	v_mfma_f32_16x16x32_bf16 v[70:73], v[174:177], v[218:221], v[70:73]
	s_setprio 0
	s_barrier
	s_add_i32 s36, s82, s69
	v_lshl_add_u64 v[150:151], s[64:65], 0, v[132:133]
	s_mov_b32 m0, s36
	ds_read_b128 v[190:193], v156 offset:16384
	ds_read_b128 v[194:197], v156 offset:17408
	ds_read_b128 v[202:205], v156 offset:18432
	ds_read_b128 v[206:209], v156 offset:19456
	ds_read_b128 v[210:213], v156 offset:20480
	ds_read_b128 v[214:217], v156 offset:21504
	ds_read_b128 v[218:221], v156 offset:22528
	ds_read_b128 v[222:225], v156 offset:23552
	global_load_lds_dwordx4 v[150:151], off
	s_add_i32 m0, s36, 0x2000
	s_add_u32 s94, s64, 0x100000
	v_lshl_add_u64 v[198:199], s[64:65], 0, v[136:137]
	s_addc_u32 s95, s65, 0
	s_add_i32 s36, s83, s69
	global_load_lds_dwordx4 v[198:199], off
	v_lshl_add_u64 v[226:227], s[94:95], 0, v[132:133]
	s_mov_b32 m0, s36
	v_lshl_add_u64 v[228:229], s[66:67], 0, v[134:135]
	global_load_lds_dwordx4 v[226:227], off
	v_lshl_add_u64 v[226:227], s[94:95], 0, v[136:137]
	s_add_i32 m0, s36, 0x2000
	s_nop 0
	global_load_lds_dwordx4 v[226:227], off
	v_lshl_add_u64 v[226:227], s[66:67], 0, v[130:131]
	s_mov_b32 m0, s72
	s_nop 0
	global_load_lds_dwordx4 v[226:227], off
	s_mov_b32 m0, s73
	s_nop 0
	global_load_lds_dwordx4 v[228:229], off
	s_waitcnt vmcnt(8)
	s_waitcnt lgkmcnt(0)
	s_barrier
	s_setprio 1
	v_mfma_f32_16x16x32_bf16 v[62:65], v[146:149], v[190:193], v[62:65]
	v_mfma_f32_16x16x32_bf16 v[62:65], v[158:161], v[194:197], v[62:65]
	v_mfma_f32_16x16x32_bf16 v[58:61], v[170:173], v[194:197], v[58:61]
	v_mfma_f32_16x16x32_bf16 v[58:61], v[166:169], v[190:193], v[58:61]
	v_mfma_f32_16x16x32_bf16 v[42:45], v[166:169], v[202:205], v[42:45]
	v_mfma_f32_16x16x32_bf16 v[42:45], v[170:173], v[206:209], v[42:45]
	v_mfma_f32_16x16x32_bf16 v[46:49], v[158:161], v[206:209], v[46:49]
	v_mfma_f32_16x16x32_bf16 v[46:49], v[146:149], v[202:205], v[46:49]
	v_mfma_f32_16x16x32_bf16 v[30:33], v[146:149], v[210:213], v[30:33]
	v_mfma_f32_16x16x32_bf16 v[30:33], v[158:161], v[214:217], v[30:33]
	v_mfma_f32_16x16x32_bf16 v[26:29], v[170:173], v[214:217], v[26:29]
	v_mfma_f32_16x16x32_bf16 v[26:29], v[166:169], v[210:213], v[26:29]
	v_mfma_f32_16x16x32_bf16 v[10:13], v[166:169], v[218:221], v[10:13]
	v_mfma_f32_16x16x32_bf16 v[10:13], v[170:173], v[222:225], v[10:13]
	v_mfma_f32_16x16x32_bf16 v[14:17], v[158:161], v[222:225], v[14:17]
	v_mfma_f32_16x16x32_bf16 v[14:17], v[146:149], v[218:221], v[14:17]
	v_mfma_f32_16x16x32_bf16 v[54:57], v[174:177], v[190:193], v[54:57]
	v_mfma_f32_16x16x32_bf16 v[54:57], v[178:181], v[194:197], v[54:57]
	v_mfma_f32_16x16x32_bf16 v[50:53], v[186:189], v[194:197], v[50:53]
	v_mfma_f32_16x16x32_bf16 v[50:53], v[182:185], v[190:193], v[50:53]
	v_mfma_f32_16x16x32_bf16 v[34:37], v[182:185], v[202:205], v[34:37]
	v_mfma_f32_16x16x32_bf16 v[34:37], v[186:189], v[206:209], v[34:37]
	v_mfma_f32_16x16x32_bf16 v[38:41], v[178:181], v[206:209], v[38:41]
	v_mfma_f32_16x16x32_bf16 v[38:41], v[174:177], v[202:205], v[38:41]
	v_mfma_f32_16x16x32_bf16 v[22:25], v[174:177], v[210:213], v[22:25]
	v_mfma_f32_16x16x32_bf16 v[22:25], v[178:181], v[214:217], v[22:25]
	v_mfma_f32_16x16x32_bf16 v[18:21], v[186:189], v[214:217], v[18:21]
	v_mfma_f32_16x16x32_bf16 v[18:21], v[182:185], v[210:213], v[18:21]
	v_mfma_f32_16x16x32_bf16 v[2:5], v[182:185], v[218:221], v[2:5]
	v_mfma_f32_16x16x32_bf16 v[2:5], v[186:189], v[222:225], v[2:5]
	v_mfma_f32_16x16x32_bf16 v[6:9], v[178:181], v[222:225], v[6:9]
	v_mfma_f32_16x16x32_bf16 v[6:9], v[174:177], v[218:221], v[6:9]
	s_setprio 0
	s_barrier
	s_add_i32 s36, 0, 0x18000
	v_add_u32_e32 v138, s36, v152
	s_add_i32 s37, 0, 0x1c000
	ds_read_b128 v[146:149], v138
	ds_read_b128 v[158:161], v138 offset:1024
	ds_read_b128 v[166:169], v138 offset:2048
	ds_read_b128 v[170:173], v138 offset:3072
	v_add_u32_e32 v138, s37, v152
	ds_read_b128 v[174:177], v138
	ds_read_b128 v[178:181], v138 offset:1024
	ds_read_b128 v[182:185], v138 offset:2048
	ds_read_b128 v[186:189], v138 offset:3072
	s_add_u32 s66, s66, 0x100000
	s_addc_u32 s67, s67, 0
	s_mov_b32 m0, s74
	v_lshl_add_u64 v[230:231], s[66:67], 0, v[130:131]
	ds_read_b128 v[190:193], v156 offset:32768
	ds_read_b128 v[194:197], v156 offset:33792
	ds_read_b128 v[202:205], v156 offset:34816
	ds_read_b128 v[206:209], v156 offset:35840
	ds_read_b128 v[210:213], v156 offset:36864
	ds_read_b128 v[214:217], v156 offset:37888
	ds_read_b128 v[218:221], v156 offset:38912
	ds_read_b128 v[222:225], v156 offset:39936
	global_load_lds_dwordx4 v[230:231], off
	v_lshl_add_u64 v[230:231], s[66:67], 0, v[134:135]
	s_mov_b32 m0, s75
	s_nop 0
	global_load_lds_dwordx4 v[230:231], off
	s_waitcnt vmcnt(8)
	s_waitcnt lgkmcnt(0)
	s_barrier
	s_setprio 1
	v_mfma_f32_16x16x32_bf16 v[126:129], v[146:149], v[190:193], v[126:129]
	v_mfma_f32_16x16x32_bf16 v[126:129], v[158:161], v[194:197], v[126:129]
	v_mfma_f32_16x16x32_bf16 v[122:125], v[170:173], v[194:197], v[122:125]
	v_mfma_f32_16x16x32_bf16 v[122:125], v[166:169], v[190:193], v[122:125]
	v_mfma_f32_16x16x32_bf16 v[106:109], v[166:169], v[202:205], v[106:109]
	v_mfma_f32_16x16x32_bf16 v[106:109], v[170:173], v[206:209], v[106:109]
	v_mfma_f32_16x16x32_bf16 v[110:113], v[158:161], v[206:209], v[110:113]
	v_mfma_f32_16x16x32_bf16 v[110:113], v[146:149], v[202:205], v[110:113]
	v_mfma_f32_16x16x32_bf16 v[94:97], v[146:149], v[210:213], v[94:97]
	v_mfma_f32_16x16x32_bf16 v[94:97], v[158:161], v[214:217], v[94:97]
	v_mfma_f32_16x16x32_bf16 v[90:93], v[170:173], v[214:217], v[90:93]
	v_mfma_f32_16x16x32_bf16 v[90:93], v[166:169], v[210:213], v[90:93]
	v_mfma_f32_16x16x32_bf16 v[74:77], v[166:169], v[218:221], v[74:77]
	v_mfma_f32_16x16x32_bf16 v[74:77], v[170:173], v[222:225], v[74:77]
	v_mfma_f32_16x16x32_bf16 v[78:81], v[158:161], v[222:225], v[78:81]
	v_mfma_f32_16x16x32_bf16 v[78:81], v[146:149], v[218:221], v[78:81]
	v_mfma_f32_16x16x32_bf16 v[118:121], v[174:177], v[190:193], v[118:121]
	v_mfma_f32_16x16x32_bf16 v[118:121], v[178:181], v[194:197], v[118:121]
	v_mfma_f32_16x16x32_bf16 v[114:117], v[186:189], v[194:197], v[114:117]
	v_mfma_f32_16x16x32_bf16 v[114:117], v[182:185], v[190:193], v[114:117]
	v_mfma_f32_16x16x32_bf16 v[98:101], v[182:185], v[202:205], v[98:101]
	v_mfma_f32_16x16x32_bf16 v[98:101], v[186:189], v[206:209], v[98:101]
	v_mfma_f32_16x16x32_bf16 v[102:105], v[178:181], v[206:209], v[102:105]
	v_mfma_f32_16x16x32_bf16 v[102:105], v[174:177], v[202:205], v[102:105]
	v_mfma_f32_16x16x32_bf16 v[86:89], v[174:177], v[210:213], v[86:89]
	v_mfma_f32_16x16x32_bf16 v[86:89], v[178:181], v[214:217], v[86:89]
	v_mfma_f32_16x16x32_bf16 v[82:85], v[186:189], v[214:217], v[82:85]
	v_mfma_f32_16x16x32_bf16 v[82:85], v[182:185], v[210:213], v[82:85]
	v_mfma_f32_16x16x32_bf16 v[66:69], v[182:185], v[218:221], v[66:69]
	v_mfma_f32_16x16x32_bf16 v[66:69], v[186:189], v[222:225], v[66:69]
	v_mfma_f32_16x16x32_bf16 v[70:73], v[178:181], v[222:225], v[70:73]
	v_mfma_f32_16x16x32_bf16 v[70:73], v[174:177], v[218:221], v[70:73]
	s_setprio 0
	s_barrier
	s_add_i32 s36, s36, s69
	v_lshl_add_u64 v[150:151], v[150:151], 0, s[16:17]
	s_mov_b32 m0, s36
	ds_read_b128 v[190:193], v156 offset:49152
	ds_read_b128 v[194:197], v156 offset:50176
	ds_read_b128 v[202:205], v156 offset:51200
	ds_read_b128 v[206:209], v156 offset:52224
	ds_read_b128 v[210:213], v156 offset:53248
	ds_read_b128 v[214:217], v156 offset:54272
	ds_read_b128 v[218:221], v156 offset:55296
	ds_read_b128 v[222:225], v156 offset:56320
	global_load_lds_dwordx4 v[150:151], off
	s_add_i32 m0, s36, 0x2000
	s_add_u32 s64, s64, 0x100080
	v_lshl_add_u64 v[150:151], v[198:199], 0, s[16:17]
	s_addc_u32 s65, s65, 0
	s_add_i32 s36, s37, s69
	global_load_lds_dwordx4 v[150:151], off
	v_lshl_add_u64 v[150:151], s[64:65], 0, v[132:133]
	s_mov_b32 m0, s36
	s_nop 0
	global_load_lds_dwordx4 v[150:151], off
	v_lshl_add_u64 v[150:151], s[64:65], 0, v[136:137]
	s_add_i32 m0, s36, 0x2000
	s_nop 0
	global_load_lds_dwordx4 v[150:151], off
	v_lshl_add_u64 v[150:151], v[226:227], 0, s[16:17]
	s_mov_b32 m0, s78
	s_nop 0
	global_load_lds_dwordx4 v[150:151], off
	v_lshl_add_u64 v[150:151], v[228:229], 0, s[16:17]
	s_mov_b32 m0, s79
	s_nop 0
	global_load_lds_dwordx4 v[150:151], off
	s_waitcnt vmcnt(8)
	s_waitcnt lgkmcnt(0)
	s_barrier
	s_setprio 1
	v_mfma_f32_16x16x32_bf16 v[62:65], v[146:149], v[190:193], v[62:65]
	v_mfma_f32_16x16x32_bf16 v[62:65], v[158:161], v[194:197], v[62:65]
	v_mfma_f32_16x16x32_bf16 v[58:61], v[170:173], v[194:197], v[58:61]
	v_mfma_f32_16x16x32_bf16 v[58:61], v[166:169], v[190:193], v[58:61]
	v_mfma_f32_16x16x32_bf16 v[42:45], v[166:169], v[202:205], v[42:45]
	v_mfma_f32_16x16x32_bf16 v[42:45], v[170:173], v[206:209], v[42:45]
	v_mfma_f32_16x16x32_bf16 v[46:49], v[158:161], v[206:209], v[46:49]
	v_mfma_f32_16x16x32_bf16 v[46:49], v[146:149], v[202:205], v[46:49]
	v_mfma_f32_16x16x32_bf16 v[30:33], v[146:149], v[210:213], v[30:33]
	v_mfma_f32_16x16x32_bf16 v[30:33], v[158:161], v[214:217], v[30:33]
	v_mfma_f32_16x16x32_bf16 v[26:29], v[170:173], v[214:217], v[26:29]
	v_mfma_f32_16x16x32_bf16 v[26:29], v[166:169], v[210:213], v[26:29]
	v_mfma_f32_16x16x32_bf16 v[10:13], v[166:169], v[218:221], v[10:13]
	v_mfma_f32_16x16x32_bf16 v[10:13], v[170:173], v[222:225], v[10:13]
	v_mfma_f32_16x16x32_bf16 v[14:17], v[158:161], v[222:225], v[14:17]
	v_mfma_f32_16x16x32_bf16 v[14:17], v[146:149], v[218:221], v[14:17]
	v_mfma_f32_16x16x32_bf16 v[54:57], v[174:177], v[190:193], v[54:57]
	v_mfma_f32_16x16x32_bf16 v[54:57], v[178:181], v[194:197], v[54:57]
	v_mfma_f32_16x16x32_bf16 v[50:53], v[186:189], v[194:197], v[50:53]
	v_mfma_f32_16x16x32_bf16 v[50:53], v[182:185], v[190:193], v[50:53]
	v_mfma_f32_16x16x32_bf16 v[34:37], v[182:185], v[202:205], v[34:37]
	v_mfma_f32_16x16x32_bf16 v[34:37], v[186:189], v[206:209], v[34:37]
	v_mfma_f32_16x16x32_bf16 v[38:41], v[178:181], v[206:209], v[38:41]
	v_mfma_f32_16x16x32_bf16 v[38:41], v[174:177], v[202:205], v[38:41]
	v_mfma_f32_16x16x32_bf16 v[22:25], v[174:177], v[210:213], v[22:25]
	v_mfma_f32_16x16x32_bf16 v[22:25], v[178:181], v[214:217], v[22:25]
	v_mfma_f32_16x16x32_bf16 v[18:21], v[186:189], v[214:217], v[18:21]
	v_mfma_f32_16x16x32_bf16 v[18:21], v[182:185], v[210:213], v[18:21]
	v_mfma_f32_16x16x32_bf16 v[2:5], v[182:185], v[218:221], v[2:5]
	v_mfma_f32_16x16x32_bf16 v[2:5], v[186:189], v[222:225], v[2:5]
	v_mfma_f32_16x16x32_bf16 v[6:9], v[178:181], v[222:225], v[6:9]
	v_mfma_f32_16x16x32_bf16 v[6:9], v[174:177], v[218:221], v[6:9]
	s_setprio 0
	s_barrier
	s_add_u32 s62, s62, 0x100
	s_addc_u32 s63, s63, 0
	s_add_u32 s61, s61, 0x100
	s_addc_u32 s92, s92, 0
	s_cmp_ge_i32 s93, s11
	s_mov_b32 s44, s93
	s_cbranch_scc0 .LBB0_1397
	s_and_b64 vcc, exec, s[18:19]
	s_cbranch_vccz .LBB0_1400

.LBB0_1631:
	ds_read_b128 v[166:169], v158
	ds_read_b128 v[170:173], v158 offset:1024
	ds_read_b128 v[174:177], v158 offset:2048
	ds_read_b128 v[178:181], v158 offset:3072
	ds_read_b128 v[182:185], v159
	ds_read_b128 v[186:189], v159 offset:1024
	ds_read_b128 v[190:193], v159 offset:2048
	ds_read_b128 v[194:197], v159 offset:3072
	s_add_u32 s36, s54, 0xfff00080
	s_addc_u32 s37, s55, -1
	s_cmp_eq_u32 s78, 60
	s_cselect_b32 s59, s21, s37
	s_cselect_b32 s58, s74, s36
	s_cselect_b32 s57, s19, s77
	s_cselect_b32 s56, s75, s76
	v_lshl_add_u64 v[198:199], s[54:55], 0, v[140:141]
	s_add_i32 m0, s53, 0xc000
	ds_read_b128 v[202:205], v160
	ds_read_b128 v[206:209], v160 offset:1024
	ds_read_b128 v[210:213], v160 offset:2048
	ds_read_b128 v[214:217], v160 offset:3072
	ds_read_b128 v[218:221], v160 offset:4096
	ds_read_b128 v[222:225], v160 offset:5120
	ds_read_b128 v[226:229], v160 offset:6144
	ds_read_b128 v[230:233], v160 offset:7168
	global_load_lds_dwordx4 v[198:199], off
	v_lshl_add_u64 v[198:199], s[54:55], 0, v[142:143]
	s_add_i32 m0, s53, 0xe000
	s_nop 0
	global_load_lds_dwordx4 v[198:199], off
	s_waitcnt vmcnt(8)
	s_waitcnt lgkmcnt(0)
	s_barrier
	s_setprio 1
	v_mfma_f32_16x16x32_bf16 v[126:129], v[166:169], v[202:205], v[126:129]
	v_mfma_f32_16x16x32_bf16 v[126:129], v[170:173], v[206:209], v[126:129]
	v_mfma_f32_16x16x32_bf16 v[122:125], v[178:181], v[206:209], v[122:125]
	v_mfma_f32_16x16x32_bf16 v[122:125], v[174:177], v[202:205], v[122:125]
	v_mfma_f32_16x16x32_bf16 v[110:113], v[174:177], v[210:213], v[110:113]
	v_mfma_f32_16x16x32_bf16 v[110:113], v[178:181], v[214:217], v[110:113]
	v_mfma_f32_16x16x32_bf16 v[118:121], v[170:173], v[214:217], v[118:121]
	v_mfma_f32_16x16x32_bf16 v[118:121], v[166:169], v[210:213], v[118:121]
	v_mfma_f32_16x16x32_bf16 v[102:105], v[166:169], v[218:221], v[102:105]
	v_mfma_f32_16x16x32_bf16 v[102:105], v[170:173], v[222:225], v[102:105]
	v_mfma_f32_16x16x32_bf16 v[94:97], v[178:181], v[222:225], v[94:97]
	v_mfma_f32_16x16x32_bf16 v[94:97], v[174:177], v[218:221], v[94:97]
	v_mfma_f32_16x16x32_bf16 v[78:81], v[174:177], v[226:229], v[78:81]
	v_mfma_f32_16x16x32_bf16 v[78:81], v[178:181], v[230:233], v[78:81]
	v_mfma_f32_16x16x32_bf16 v[86:89], v[170:173], v[230:233], v[86:89]
	v_mfma_f32_16x16x32_bf16 v[86:89], v[166:169], v[226:229], v[86:89]
	v_mfma_f32_16x16x32_bf16 v[114:117], v[182:185], v[202:205], v[114:117]
	v_mfma_f32_16x16x32_bf16 v[114:117], v[186:189], v[206:209], v[114:117]
	v_mfma_f32_16x16x32_bf16 v[106:109], v[194:197], v[206:209], v[106:109]
	v_mfma_f32_16x16x32_bf16 v[106:109], v[190:193], v[202:205], v[106:109]
	v_mfma_f32_16x16x32_bf16 v[90:93], v[190:193], v[210:213], v[90:93]
	v_mfma_f32_16x16x32_bf16 v[90:93], v[194:197], v[214:217], v[90:93]
	v_mfma_f32_16x16x32_bf16 v[98:101], v[186:189], v[214:217], v[98:101]
	v_mfma_f32_16x16x32_bf16 v[98:101], v[182:185], v[210:213], v[98:101]
	v_mfma_f32_16x16x32_bf16 v[82:85], v[182:185], v[218:221], v[82:85]
	v_mfma_f32_16x16x32_bf16 v[82:85], v[186:189], v[222:225], v[82:85]
	v_mfma_f32_16x16x32_bf16 v[74:77], v[194:197], v[222:225], v[74:77]
	v_mfma_f32_16x16x32_bf16 v[74:77], v[190:193], v[218:221], v[74:77]
	v_mfma_f32_16x16x32_bf16 v[66:69], v[190:193], v[226:229], v[66:69]
	v_mfma_f32_16x16x32_bf16 v[66:69], v[194:197], v[230:233], v[66:69]
	v_mfma_f32_16x16x32_bf16 v[70:73], v[186:189], v[230:233], v[70:73]
	v_mfma_f32_16x16x32_bf16 v[70:73], v[182:185], v[226:229], v[70:73]
	s_setprio 0
	s_barrier
	s_add_i32 s36, s68, s38
	v_lshl_add_u64 v[198:199], s[56:57], 0, v[136:137]
	s_mov_b32 m0, s36
	ds_read_b128 v[202:205], v160 offset:16384
	ds_read_b128 v[206:209], v160 offset:17408
	ds_read_b128 v[210:213], v160 offset:18432
	ds_read_b128 v[214:217], v160 offset:19456
	ds_read_b128 v[218:221], v160 offset:20480
	ds_read_b128 v[222:225], v160 offset:21504
	ds_read_b128 v[226:229], v160 offset:22528
	ds_read_b128 v[230:233], v160 offset:23552
	global_load_lds_dwordx4 v[198:199], off
	s_add_i32 m0, s36, 0x2000
	s_add_u32 s80, s56, 0x100000
	v_lshl_add_u64 v[234:235], s[56:57], 0, v[132:133]
	s_addc_u32 s81, s57, 0
	s_add_i32 s36, s69, s38
	global_load_lds_dwordx4 v[234:235], off
	v_lshl_add_u64 v[236:237], s[80:81], 0, v[136:137]
	s_mov_b32 m0, s36
	v_lshl_add_u64 v[238:239], s[58:59], 0, v[134:135]
	global_load_lds_dwordx4 v[236:237], off
	v_lshl_add_u64 v[236:237], s[80:81], 0, v[132:133]
	s_add_i32 m0, s36, 0x2000
	s_nop 0
	global_load_lds_dwordx4 v[236:237], off
	v_lshl_add_u64 v[236:237], s[58:59], 0, v[138:139]
	s_mov_b32 m0, s53
	s_nop 0
	global_load_lds_dwordx4 v[236:237], off
	s_mov_b32 m0, s61
	s_nop 0
	global_load_lds_dwordx4 v[238:239], off
	s_waitcnt vmcnt(8)
	s_waitcnt lgkmcnt(0)
	s_barrier
	s_setprio 1
	v_mfma_f32_16x16x32_bf16 v[62:65], v[166:169], v[202:205], v[62:65]
	v_mfma_f32_16x16x32_bf16 v[62:65], v[170:173], v[206:209], v[62:65]
	v_mfma_f32_16x16x32_bf16 v[58:61], v[178:181], v[206:209], v[58:61]
	v_mfma_f32_16x16x32_bf16 v[58:61], v[174:177], v[202:205], v[58:61]
	v_mfma_f32_16x16x32_bf16 v[46:49], v[174:177], v[210:213], v[46:49]
	v_mfma_f32_16x16x32_bf16 v[46:49], v[178:181], v[214:217], v[46:49]
	v_mfma_f32_16x16x32_bf16 v[54:57], v[170:173], v[214:217], v[54:57]
	v_mfma_f32_16x16x32_bf16 v[54:57], v[166:169], v[210:213], v[54:57]
	v_mfma_f32_16x16x32_bf16 v[38:41], v[166:169], v[218:221], v[38:41]
	v_mfma_f32_16x16x32_bf16 v[38:41], v[170:173], v[222:225], v[38:41]
	v_mfma_f32_16x16x32_bf16 v[30:33], v[178:181], v[222:225], v[30:33]
	v_mfma_f32_16x16x32_bf16 v[30:33], v[174:177], v[218:221], v[30:33]
	v_mfma_f32_16x16x32_bf16 v[14:17], v[174:177], v[226:229], v[14:17]
	v_mfma_f32_16x16x32_bf16 v[14:17], v[178:181], v[230:233], v[14:17]
	v_mfma_f32_16x16x32_bf16 v[22:25], v[170:173], v[230:233], v[22:25]
	v_mfma_f32_16x16x32_bf16 v[22:25], v[166:169], v[226:229], v[22:25]
	v_mfma_f32_16x16x32_bf16 v[50:53], v[182:185], v[202:205], v[50:53]
	v_mfma_f32_16x16x32_bf16 v[50:53], v[186:189], v[206:209], v[50:53]
	v_mfma_f32_16x16x32_bf16 v[42:45], v[194:197], v[206:209], v[42:45]
	v_mfma_f32_16x16x32_bf16 v[42:45], v[190:193], v[202:205], v[42:45]
	v_mfma_f32_16x16x32_bf16 v[26:29], v[190:193], v[210:213], v[26:29]
	v_mfma_f32_16x16x32_bf16 v[26:29], v[194:197], v[214:217], v[26:29]
	v_mfma_f32_16x16x32_bf16 v[34:37], v[186:189], v[214:217], v[34:37]
	v_mfma_f32_16x16x32_bf16 v[34:37], v[182:185], v[210:213], v[34:37]
	v_mfma_f32_16x16x32_bf16 v[18:21], v[182:185], v[218:221], v[18:21]
	v_mfma_f32_16x16x32_bf16 v[18:21], v[186:189], v[222:225], v[18:21]
	v_mfma_f32_16x16x32_bf16 v[10:13], v[194:197], v[222:225], v[10:13]
	v_mfma_f32_16x16x32_bf16 v[10:13], v[190:193], v[218:221], v[10:13]
	v_mfma_f32_16x16x32_bf16 v[2:5], v[190:193], v[226:229], v[2:5]
	v_mfma_f32_16x16x32_bf16 v[2:5], v[194:197], v[230:233], v[2:5]
	v_mfma_f32_16x16x32_bf16 v[6:9], v[186:189], v[230:233], v[6:9]
	v_mfma_f32_16x16x32_bf16 v[6:9], v[182:185], v[226:229], v[6:9]
	s_setprio 0
	s_barrier
	s_add_i32 s36, 0, 0x18000
	v_add_u32_e32 v161, s36, v156
	s_add_i32 s37, 0, 0x1c000
	ds_read_b128 v[166:169], v161
	ds_read_b128 v[170:173], v161 offset:1024
	ds_read_b128 v[174:177], v161 offset:2048
	ds_read_b128 v[178:181], v161 offset:3072
	v_add_u32_e32 v161, s37, v156
	ds_read_b128 v[182:185], v161
	ds_read_b128 v[186:189], v161 offset:1024
	ds_read_b128 v[190:193], v161 offset:2048
	ds_read_b128 v[194:197], v161 offset:3072
	s_add_u32 s58, s58, 0x100000
	s_addc_u32 s59, s59, 0
	s_mov_b32 m0, s62
	v_lshl_add_u64 v[240:241], s[58:59], 0, v[138:139]
	ds_read_b128 v[202:205], v160 offset:32768
	ds_read_b128 v[206:209], v160 offset:33792
	ds_read_b128 v[210:213], v160 offset:34816
	ds_read_b128 v[214:217], v160 offset:35840
	ds_read_b128 v[218:221], v160 offset:36864
	ds_read_b128 v[222:225], v160 offset:37888
	ds_read_b128 v[226:229], v160 offset:38912
	ds_read_b128 v[230:233], v160 offset:39936
	global_load_lds_dwordx4 v[240:241], off
	v_lshl_add_u64 v[240:241], s[58:59], 0, v[134:135]
	s_mov_b32 m0, s63
	s_nop 0
	global_load_lds_dwordx4 v[240:241], off
	s_waitcnt vmcnt(8)
	s_waitcnt lgkmcnt(0)
	s_barrier
	s_setprio 1
	v_mfma_f32_16x16x32_bf16 v[126:129], v[166:169], v[202:205], v[126:129]
	v_mfma_f32_16x16x32_bf16 v[126:129], v[170:173], v[206:209], v[126:129]
	v_mfma_f32_16x16x32_bf16 v[122:125], v[178:181], v[206:209], v[122:125]
	v_mfma_f32_16x16x32_bf16 v[122:125], v[174:177], v[202:205], v[122:125]
	v_mfma_f32_16x16x32_bf16 v[110:113], v[174:177], v[210:213], v[110:113]
	v_mfma_f32_16x16x32_bf16 v[110:113], v[178:181], v[214:217], v[110:113]
	v_mfma_f32_16x16x32_bf16 v[118:121], v[170:173], v[214:217], v[118:121]
	v_mfma_f32_16x16x32_bf16 v[118:121], v[166:169], v[210:213], v[118:121]
	v_mfma_f32_16x16x32_bf16 v[102:105], v[166:169], v[218:221], v[102:105]
	v_mfma_f32_16x16x32_bf16 v[102:105], v[170:173], v[222:225], v[102:105]
	v_mfma_f32_16x16x32_bf16 v[94:97], v[178:181], v[222:225], v[94:97]
	v_mfma_f32_16x16x32_bf16 v[94:97], v[174:177], v[218:221], v[94:97]
	v_mfma_f32_16x16x32_bf16 v[78:81], v[174:177], v[226:229], v[78:81]
	v_mfma_f32_16x16x32_bf16 v[78:81], v[178:181], v[230:233], v[78:81]
	v_mfma_f32_16x16x32_bf16 v[86:89], v[170:173], v[230:233], v[86:89]
	v_mfma_f32_16x16x32_bf16 v[86:89], v[166:169], v[226:229], v[86:89]
	v_mfma_f32_16x16x32_bf16 v[114:117], v[182:185], v[202:205], v[114:117]
	v_mfma_f32_16x16x32_bf16 v[114:117], v[186:189], v[206:209], v[114:117]
	v_mfma_f32_16x16x32_bf16 v[106:109], v[194:197], v[206:209], v[106:109]
	v_mfma_f32_16x16x32_bf16 v[106:109], v[190:193], v[202:205], v[106:109]
	v_mfma_f32_16x16x32_bf16 v[90:93], v[190:193], v[210:213], v[90:93]
	v_mfma_f32_16x16x32_bf16 v[90:93], v[194:197], v[214:217], v[90:93]
	v_mfma_f32_16x16x32_bf16 v[98:101], v[186:189], v[214:217], v[98:101]
	v_mfma_f32_16x16x32_bf16 v[98:101], v[182:185], v[210:213], v[98:101]
	v_mfma_f32_16x16x32_bf16 v[82:85], v[182:185], v[218:221], v[82:85]
	v_mfma_f32_16x16x32_bf16 v[82:85], v[186:189], v[222:225], v[82:85]
	v_mfma_f32_16x16x32_bf16 v[74:77], v[194:197], v[222:225], v[74:77]
	v_mfma_f32_16x16x32_bf16 v[74:77], v[190:193], v[218:221], v[74:77]
	v_mfma_f32_16x16x32_bf16 v[66:69], v[190:193], v[226:229], v[66:69]
	v_mfma_f32_16x16x32_bf16 v[66:69], v[194:197], v[230:233], v[66:69]
	v_mfma_f32_16x16x32_bf16 v[70:73], v[186:189], v[230:233], v[70:73]
	v_mfma_f32_16x16x32_bf16 v[70:73], v[182:185], v[226:229], v[70:73]
	s_setprio 0
	s_barrier
	s_add_i32 s36, s36, s38
	v_lshl_add_u64 v[198:199], v[198:199], 0, s[14:15]
	s_mov_b32 m0, s36
	ds_read_b128 v[202:205], v160 offset:49152
	ds_read_b128 v[206:209], v160 offset:50176
	ds_read_b128 v[210:213], v160 offset:51200
	ds_read_b128 v[214:217], v160 offset:52224
	ds_read_b128 v[218:221], v160 offset:53248
	ds_read_b128 v[222:225], v160 offset:54272
	ds_read_b128 v[226:229], v160 offset:55296
	ds_read_b128 v[230:233], v160 offset:56320
	global_load_lds_dwordx4 v[198:199], off
	s_add_i32 m0, s36, 0x2000
	s_add_u32 s56, s56, 0x100080
	v_lshl_add_u64 v[198:199], v[234:235], 0, s[14:15]
	s_addc_u32 s57, s57, 0
	s_add_i32 s36, s37, s38
	global_load_lds_dwordx4 v[198:199], off
	v_lshl_add_u64 v[198:199], s[56:57], 0, v[136:137]
	s_mov_b32 m0, s36
	s_nop 0
	global_load_lds_dwordx4 v[198:199], off
	v_lshl_add_u64 v[198:199], s[56:57], 0, v[132:133]
	s_add_i32 m0, s36, 0x2000
	s_nop 0
	global_load_lds_dwordx4 v[198:199], off
	v_lshl_add_u64 v[198:199], v[236:237], 0, s[14:15]
	s_mov_b32 m0, s65
	s_nop 0
	global_load_lds_dwordx4 v[198:199], off
	v_lshl_add_u64 v[198:199], v[238:239], 0, s[14:15]
	s_mov_b32 m0, s66
	s_nop 0
	global_load_lds_dwordx4 v[198:199], off
	s_waitcnt vmcnt(8)
	s_waitcnt lgkmcnt(0)
	s_barrier
	s_setprio 1
	v_mfma_f32_16x16x32_bf16 v[62:65], v[166:169], v[202:205], v[62:65]
	v_mfma_f32_16x16x32_bf16 v[62:65], v[170:173], v[206:209], v[62:65]
	v_mfma_f32_16x16x32_bf16 v[58:61], v[178:181], v[206:209], v[58:61]
	v_mfma_f32_16x16x32_bf16 v[58:61], v[174:177], v[202:205], v[58:61]
	v_mfma_f32_16x16x32_bf16 v[46:49], v[174:177], v[210:213], v[46:49]
	v_mfma_f32_16x16x32_bf16 v[46:49], v[178:181], v[214:217], v[46:49]
	v_mfma_f32_16x16x32_bf16 v[54:57], v[170:173], v[214:217], v[54:57]
	v_mfma_f32_16x16x32_bf16 v[54:57], v[166:169], v[210:213], v[54:57]
	v_mfma_f32_16x16x32_bf16 v[38:41], v[166:169], v[218:221], v[38:41]
	v_mfma_f32_16x16x32_bf16 v[38:41], v[170:173], v[222:225], v[38:41]
	v_mfma_f32_16x16x32_bf16 v[30:33], v[178:181], v[222:225], v[30:33]
	v_mfma_f32_16x16x32_bf16 v[30:33], v[174:177], v[218:221], v[30:33]
	v_mfma_f32_16x16x32_bf16 v[14:17], v[174:177], v[226:229], v[14:17]
	v_mfma_f32_16x16x32_bf16 v[14:17], v[178:181], v[230:233], v[14:17]
	v_mfma_f32_16x16x32_bf16 v[22:25], v[170:173], v[230:233], v[22:25]
	v_mfma_f32_16x16x32_bf16 v[22:25], v[166:169], v[226:229], v[22:25]
	v_mfma_f32_16x16x32_bf16 v[50:53], v[182:185], v[202:205], v[50:53]
	v_mfma_f32_16x16x32_bf16 v[50:53], v[186:189], v[206:209], v[50:53]
	v_mfma_f32_16x16x32_bf16 v[42:45], v[194:197], v[206:209], v[42:45]
	v_mfma_f32_16x16x32_bf16 v[42:45], v[190:193], v[202:205], v[42:45]
	v_mfma_f32_16x16x32_bf16 v[26:29], v[190:193], v[210:213], v[26:29]
	v_mfma_f32_16x16x32_bf16 v[26:29], v[194:197], v[214:217], v[26:29]
	v_mfma_f32_16x16x32_bf16 v[34:37], v[186:189], v[214:217], v[34:37]
	v_mfma_f32_16x16x32_bf16 v[34:37], v[182:185], v[210:213], v[34:37]
	v_mfma_f32_16x16x32_bf16 v[18:21], v[182:185], v[218:221], v[18:21]
	v_mfma_f32_16x16x32_bf16 v[18:21], v[186:189], v[222:225], v[18:21]
	v_mfma_f32_16x16x32_bf16 v[10:13], v[194:197], v[222:225], v[10:13]
	v_mfma_f32_16x16x32_bf16 v[10:13], v[190:193], v[218:221], v[10:13]
	v_mfma_f32_16x16x32_bf16 v[2:5], v[190:193], v[226:229], v[2:5]
	v_mfma_f32_16x16x32_bf16 v[2:5], v[194:197], v[230:233], v[2:5]
	v_mfma_f32_16x16x32_bf16 v[6:9], v[186:189], v[230:233], v[6:9]
	v_mfma_f32_16x16x32_bf16 v[6:9], v[182:185], v[226:229], v[6:9]
	s_setprio 0
	s_barrier
	s_add_i32 s78, s78, 2
	s_add_u32 s54, s54, 0x100
	s_addc_u32 s55, s55, 0
	s_add_u32 s76, s76, 0x100
	s_addc_u32 s77, s77, 0
	s_cmp_gt_u32 s78, 61
	s_cbranch_scc0 .LBB0_1631
	s_and_b64 vcc, exec, s[16:17]
	s_cbranch_vccz .LBB0_1634
	s_barrier

.LBB0_1649:
	s_add_u32 s36, s56, s44
	s_addc_u32 s37, s57, 0
	s_add_u32 s64, s36, 0x100
	s_addc_u32 s65, s37, 0
	s_and_b64 s[62:63], s[60:61], exec
	s_cselect_b32 s65, s21, s65
	s_cselect_b32 s64, s87, s64
	s_add_u32 s44, s54, s44
	s_addc_u32 s62, s55, 0
	s_add_u32 s44, s44, 0x100
	s_addc_u32 s62, s62, 0
	s_and_b64 s[60:61], s[60:61], exec
	s_cselect_b32 s67, s19, s62
	s_cselect_b32 s66, s89, s44
	s_add_u32 s70, s36, 0x10080
	s_addc_u32 s71, s37, 0
	s_add_i32 vcc_lo, s84, s39
	ds_read_b128 v[158:161], v147
	ds_read_b128 v[166:169], v147 offset:1024
	ds_read_b128 v[170:173], v147 offset:2048
	ds_read_b128 v[174:177], v147 offset:3072
	ds_read_b128 v[178:181], v155
	ds_read_b128 v[182:185], v155 offset:1024
	ds_read_b128 v[186:189], v155 offset:2048
	ds_read_b128 v[190:193], v155 offset:3072
	s_add_i32 m0, s53, 0xc000
	s_add_i32 vcc_hi, s53, 0xe000
	s_add_i32 s95, vcc_lo, 0x2000
	s_add_u32 s68, s66, 0x10000
	s_addc_u32 s69, s67, 0
	s_add_i32 s97, s85, s39
	s_add_i32 s96, s97, 0x2000
	s_add_i32 s94, 0, 0x18000
	s_add_i32 s93, 0, 0x1c000
	s_add_u32 s62, s64, 0x10000
	s_addc_u32 s63, s65, 0
	s_add_i32 s92, s94, s39
	s_add_i32 s90, s92, 0x2000
	s_add_u32 s60, s66, 0x10080
	s_addc_u32 s61, s67, 0
	s_add_i32 s91, s93, s39
	s_add_i32 s44, s91, 0x2000
	v_lshl_add_u64 v[198:199], s[70:71], 0, v[138:139]
	ds_read_b128 v[194:197], v156
	ds_read_b128 v[202:205], v156 offset:1024
	ds_read_b128 v[206:209], v156 offset:2048
	ds_read_b128 v[210:213], v156 offset:3072
	ds_read_b128 v[214:217], v156 offset:4096
	ds_read_b128 v[218:221], v156 offset:5120
	ds_read_b128 v[222:225], v156 offset:6144
	ds_read_b128 v[226:229], v156 offset:7168
	global_load_lds_dwordx4 v[198:199], off
	v_lshl_add_u64 v[198:199], s[70:71], 0, v[134:135]
	s_mov_b32 m0, vcc_hi
	s_nop 0
	global_load_lds_dwordx4 v[198:199], off
	s_waitcnt vmcnt(8)
	s_waitcnt lgkmcnt(0)
	s_barrier
	s_setprio 1
	v_mfma_f32_16x16x32_bf16 v[126:129], v[158:161], v[194:197], v[126:129]
	v_mfma_f32_16x16x32_bf16 v[126:129], v[166:169], v[202:205], v[126:129]
	v_mfma_f32_16x16x32_bf16 v[122:125], v[174:177], v[202:205], v[122:125]
	v_mfma_f32_16x16x32_bf16 v[122:125], v[170:173], v[194:197], v[122:125]
	v_mfma_f32_16x16x32_bf16 v[110:113], v[170:173], v[206:209], v[110:113]
	v_mfma_f32_16x16x32_bf16 v[110:113], v[174:177], v[210:213], v[110:113]
	v_mfma_f32_16x16x32_bf16 v[118:121], v[166:169], v[210:213], v[118:121]
	v_mfma_f32_16x16x32_bf16 v[118:121], v[158:161], v[206:209], v[118:121]
	v_mfma_f32_16x16x32_bf16 v[102:105], v[158:161], v[214:217], v[102:105]
	v_mfma_f32_16x16x32_bf16 v[102:105], v[166:169], v[218:221], v[102:105]
	v_mfma_f32_16x16x32_bf16 v[94:97], v[174:177], v[218:221], v[94:97]
	v_mfma_f32_16x16x32_bf16 v[94:97], v[170:173], v[214:217], v[94:97]
	v_mfma_f32_16x16x32_bf16 v[78:81], v[170:173], v[222:225], v[78:81]
	v_mfma_f32_16x16x32_bf16 v[78:81], v[174:177], v[226:229], v[78:81]
	v_mfma_f32_16x16x32_bf16 v[86:89], v[166:169], v[226:229], v[86:89]
	v_mfma_f32_16x16x32_bf16 v[86:89], v[158:161], v[222:225], v[86:89]
	v_mfma_f32_16x16x32_bf16 v[114:117], v[178:181], v[194:197], v[114:117]
	v_mfma_f32_16x16x32_bf16 v[114:117], v[182:185], v[202:205], v[114:117]
	v_mfma_f32_16x16x32_bf16 v[106:109], v[190:193], v[202:205], v[106:109]
	v_mfma_f32_16x16x32_bf16 v[106:109], v[186:189], v[194:197], v[106:109]
	v_mfma_f32_16x16x32_bf16 v[90:93], v[186:189], v[206:209], v[90:93]
	v_mfma_f32_16x16x32_bf16 v[90:93], v[190:193], v[210:213], v[90:93]
	v_mfma_f32_16x16x32_bf16 v[98:101], v[182:185], v[210:213], v[98:101]
	v_mfma_f32_16x16x32_bf16 v[98:101], v[178:181], v[206:209], v[98:101]
	v_mfma_f32_16x16x32_bf16 v[82:85], v[178:181], v[214:217], v[82:85]
	v_mfma_f32_16x16x32_bf16 v[82:85], v[182:185], v[218:221], v[82:85]
	v_mfma_f32_16x16x32_bf16 v[74:77], v[190:193], v[218:221], v[74:77]
	v_mfma_f32_16x16x32_bf16 v[74:77], v[186:189], v[214:217], v[74:77]
	v_mfma_f32_16x16x32_bf16 v[66:69], v[186:189], v[222:225], v[66:69]
	v_mfma_f32_16x16x32_bf16 v[66:69], v[190:193], v[226:229], v[66:69]
	v_mfma_f32_16x16x32_bf16 v[70:73], v[182:185], v[226:229], v[70:73]
	v_mfma_f32_16x16x32_bf16 v[70:73], v[178:181], v[222:225], v[70:73]
	s_setprio 0
	s_barrier
	s_mov_b32 m0, vcc_lo
	v_lshl_add_u64 v[198:199], s[66:67], 0, v[136:137]
	ds_read_b128 v[194:197], v156 offset:16384
	ds_read_b128 v[202:205], v156 offset:17408
	ds_read_b128 v[206:209], v156 offset:18432
	ds_read_b128 v[210:213], v156 offset:19456
	ds_read_b128 v[214:217], v156 offset:20480
	ds_read_b128 v[218:221], v156 offset:21504
	ds_read_b128 v[222:225], v156 offset:22528
	ds_read_b128 v[226:229], v156 offset:23552
	global_load_lds_dwordx4 v[198:199], off
	v_lshl_add_u64 v[230:231], s[66:67], 0, v[132:133]
	s_mov_b32 m0, s95
	v_lshl_add_u64 v[232:233], s[68:69], 0, v[136:137]
	global_load_lds_dwordx4 v[230:231], off
	s_mov_b32 m0, s97
	v_lshl_add_u64 v[234:235], s[64:65], 0, v[134:135]
	global_load_lds_dwordx4 v[232:233], off
	v_lshl_add_u64 v[232:233], s[68:69], 0, v[132:133]
	s_mov_b32 m0, s96
	s_nop 0
	global_load_lds_dwordx4 v[232:233], off
	v_lshl_add_u64 v[232:233], s[64:65], 0, v[138:139]
	s_mov_b32 m0, s53
	s_nop 0
	global_load_lds_dwordx4 v[232:233], off
	s_mov_b32 m0, s75
	s_nop 0
	global_load_lds_dwordx4 v[234:235], off
	s_waitcnt vmcnt(8)
	s_waitcnt lgkmcnt(0)
	s_barrier
	s_setprio 1
	v_mfma_f32_16x16x32_bf16 v[62:65], v[158:161], v[194:197], v[62:65]
	v_mfma_f32_16x16x32_bf16 v[62:65], v[166:169], v[202:205], v[62:65]
	v_mfma_f32_16x16x32_bf16 v[58:61], v[174:177], v[202:205], v[58:61]
	v_mfma_f32_16x16x32_bf16 v[58:61], v[170:173], v[194:197], v[58:61]
	v_mfma_f32_16x16x32_bf16 v[46:49], v[170:173], v[206:209], v[46:49]
	v_mfma_f32_16x16x32_bf16 v[46:49], v[174:177], v[210:213], v[46:49]
	v_mfma_f32_16x16x32_bf16 v[54:57], v[166:169], v[210:213], v[54:57]
	v_mfma_f32_16x16x32_bf16 v[54:57], v[158:161], v[206:209], v[54:57]
	v_mfma_f32_16x16x32_bf16 v[38:41], v[158:161], v[214:217], v[38:41]
	v_mfma_f32_16x16x32_bf16 v[38:41], v[166:169], v[218:221], v[38:41]
	v_mfma_f32_16x16x32_bf16 v[30:33], v[174:177], v[218:221], v[30:33]
	v_mfma_f32_16x16x32_bf16 v[30:33], v[170:173], v[214:217], v[30:33]
	v_mfma_f32_16x16x32_bf16 v[14:17], v[170:173], v[222:225], v[14:17]
	v_mfma_f32_16x16x32_bf16 v[14:17], v[174:177], v[226:229], v[14:17]
	v_mfma_f32_16x16x32_bf16 v[22:25], v[166:169], v[226:229], v[22:25]
	v_mfma_f32_16x16x32_bf16 v[22:25], v[158:161], v[222:225], v[22:25]
	v_mfma_f32_16x16x32_bf16 v[50:53], v[178:181], v[194:197], v[50:53]
	v_mfma_f32_16x16x32_bf16 v[50:53], v[182:185], v[202:205], v[50:53]
	v_mfma_f32_16x16x32_bf16 v[42:45], v[190:193], v[202:205], v[42:45]
	v_mfma_f32_16x16x32_bf16 v[42:45], v[186:189], v[194:197], v[42:45]
	v_mfma_f32_16x16x32_bf16 v[26:29], v[186:189], v[206:209], v[26:29]
	v_mfma_f32_16x16x32_bf16 v[26:29], v[190:193], v[210:213], v[26:29]
	v_mfma_f32_16x16x32_bf16 v[34:37], v[182:185], v[210:213], v[34:37]
	v_mfma_f32_16x16x32_bf16 v[34:37], v[178:181], v[206:209], v[34:37]
	v_mfma_f32_16x16x32_bf16 v[18:21], v[178:181], v[214:217], v[18:21]
	v_mfma_f32_16x16x32_bf16 v[18:21], v[182:185], v[218:221], v[18:21]
	v_mfma_f32_16x16x32_bf16 v[10:13], v[190:193], v[218:221], v[10:13]
	v_mfma_f32_16x16x32_bf16 v[10:13], v[186:189], v[214:217], v[10:13]
	v_mfma_f32_16x16x32_bf16 v[2:5], v[186:189], v[222:225], v[2:5]
	v_mfma_f32_16x16x32_bf16 v[2:5], v[190:193], v[226:229], v[2:5]
	v_mfma_f32_16x16x32_bf16 v[6:9], v[182:185], v[226:229], v[6:9]
	v_mfma_f32_16x16x32_bf16 v[6:9], v[178:181], v[222:225], v[6:9]
	s_setprio 0
	s_barrier
	v_add_u32_e32 v157, s94, v145
	ds_read_b128 v[158:161], v157
	ds_read_b128 v[166:169], v157 offset:1024
	ds_read_b128 v[170:173], v157 offset:2048
	ds_read_b128 v[174:177], v157 offset:3072
	v_add_u32_e32 v157, s93, v145
	ds_read_b128 v[178:181], v157
	ds_read_b128 v[182:185], v157 offset:1024
	ds_read_b128 v[186:189], v157 offset:2048
	ds_read_b128 v[190:193], v157 offset:3072
	s_mov_b32 m0, s76
	v_lshl_add_u64 v[236:237], s[62:63], 0, v[138:139]
	ds_read_b128 v[194:197], v156 offset:32768
	ds_read_b128 v[202:205], v156 offset:33792
	ds_read_b128 v[206:209], v156 offset:34816
	ds_read_b128 v[210:213], v156 offset:35840
	ds_read_b128 v[214:217], v156 offset:36864
	ds_read_b128 v[218:221], v156 offset:37888
	ds_read_b128 v[222:225], v156 offset:38912
	ds_read_b128 v[226:229], v156 offset:39936
	global_load_lds_dwordx4 v[236:237], off
	v_lshl_add_u64 v[236:237], s[62:63], 0, v[134:135]
	s_mov_b32 m0, s77
	s_nop 0
	global_load_lds_dwordx4 v[236:237], off
	s_waitcnt vmcnt(8)
	s_waitcnt lgkmcnt(0)
	s_barrier
	s_setprio 1
	v_mfma_f32_16x16x32_bf16 v[126:129], v[158:161], v[194:197], v[126:129]
	v_mfma_f32_16x16x32_bf16 v[126:129], v[166:169], v[202:205], v[126:129]
	v_mfma_f32_16x16x32_bf16 v[122:125], v[174:177], v[202:205], v[122:125]
	v_mfma_f32_16x16x32_bf16 v[122:125], v[170:173], v[194:197], v[122:125]
	v_mfma_f32_16x16x32_bf16 v[110:113], v[170:173], v[206:209], v[110:113]
	v_mfma_f32_16x16x32_bf16 v[110:113], v[174:177], v[210:213], v[110:113]
	v_mfma_f32_16x16x32_bf16 v[118:121], v[166:169], v[210:213], v[118:121]
	v_mfma_f32_16x16x32_bf16 v[118:121], v[158:161], v[206:209], v[118:121]
	v_mfma_f32_16x16x32_bf16 v[102:105], v[158:161], v[214:217], v[102:105]
	v_mfma_f32_16x16x32_bf16 v[102:105], v[166:169], v[218:221], v[102:105]
	v_mfma_f32_16x16x32_bf16 v[94:97], v[174:177], v[218:221], v[94:97]
	v_mfma_f32_16x16x32_bf16 v[94:97], v[170:173], v[214:217], v[94:97]
	v_mfma_f32_16x16x32_bf16 v[78:81], v[170:173], v[222:225], v[78:81]
	v_mfma_f32_16x16x32_bf16 v[78:81], v[174:177], v[226:229], v[78:81]
	v_mfma_f32_16x16x32_bf16 v[86:89], v[166:169], v[226:229], v[86:89]
	v_mfma_f32_16x16x32_bf16 v[86:89], v[158:161], v[222:225], v[86:89]
	v_mfma_f32_16x16x32_bf16 v[114:117], v[178:181], v[194:197], v[114:117]
	v_mfma_f32_16x16x32_bf16 v[114:117], v[182:185], v[202:205], v[114:117]
	v_mfma_f32_16x16x32_bf16 v[106:109], v[190:193], v[202:205], v[106:109]
	v_mfma_f32_16x16x32_bf16 v[106:109], v[186:189], v[194:197], v[106:109]
	v_mfma_f32_16x16x32_bf16 v[90:93], v[186:189], v[206:209], v[90:93]
	v_mfma_f32_16x16x32_bf16 v[90:93], v[190:193], v[210:213], v[90:93]
	v_mfma_f32_16x16x32_bf16 v[98:101], v[182:185], v[210:213], v[98:101]
	v_mfma_f32_16x16x32_bf16 v[98:101], v[178:181], v[206:209], v[98:101]
	v_mfma_f32_16x16x32_bf16 v[82:85], v[178:181], v[214:217], v[82:85]
	v_mfma_f32_16x16x32_bf16 v[82:85], v[182:185], v[218:221], v[82:85]
	v_mfma_f32_16x16x32_bf16 v[74:77], v[190:193], v[218:221], v[74:77]
	v_mfma_f32_16x16x32_bf16 v[74:77], v[186:189], v[214:217], v[74:77]
	v_mfma_f32_16x16x32_bf16 v[66:69], v[186:189], v[222:225], v[66:69]
	v_mfma_f32_16x16x32_bf16 v[66:69], v[190:193], v[226:229], v[66:69]
	v_mfma_f32_16x16x32_bf16 v[70:73], v[182:185], v[226:229], v[70:73]
	v_mfma_f32_16x16x32_bf16 v[70:73], v[178:181], v[222:225], v[70:73]
	s_setprio 0
	s_barrier
	s_mov_b32 m0, s92
	v_lshl_add_u64 v[198:199], v[198:199], 0, s[14:15]
	ds_read_b128 v[194:197], v156 offset:49152
	ds_read_b128 v[202:205], v156 offset:50176
	ds_read_b128 v[206:209], v156 offset:51200
	ds_read_b128 v[210:213], v156 offset:52224
	ds_read_b128 v[214:217], v156 offset:53248
	ds_read_b128 v[218:221], v156 offset:54272
	ds_read_b128 v[222:225], v156 offset:55296
	ds_read_b128 v[226:229], v156 offset:56320
	global_load_lds_dwordx4 v[198:199], off
	v_lshl_add_u64 v[198:199], v[230:231], 0, s[14:15]
	s_mov_b32 m0, s90
	s_nop 0
	global_load_lds_dwordx4 v[198:199], off
	v_lshl_add_u64 v[198:199], s[60:61], 0, v[136:137]
	s_mov_b32 m0, s91
	s_nop 0
	global_load_lds_dwordx4 v[198:199], off
	v_lshl_add_u64 v[198:199], s[60:61], 0, v[132:133]
	s_mov_b32 m0, s44
	s_nop 0
	global_load_lds_dwordx4 v[198:199], off
	v_lshl_add_u64 v[198:199], v[232:233], 0, s[14:15]
	s_mov_b32 m0, s80
	s_nop 0
	global_load_lds_dwordx4 v[198:199], off
	v_lshl_add_u64 v[198:199], v[234:235], 0, s[14:15]
	s_mov_b32 m0, s81
	s_nop 0
	global_load_lds_dwordx4 v[198:199], off
	s_waitcnt vmcnt(8)
	s_waitcnt lgkmcnt(0)
	s_barrier
	s_setprio 1
	v_mfma_f32_16x16x32_bf16 v[62:65], v[158:161], v[194:197], v[62:65]
	v_mfma_f32_16x16x32_bf16 v[62:65], v[166:169], v[202:205], v[62:65]
	v_mfma_f32_16x16x32_bf16 v[58:61], v[174:177], v[202:205], v[58:61]
	v_mfma_f32_16x16x32_bf16 v[58:61], v[170:173], v[194:197], v[58:61]
	v_mfma_f32_16x16x32_bf16 v[46:49], v[170:173], v[206:209], v[46:49]
	v_mfma_f32_16x16x32_bf16 v[46:49], v[174:177], v[210:213], v[46:49]
	v_mfma_f32_16x16x32_bf16 v[54:57], v[166:169], v[210:213], v[54:57]
	v_mfma_f32_16x16x32_bf16 v[54:57], v[158:161], v[206:209], v[54:57]
	v_mfma_f32_16x16x32_bf16 v[38:41], v[158:161], v[214:217], v[38:41]
	v_mfma_f32_16x16x32_bf16 v[38:41], v[166:169], v[218:221], v[38:41]
	v_mfma_f32_16x16x32_bf16 v[30:33], v[174:177], v[218:221], v[30:33]
	v_mfma_f32_16x16x32_bf16 v[30:33], v[170:173], v[214:217], v[30:33]
	v_mfma_f32_16x16x32_bf16 v[14:17], v[170:173], v[222:225], v[14:17]
	v_mfma_f32_16x16x32_bf16 v[14:17], v[174:177], v[226:229], v[14:17]
	v_mfma_f32_16x16x32_bf16 v[22:25], v[166:169], v[226:229], v[22:25]
	v_mfma_f32_16x16x32_bf16 v[22:25], v[158:161], v[222:225], v[22:25]
	v_mfma_f32_16x16x32_bf16 v[50:53], v[178:181], v[194:197], v[50:53]
	v_mfma_f32_16x16x32_bf16 v[50:53], v[182:185], v[202:205], v[50:53]
	v_mfma_f32_16x16x32_bf16 v[42:45], v[190:193], v[202:205], v[42:45]
	v_mfma_f32_16x16x32_bf16 v[42:45], v[186:189], v[194:197], v[42:45]
	v_mfma_f32_16x16x32_bf16 v[26:29], v[186:189], v[206:209], v[26:29]
	v_mfma_f32_16x16x32_bf16 v[26:29], v[190:193], v[210:213], v[26:29]
	v_mfma_f32_16x16x32_bf16 v[34:37], v[182:185], v[210:213], v[34:37]
	v_mfma_f32_16x16x32_bf16 v[34:37], v[178:181], v[206:209], v[34:37]
	v_mfma_f32_16x16x32_bf16 v[18:21], v[178:181], v[214:217], v[18:21]
	v_mfma_f32_16x16x32_bf16 v[18:21], v[182:185], v[218:221], v[18:21]
	v_mfma_f32_16x16x32_bf16 v[10:13], v[190:193], v[218:221], v[10:13]
	v_mfma_f32_16x16x32_bf16 v[10:13], v[186:189], v[214:217], v[10:13]
	v_mfma_f32_16x16x32_bf16 v[2:5], v[186:189], v[222:225], v[2:5]
	v_mfma_f32_16x16x32_bf16 v[2:5], v[190:193], v[226:229], v[2:5]
	v_mfma_f32_16x16x32_bf16 v[6:9], v[182:185], v[226:229], v[6:9]
	v_mfma_f32_16x16x32_bf16 v[6:9], v[178:181], v[222:225], v[6:9]
	s_setprio 0
	s_barrier
	s_movk_i32 s44, 0x100
	s_andn2_b64 vcc, exec, s[58:59]
	s_mov_b64 s[60:61], -1
	s_mov_b64 s[58:59], 0
	s_cbranch_vccz .LBB0_1649
	s_and_b64 vcc, exec, s[16:17]
	s_cbranch_vccz .LBB0_1652
	s_barrier

.LBB0_1667:
	s_add_u32 s36, s56, s44
	s_addc_u32 s37, s57, 0
	s_add_u32 s64, s36, 0x100
	s_addc_u32 s65, s37, 0
	s_and_b64 s[62:63], s[60:61], exec
	s_cselect_b32 s65, s21, s65
	s_cselect_b32 s64, s86, s64
	s_add_u32 s44, s54, s44
	s_addc_u32 s62, s55, 0
	s_add_u32 s44, s44, 0x100
	s_addc_u32 s62, s62, 0
	s_and_b64 s[60:61], s[60:61], exec
	s_cselect_b32 s67, s19, s62
	s_cselect_b32 s66, s87, s44
	s_add_u32 s70, s36, 0x10080
	s_addc_u32 s71, s37, 0
	s_add_i32 s97, s82, s38
	ds_read_b128 v[150:153], v146
	ds_read_b128 v[154:157], v146 offset:1024
	ds_read_b128 v[158:161], v146 offset:2048
	ds_read_b128 v[166:169], v146 offset:3072
	ds_read_b128 v[170:173], v147
	ds_read_b128 v[174:177], v147 offset:1024
	ds_read_b128 v[178:181], v147 offset:2048
	ds_read_b128 v[182:185], v147 offset:3072
	s_add_i32 m0, s53, 0xc000
	s_add_i32 vcc_lo, s53, 0xe000
	s_add_i32 s94, s97, 0x2000
	s_add_u32 s68, s66, 0x10000
	s_addc_u32 s69, s67, 0
	s_add_i32 s96, s83, s38
	s_add_i32 s95, s96, 0x2000
	s_add_i32 s93, 0, 0x18000
	s_add_i32 s92, 0, 0x1c000
	s_add_u32 s62, s64, 0x10000
	s_addc_u32 s63, s65, 0
	s_add_i32 s91, s93, s38
	s_add_i32 s89, s91, 0x2000
	s_add_u32 s60, s66, 0x10080
	s_addc_u32 s61, s67, 0
	s_add_i32 s90, s92, s38
	s_add_i32 s44, s90, 0x2000
	v_lshl_add_u64 v[198:199], s[70:71], 0, v[138:139]
	ds_read_b128 v[186:189], v148
	ds_read_b128 v[190:193], v148 offset:1024
	ds_read_b128 v[194:197], v148 offset:2048
	ds_read_b128 v[202:205], v148 offset:3072
	ds_read_b128 v[206:209], v148 offset:4096
	ds_read_b128 v[210:213], v148 offset:5120
	ds_read_b128 v[214:217], v148 offset:6144
	ds_read_b128 v[218:221], v148 offset:7168
	global_load_lds_dwordx4 v[198:199], off
	v_lshl_add_u64 v[198:199], s[70:71], 0, v[134:135]
	s_mov_b32 m0, vcc_lo
	s_nop 0
	global_load_lds_dwordx4 v[198:199], off
	s_waitcnt vmcnt(8)
	s_waitcnt lgkmcnt(0)
	s_barrier
	s_setprio 1
	v_mfma_f32_16x16x32_bf16 v[126:129], v[150:153], v[186:189], v[126:129]
	v_mfma_f32_16x16x32_bf16 v[126:129], v[154:157], v[190:193], v[126:129]
	v_mfma_f32_16x16x32_bf16 v[122:125], v[166:169], v[190:193], v[122:125]
	v_mfma_f32_16x16x32_bf16 v[122:125], v[158:161], v[186:189], v[122:125]
	v_mfma_f32_16x16x32_bf16 v[110:113], v[158:161], v[194:197], v[110:113]
	v_mfma_f32_16x16x32_bf16 v[110:113], v[166:169], v[202:205], v[110:113]
	v_mfma_f32_16x16x32_bf16 v[118:121], v[154:157], v[202:205], v[118:121]
	v_mfma_f32_16x16x32_bf16 v[118:121], v[150:153], v[194:197], v[118:121]
	v_mfma_f32_16x16x32_bf16 v[102:105], v[150:153], v[206:209], v[102:105]
	v_mfma_f32_16x16x32_bf16 v[102:105], v[154:157], v[210:213], v[102:105]
	v_mfma_f32_16x16x32_bf16 v[94:97], v[166:169], v[210:213], v[94:97]
	v_mfma_f32_16x16x32_bf16 v[94:97], v[158:161], v[206:209], v[94:97]
	v_mfma_f32_16x16x32_bf16 v[78:81], v[158:161], v[214:217], v[78:81]
	v_mfma_f32_16x16x32_bf16 v[78:81], v[166:169], v[218:221], v[78:81]
	v_mfma_f32_16x16x32_bf16 v[86:89], v[154:157], v[218:221], v[86:89]
	v_mfma_f32_16x16x32_bf16 v[86:89], v[150:153], v[214:217], v[86:89]
	v_mfma_f32_16x16x32_bf16 v[114:117], v[170:173], v[186:189], v[114:117]
	v_mfma_f32_16x16x32_bf16 v[114:117], v[174:177], v[190:193], v[114:117]
	v_mfma_f32_16x16x32_bf16 v[106:109], v[182:185], v[190:193], v[106:109]
	v_mfma_f32_16x16x32_bf16 v[106:109], v[178:181], v[186:189], v[106:109]
	v_mfma_f32_16x16x32_bf16 v[90:93], v[178:181], v[194:197], v[90:93]
	v_mfma_f32_16x16x32_bf16 v[90:93], v[182:185], v[202:205], v[90:93]
	v_mfma_f32_16x16x32_bf16 v[98:101], v[174:177], v[202:205], v[98:101]
	v_mfma_f32_16x16x32_bf16 v[98:101], v[170:173], v[194:197], v[98:101]
	v_mfma_f32_16x16x32_bf16 v[82:85], v[170:173], v[206:209], v[82:85]
	v_mfma_f32_16x16x32_bf16 v[82:85], v[174:177], v[210:213], v[82:85]
	v_mfma_f32_16x16x32_bf16 v[74:77], v[182:185], v[210:213], v[74:77]
	v_mfma_f32_16x16x32_bf16 v[74:77], v[178:181], v[206:209], v[74:77]
	v_mfma_f32_16x16x32_bf16 v[66:69], v[178:181], v[214:217], v[66:69]
	v_mfma_f32_16x16x32_bf16 v[66:69], v[182:185], v[218:221], v[66:69]
	v_mfma_f32_16x16x32_bf16 v[70:73], v[174:177], v[218:221], v[70:73]
	v_mfma_f32_16x16x32_bf16 v[70:73], v[170:173], v[214:217], v[70:73]
	s_setprio 0
	s_barrier
	s_mov_b32 m0, s97
	v_lshl_add_u64 v[198:199], s[66:67], 0, v[136:137]
	ds_read_b128 v[186:189], v148 offset:16384
	ds_read_b128 v[190:193], v148 offset:17408
	ds_read_b128 v[194:197], v148 offset:18432
	ds_read_b128 v[202:205], v148 offset:19456
	ds_read_b128 v[206:209], v148 offset:20480
	ds_read_b128 v[210:213], v148 offset:21504
	ds_read_b128 v[214:217], v148 offset:22528
	ds_read_b128 v[218:221], v148 offset:23552
	global_load_lds_dwordx4 v[198:199], off
	v_lshl_add_u64 v[222:223], s[66:67], 0, v[132:133]
	s_mov_b32 m0, s94
	v_lshl_add_u64 v[224:225], s[68:69], 0, v[136:137]
	global_load_lds_dwordx4 v[222:223], off
	s_mov_b32 m0, s96
	v_lshl_add_u64 v[226:227], s[64:65], 0, v[134:135]
	global_load_lds_dwordx4 v[224:225], off
	v_lshl_add_u64 v[224:225], s[68:69], 0, v[132:133]
	s_mov_b32 m0, s95
	s_nop 0
	global_load_lds_dwordx4 v[224:225], off
	v_lshl_add_u64 v[224:225], s[64:65], 0, v[138:139]
	s_mov_b32 m0, s53
	s_nop 0
	global_load_lds_dwordx4 v[224:225], off
	s_mov_b32 m0, s75
	s_nop 0
	global_load_lds_dwordx4 v[226:227], off
	s_waitcnt vmcnt(8)
	s_waitcnt lgkmcnt(0)
	s_barrier
	s_setprio 1
	v_mfma_f32_16x16x32_bf16 v[62:65], v[150:153], v[186:189], v[62:65]
	v_mfma_f32_16x16x32_bf16 v[62:65], v[154:157], v[190:193], v[62:65]
	v_mfma_f32_16x16x32_bf16 v[58:61], v[166:169], v[190:193], v[58:61]
	v_mfma_f32_16x16x32_bf16 v[58:61], v[158:161], v[186:189], v[58:61]
	v_mfma_f32_16x16x32_bf16 v[46:49], v[158:161], v[194:197], v[46:49]
	v_mfma_f32_16x16x32_bf16 v[46:49], v[166:169], v[202:205], v[46:49]
	v_mfma_f32_16x16x32_bf16 v[54:57], v[154:157], v[202:205], v[54:57]
	v_mfma_f32_16x16x32_bf16 v[54:57], v[150:153], v[194:197], v[54:57]
	v_mfma_f32_16x16x32_bf16 v[38:41], v[150:153], v[206:209], v[38:41]
	v_mfma_f32_16x16x32_bf16 v[38:41], v[154:157], v[210:213], v[38:41]
	v_mfma_f32_16x16x32_bf16 v[30:33], v[166:169], v[210:213], v[30:33]
	v_mfma_f32_16x16x32_bf16 v[30:33], v[158:161], v[206:209], v[30:33]
	v_mfma_f32_16x16x32_bf16 v[14:17], v[158:161], v[214:217], v[14:17]
	v_mfma_f32_16x16x32_bf16 v[14:17], v[166:169], v[218:221], v[14:17]
	v_mfma_f32_16x16x32_bf16 v[22:25], v[154:157], v[218:221], v[22:25]
	v_mfma_f32_16x16x32_bf16 v[22:25], v[150:153], v[214:217], v[22:25]
	v_mfma_f32_16x16x32_bf16 v[50:53], v[170:173], v[186:189], v[50:53]
	v_mfma_f32_16x16x32_bf16 v[50:53], v[174:177], v[190:193], v[50:53]
	v_mfma_f32_16x16x32_bf16 v[42:45], v[182:185], v[190:193], v[42:45]
	v_mfma_f32_16x16x32_bf16 v[42:45], v[178:181], v[186:189], v[42:45]
	v_mfma_f32_16x16x32_bf16 v[26:29], v[178:181], v[194:197], v[26:29]
	v_mfma_f32_16x16x32_bf16 v[26:29], v[182:185], v[202:205], v[26:29]
	v_mfma_f32_16x16x32_bf16 v[34:37], v[174:177], v[202:205], v[34:37]
	v_mfma_f32_16x16x32_bf16 v[34:37], v[170:173], v[194:197], v[34:37]
	v_mfma_f32_16x16x32_bf16 v[18:21], v[170:173], v[206:209], v[18:21]
	v_mfma_f32_16x16x32_bf16 v[18:21], v[174:177], v[210:213], v[18:21]
	v_mfma_f32_16x16x32_bf16 v[10:13], v[182:185], v[210:213], v[10:13]
	v_mfma_f32_16x16x32_bf16 v[10:13], v[178:181], v[206:209], v[10:13]
	v_mfma_f32_16x16x32_bf16 v[2:5], v[178:181], v[214:217], v[2:5]
	v_mfma_f32_16x16x32_bf16 v[2:5], v[182:185], v[218:221], v[2:5]
	v_mfma_f32_16x16x32_bf16 v[6:9], v[174:177], v[218:221], v[6:9]
	v_mfma_f32_16x16x32_bf16 v[6:9], v[170:173], v[214:217], v[6:9]
	s_setprio 0
	s_barrier
	v_add_u32_e32 v149, s93, v145
	ds_read_b128 v[150:153], v149
	ds_read_b128 v[154:157], v149 offset:1024
	ds_read_b128 v[158:161], v149 offset:2048
	ds_read_b128 v[166:169], v149 offset:3072
	v_add_u32_e32 v149, s92, v145
	ds_read_b128 v[170:173], v149
	ds_read_b128 v[174:177], v149 offset:1024
	ds_read_b128 v[178:181], v149 offset:2048
	ds_read_b128 v[182:185], v149 offset:3072
	s_mov_b32 m0, s76
	v_lshl_add_u64 v[228:229], s[62:63], 0, v[138:139]
	ds_read_b128 v[186:189], v148 offset:32768
	ds_read_b128 v[190:193], v148 offset:33792
	ds_read_b128 v[194:197], v148 offset:34816
	ds_read_b128 v[202:205], v148 offset:35840
	ds_read_b128 v[206:209], v148 offset:36864
	ds_read_b128 v[210:213], v148 offset:37888
	ds_read_b128 v[214:217], v148 offset:38912
	ds_read_b128 v[218:221], v148 offset:39936
	global_load_lds_dwordx4 v[228:229], off
	v_lshl_add_u64 v[228:229], s[62:63], 0, v[134:135]
	s_mov_b32 m0, s77
	s_nop 0
	global_load_lds_dwordx4 v[228:229], off
	s_waitcnt vmcnt(8)
	s_waitcnt lgkmcnt(0)
	s_barrier
	s_setprio 1
	v_mfma_f32_16x16x32_bf16 v[126:129], v[150:153], v[186:189], v[126:129]
	v_mfma_f32_16x16x32_bf16 v[126:129], v[154:157], v[190:193], v[126:129]
	v_mfma_f32_16x16x32_bf16 v[122:125], v[166:169], v[190:193], v[122:125]
	v_mfma_f32_16x16x32_bf16 v[122:125], v[158:161], v[186:189], v[122:125]
	v_mfma_f32_16x16x32_bf16 v[110:113], v[158:161], v[194:197], v[110:113]
	v_mfma_f32_16x16x32_bf16 v[110:113], v[166:169], v[202:205], v[110:113]
	v_mfma_f32_16x16x32_bf16 v[118:121], v[154:157], v[202:205], v[118:121]
	v_mfma_f32_16x16x32_bf16 v[118:121], v[150:153], v[194:197], v[118:121]
	v_mfma_f32_16x16x32_bf16 v[102:105], v[150:153], v[206:209], v[102:105]
	v_mfma_f32_16x16x32_bf16 v[102:105], v[154:157], v[210:213], v[102:105]
	v_mfma_f32_16x16x32_bf16 v[94:97], v[166:169], v[210:213], v[94:97]
	v_mfma_f32_16x16x32_bf16 v[94:97], v[158:161], v[206:209], v[94:97]
	v_mfma_f32_16x16x32_bf16 v[78:81], v[158:161], v[214:217], v[78:81]
	v_mfma_f32_16x16x32_bf16 v[78:81], v[166:169], v[218:221], v[78:81]
	v_mfma_f32_16x16x32_bf16 v[86:89], v[154:157], v[218:221], v[86:89]
	v_mfma_f32_16x16x32_bf16 v[86:89], v[150:153], v[214:217], v[86:89]
	v_mfma_f32_16x16x32_bf16 v[114:117], v[170:173], v[186:189], v[114:117]
	v_mfma_f32_16x16x32_bf16 v[114:117], v[174:177], v[190:193], v[114:117]
	v_mfma_f32_16x16x32_bf16 v[106:109], v[182:185], v[190:193], v[106:109]
	v_mfma_f32_16x16x32_bf16 v[106:109], v[178:181], v[186:189], v[106:109]
	v_mfma_f32_16x16x32_bf16 v[90:93], v[178:181], v[194:197], v[90:93]
	v_mfma_f32_16x16x32_bf16 v[90:93], v[182:185], v[202:205], v[90:93]
	v_mfma_f32_16x16x32_bf16 v[98:101], v[174:177], v[202:205], v[98:101]
	v_mfma_f32_16x16x32_bf16 v[98:101], v[170:173], v[194:197], v[98:101]
	v_mfma_f32_16x16x32_bf16 v[82:85], v[170:173], v[206:209], v[82:85]
	v_mfma_f32_16x16x32_bf16 v[82:85], v[174:177], v[210:213], v[82:85]
	v_mfma_f32_16x16x32_bf16 v[74:77], v[182:185], v[210:213], v[74:77]
	v_mfma_f32_16x16x32_bf16 v[74:77], v[178:181], v[206:209], v[74:77]
	v_mfma_f32_16x16x32_bf16 v[66:69], v[178:181], v[214:217], v[66:69]
	v_mfma_f32_16x16x32_bf16 v[66:69], v[182:185], v[218:221], v[66:69]
	v_mfma_f32_16x16x32_bf16 v[70:73], v[174:177], v[218:221], v[70:73]
	v_mfma_f32_16x16x32_bf16 v[70:73], v[170:173], v[214:217], v[70:73]
	s_setprio 0
	s_barrier
	s_mov_b32 m0, s91
	v_lshl_add_u64 v[198:199], v[198:199], 0, s[14:15]
	ds_read_b128 v[186:189], v148 offset:49152
	ds_read_b128 v[190:193], v148 offset:50176
	ds_read_b128 v[194:197], v148 offset:51200
	ds_read_b128 v[202:205], v148 offset:52224
	ds_read_b128 v[206:209], v148 offset:53248
	ds_read_b128 v[210:213], v148 offset:54272
	ds_read_b128 v[214:217], v148 offset:55296
	ds_read_b128 v[218:221], v148 offset:56320
	global_load_lds_dwordx4 v[198:199], off
	v_lshl_add_u64 v[198:199], v[222:223], 0, s[14:15]
	s_mov_b32 m0, s89
	s_nop 0
	global_load_lds_dwordx4 v[198:199], off
	v_lshl_add_u64 v[198:199], s[60:61], 0, v[136:137]
	s_mov_b32 m0, s90
	s_nop 0
	global_load_lds_dwordx4 v[198:199], off
	v_lshl_add_u64 v[198:199], s[60:61], 0, v[132:133]
	s_mov_b32 m0, s44
	s_nop 0
	global_load_lds_dwordx4 v[198:199], off
	v_lshl_add_u64 v[198:199], v[224:225], 0, s[14:15]
	s_mov_b32 m0, s79
	s_nop 0
	global_load_lds_dwordx4 v[198:199], off
	v_lshl_add_u64 v[198:199], v[226:227], 0, s[14:15]
	s_mov_b32 m0, s80
	s_nop 0
	global_load_lds_dwordx4 v[198:199], off
	s_waitcnt vmcnt(8)
	s_waitcnt lgkmcnt(0)
	s_barrier
	s_setprio 1
	v_mfma_f32_16x16x32_bf16 v[62:65], v[150:153], v[186:189], v[62:65]
	v_mfma_f32_16x16x32_bf16 v[62:65], v[154:157], v[190:193], v[62:65]
	v_mfma_f32_16x16x32_bf16 v[58:61], v[166:169], v[190:193], v[58:61]
	v_mfma_f32_16x16x32_bf16 v[58:61], v[158:161], v[186:189], v[58:61]
	v_mfma_f32_16x16x32_bf16 v[46:49], v[158:161], v[194:197], v[46:49]
	v_mfma_f32_16x16x32_bf16 v[46:49], v[166:169], v[202:205], v[46:49]
	v_mfma_f32_16x16x32_bf16 v[54:57], v[154:157], v[202:205], v[54:57]
	v_mfma_f32_16x16x32_bf16 v[54:57], v[150:153], v[194:197], v[54:57]
	v_mfma_f32_16x16x32_bf16 v[38:41], v[150:153], v[206:209], v[38:41]
	v_mfma_f32_16x16x32_bf16 v[38:41], v[154:157], v[210:213], v[38:41]
	v_mfma_f32_16x16x32_bf16 v[30:33], v[166:169], v[210:213], v[30:33]
	v_mfma_f32_16x16x32_bf16 v[30:33], v[158:161], v[206:209], v[30:33]
	v_mfma_f32_16x16x32_bf16 v[14:17], v[158:161], v[214:217], v[14:17]
	v_mfma_f32_16x16x32_bf16 v[14:17], v[166:169], v[218:221], v[14:17]
	v_mfma_f32_16x16x32_bf16 v[22:25], v[154:157], v[218:221], v[22:25]
	v_mfma_f32_16x16x32_bf16 v[22:25], v[150:153], v[214:217], v[22:25]
	v_mfma_f32_16x16x32_bf16 v[50:53], v[170:173], v[186:189], v[50:53]
	v_mfma_f32_16x16x32_bf16 v[50:53], v[174:177], v[190:193], v[50:53]
	v_mfma_f32_16x16x32_bf16 v[42:45], v[182:185], v[190:193], v[42:45]
	v_mfma_f32_16x16x32_bf16 v[42:45], v[178:181], v[186:189], v[42:45]
	v_mfma_f32_16x16x32_bf16 v[26:29], v[178:181], v[194:197], v[26:29]
	v_mfma_f32_16x16x32_bf16 v[26:29], v[182:185], v[202:205], v[26:29]
	v_mfma_f32_16x16x32_bf16 v[34:37], v[174:177], v[202:205], v[34:37]
	v_mfma_f32_16x16x32_bf16 v[34:37], v[170:173], v[194:197], v[34:37]
	v_mfma_f32_16x16x32_bf16 v[18:21], v[170:173], v[206:209], v[18:21]
	v_mfma_f32_16x16x32_bf16 v[18:21], v[174:177], v[210:213], v[18:21]
	v_mfma_f32_16x16x32_bf16 v[10:13], v[182:185], v[210:213], v[10:13]
	v_mfma_f32_16x16x32_bf16 v[10:13], v[178:181], v[206:209], v[10:13]
	v_mfma_f32_16x16x32_bf16 v[2:5], v[178:181], v[214:217], v[2:5]
	v_mfma_f32_16x16x32_bf16 v[2:5], v[182:185], v[218:221], v[2:5]
	v_mfma_f32_16x16x32_bf16 v[6:9], v[174:177], v[218:221], v[6:9]
	v_mfma_f32_16x16x32_bf16 v[6:9], v[170:173], v[214:217], v[6:9]
	s_setprio 0
	s_barrier
	s_movk_i32 s44, 0x100
	s_andn2_b64 vcc, exec, s[58:59]
	s_mov_b64 s[60:61], -1
	s_mov_b64 s[58:59], 0
	s_cbranch_vccz .LBB0_1667
	s_and_b64 vcc, exec, s[16:17]
	s_cbranch_vccz .LBB0_1670
	s_barrier

.LBB0_1685:
	ds_read_b128 v[156:159], v153
	ds_read_b128 v[166:169], v153 offset:1024
	ds_read_b128 v[170:173], v153 offset:2048
	ds_read_b128 v[174:177], v153 offset:3072
	ds_read_b128 v[178:181], v154
	ds_read_b128 v[182:185], v154 offset:1024
	ds_read_b128 v[186:189], v154 offset:2048
	ds_read_b128 v[190:193], v154 offset:3072
	s_add_u32 s36, s56, 0xfff00080
	s_addc_u32 s37, s57, -1
	s_cmp_eq_u32 s78, 60
	s_cselect_b32 s61, s25, s37
	s_cselect_b32 s60, s74, s36
	s_cselect_b32 s59, s21, s77
	s_cselect_b32 s58, s75, s76
	v_lshl_add_u64 v[160:161], s[56:57], 0, v[140:141]
	s_add_i32 m0, s55, 0xc000
	ds_read_b128 v[194:197], v155
	ds_read_b128 v[202:205], v155 offset:1024
	ds_read_b128 v[206:209], v155 offset:2048
	ds_read_b128 v[210:213], v155 offset:3072
	ds_read_b128 v[214:217], v155 offset:4096
	ds_read_b128 v[218:221], v155 offset:5120
	ds_read_b128 v[222:225], v155 offset:6144
	ds_read_b128 v[226:229], v155 offset:7168
	global_load_lds_dwordx4 v[160:161], off
	v_lshl_add_u64 v[160:161], s[56:57], 0, v[142:143]
	s_add_i32 m0, s55, 0xe000
	s_nop 0
	global_load_lds_dwordx4 v[160:161], off
	s_waitcnt vmcnt(8)
	s_waitcnt lgkmcnt(0)
	s_barrier
	s_setprio 1
	v_mfma_f32_16x16x32_bf16 v[126:129], v[156:159], v[194:197], v[126:129]
	v_mfma_f32_16x16x32_bf16 v[126:129], v[166:169], v[202:205], v[126:129]
	v_mfma_f32_16x16x32_bf16 v[122:125], v[174:177], v[202:205], v[122:125]
	v_mfma_f32_16x16x32_bf16 v[122:125], v[170:173], v[194:197], v[122:125]
	v_mfma_f32_16x16x32_bf16 v[110:113], v[170:173], v[206:209], v[110:113]
	v_mfma_f32_16x16x32_bf16 v[110:113], v[174:177], v[210:213], v[110:113]
	v_mfma_f32_16x16x32_bf16 v[118:121], v[166:169], v[210:213], v[118:121]
	v_mfma_f32_16x16x32_bf16 v[118:121], v[156:159], v[206:209], v[118:121]
	v_mfma_f32_16x16x32_bf16 v[102:105], v[156:159], v[214:217], v[102:105]
	v_mfma_f32_16x16x32_bf16 v[102:105], v[166:169], v[218:221], v[102:105]
	v_mfma_f32_16x16x32_bf16 v[94:97], v[174:177], v[218:221], v[94:97]
	v_mfma_f32_16x16x32_bf16 v[94:97], v[170:173], v[214:217], v[94:97]
	v_mfma_f32_16x16x32_bf16 v[78:81], v[170:173], v[222:225], v[78:81]
	v_mfma_f32_16x16x32_bf16 v[78:81], v[174:177], v[226:229], v[78:81]
	v_mfma_f32_16x16x32_bf16 v[86:89], v[166:169], v[226:229], v[86:89]
	v_mfma_f32_16x16x32_bf16 v[86:89], v[156:159], v[222:225], v[86:89]
	v_mfma_f32_16x16x32_bf16 v[114:117], v[178:181], v[194:197], v[114:117]
	v_mfma_f32_16x16x32_bf16 v[114:117], v[182:185], v[202:205], v[114:117]
	v_mfma_f32_16x16x32_bf16 v[106:109], v[190:193], v[202:205], v[106:109]
	v_mfma_f32_16x16x32_bf16 v[106:109], v[186:189], v[194:197], v[106:109]
	v_mfma_f32_16x16x32_bf16 v[90:93], v[186:189], v[206:209], v[90:93]
	v_mfma_f32_16x16x32_bf16 v[90:93], v[190:193], v[210:213], v[90:93]
	v_mfma_f32_16x16x32_bf16 v[98:101], v[182:185], v[210:213], v[98:101]
	v_mfma_f32_16x16x32_bf16 v[98:101], v[178:181], v[206:209], v[98:101]
	v_mfma_f32_16x16x32_bf16 v[82:85], v[178:181], v[214:217], v[82:85]
	v_mfma_f32_16x16x32_bf16 v[82:85], v[182:185], v[218:221], v[82:85]
	v_mfma_f32_16x16x32_bf16 v[74:77], v[190:193], v[218:221], v[74:77]
	v_mfma_f32_16x16x32_bf16 v[74:77], v[186:189], v[214:217], v[74:77]
	v_mfma_f32_16x16x32_bf16 v[66:69], v[186:189], v[222:225], v[66:69]
	v_mfma_f32_16x16x32_bf16 v[66:69], v[190:193], v[226:229], v[66:69]
	v_mfma_f32_16x16x32_bf16 v[70:73], v[182:185], v[226:229], v[70:73]
	v_mfma_f32_16x16x32_bf16 v[70:73], v[178:181], v[222:225], v[70:73]
	s_setprio 0
	s_barrier
	s_add_i32 s36, s68, s38
	v_lshl_add_u64 v[160:161], s[58:59], 0, v[136:137]
	s_mov_b32 m0, s36
	ds_read_b128 v[194:197], v155 offset:16384
	ds_read_b128 v[202:205], v155 offset:17408
	ds_read_b128 v[206:209], v155 offset:18432
	ds_read_b128 v[210:213], v155 offset:19456
	ds_read_b128 v[214:217], v155 offset:20480
	ds_read_b128 v[218:221], v155 offset:21504
	ds_read_b128 v[222:225], v155 offset:22528
	ds_read_b128 v[226:229], v155 offset:23552
	global_load_lds_dwordx4 v[160:161], off
	s_add_i32 m0, s36, 0x2000
	s_add_u32 s80, s58, 0x100000
	v_lshl_add_u64 v[198:199], s[58:59], 0, v[132:133]
	s_addc_u32 s81, s59, 0
	s_add_i32 s36, s69, s38
	global_load_lds_dwordx4 v[198:199], off
	v_lshl_add_u64 v[230:231], s[80:81], 0, v[136:137]
	s_mov_b32 m0, s36
	v_lshl_add_u64 v[232:233], s[60:61], 0, v[134:135]
	global_load_lds_dwordx4 v[230:231], off
	v_lshl_add_u64 v[230:231], s[80:81], 0, v[132:133]
	s_add_i32 m0, s36, 0x2000
	s_nop 0
	global_load_lds_dwordx4 v[230:231], off
	v_lshl_add_u64 v[230:231], s[60:61], 0, v[138:139]
	s_mov_b32 m0, s55
	s_nop 0
	global_load_lds_dwordx4 v[230:231], off
	s_mov_b32 m0, s63
	s_nop 0
	global_load_lds_dwordx4 v[232:233], off
	s_waitcnt vmcnt(8)
	s_waitcnt lgkmcnt(0)
	s_barrier
	s_setprio 1
	v_mfma_f32_16x16x32_bf16 v[62:65], v[156:159], v[194:197], v[62:65]
	v_mfma_f32_16x16x32_bf16 v[62:65], v[166:169], v[202:205], v[62:65]
	v_mfma_f32_16x16x32_bf16 v[58:61], v[174:177], v[202:205], v[58:61]
	v_mfma_f32_16x16x32_bf16 v[58:61], v[170:173], v[194:197], v[58:61]
	v_mfma_f32_16x16x32_bf16 v[46:49], v[170:173], v[206:209], v[46:49]
	v_mfma_f32_16x16x32_bf16 v[46:49], v[174:177], v[210:213], v[46:49]
	v_mfma_f32_16x16x32_bf16 v[54:57], v[166:169], v[210:213], v[54:57]
	v_mfma_f32_16x16x32_bf16 v[54:57], v[156:159], v[206:209], v[54:57]
	v_mfma_f32_16x16x32_bf16 v[38:41], v[156:159], v[214:217], v[38:41]
	v_mfma_f32_16x16x32_bf16 v[38:41], v[166:169], v[218:221], v[38:41]
	v_mfma_f32_16x16x32_bf16 v[30:33], v[174:177], v[218:221], v[30:33]
	v_mfma_f32_16x16x32_bf16 v[30:33], v[170:173], v[214:217], v[30:33]
	v_mfma_f32_16x16x32_bf16 v[14:17], v[170:173], v[222:225], v[14:17]
	v_mfma_f32_16x16x32_bf16 v[14:17], v[174:177], v[226:229], v[14:17]
	v_mfma_f32_16x16x32_bf16 v[22:25], v[166:169], v[226:229], v[22:25]
	v_mfma_f32_16x16x32_bf16 v[22:25], v[156:159], v[222:225], v[22:25]
	v_mfma_f32_16x16x32_bf16 v[50:53], v[178:181], v[194:197], v[50:53]
	v_mfma_f32_16x16x32_bf16 v[50:53], v[182:185], v[202:205], v[50:53]
	v_mfma_f32_16x16x32_bf16 v[42:45], v[190:193], v[202:205], v[42:45]
	v_mfma_f32_16x16x32_bf16 v[42:45], v[186:189], v[194:197], v[42:45]
	v_mfma_f32_16x16x32_bf16 v[26:29], v[186:189], v[206:209], v[26:29]
	v_mfma_f32_16x16x32_bf16 v[26:29], v[190:193], v[210:213], v[26:29]
	v_mfma_f32_16x16x32_bf16 v[34:37], v[182:185], v[210:213], v[34:37]
	v_mfma_f32_16x16x32_bf16 v[34:37], v[178:181], v[206:209], v[34:37]
	v_mfma_f32_16x16x32_bf16 v[18:21], v[178:181], v[214:217], v[18:21]
	v_mfma_f32_16x16x32_bf16 v[18:21], v[182:185], v[218:221], v[18:21]
	v_mfma_f32_16x16x32_bf16 v[10:13], v[190:193], v[218:221], v[10:13]
	v_mfma_f32_16x16x32_bf16 v[10:13], v[186:189], v[214:217], v[10:13]
	v_mfma_f32_16x16x32_bf16 v[2:5], v[186:189], v[222:225], v[2:5]
	v_mfma_f32_16x16x32_bf16 v[2:5], v[190:193], v[226:229], v[2:5]
	v_mfma_f32_16x16x32_bf16 v[6:9], v[182:185], v[226:229], v[6:9]
	v_mfma_f32_16x16x32_bf16 v[6:9], v[178:181], v[222:225], v[6:9]
	s_setprio 0
	s_barrier
	s_add_i32 s36, 0, 0x18000
	v_add_u32_e32 v165, s36, v151
	s_add_i32 s37, 0, 0x1c000
	ds_read_b128 v[156:159], v165
	ds_read_b128 v[166:169], v165 offset:1024
	ds_read_b128 v[170:173], v165 offset:2048
	ds_read_b128 v[174:177], v165 offset:3072
	v_add_u32_e32 v165, s37, v151
	ds_read_b128 v[178:181], v165
	ds_read_b128 v[182:185], v165 offset:1024
	ds_read_b128 v[186:189], v165 offset:2048
	ds_read_b128 v[190:193], v165 offset:3072
	s_add_u32 s60, s60, 0x100000
	s_addc_u32 s61, s61, 0
	s_mov_b32 m0, s64
	v_lshl_add_u64 v[234:235], s[60:61], 0, v[138:139]
	ds_read_b128 v[194:197], v155 offset:32768
	ds_read_b128 v[202:205], v155 offset:33792
	ds_read_b128 v[206:209], v155 offset:34816
	ds_read_b128 v[210:213], v155 offset:35840
	ds_read_b128 v[214:217], v155 offset:36864
	ds_read_b128 v[218:221], v155 offset:37888
	ds_read_b128 v[222:225], v155 offset:38912
	ds_read_b128 v[226:229], v155 offset:39936
	global_load_lds_dwordx4 v[234:235], off
	v_lshl_add_u64 v[234:235], s[60:61], 0, v[134:135]
	s_mov_b32 m0, s65
	s_nop 0
	global_load_lds_dwordx4 v[234:235], off
	s_waitcnt vmcnt(8)
	s_waitcnt lgkmcnt(0)
	s_barrier
	s_setprio 1
	v_mfma_f32_16x16x32_bf16 v[126:129], v[156:159], v[194:197], v[126:129]
	v_mfma_f32_16x16x32_bf16 v[126:129], v[166:169], v[202:205], v[126:129]
	v_mfma_f32_16x16x32_bf16 v[122:125], v[174:177], v[202:205], v[122:125]
	v_mfma_f32_16x16x32_bf16 v[122:125], v[170:173], v[194:197], v[122:125]
	v_mfma_f32_16x16x32_bf16 v[110:113], v[170:173], v[206:209], v[110:113]
	v_mfma_f32_16x16x32_bf16 v[110:113], v[174:177], v[210:213], v[110:113]
	v_mfma_f32_16x16x32_bf16 v[118:121], v[166:169], v[210:213], v[118:121]
	v_mfma_f32_16x16x32_bf16 v[118:121], v[156:159], v[206:209], v[118:121]
	v_mfma_f32_16x16x32_bf16 v[102:105], v[156:159], v[214:217], v[102:105]
	v_mfma_f32_16x16x32_bf16 v[102:105], v[166:169], v[218:221], v[102:105]
	v_mfma_f32_16x16x32_bf16 v[94:97], v[174:177], v[218:221], v[94:97]
	v_mfma_f32_16x16x32_bf16 v[94:97], v[170:173], v[214:217], v[94:97]
	v_mfma_f32_16x16x32_bf16 v[78:81], v[170:173], v[222:225], v[78:81]
	v_mfma_f32_16x16x32_bf16 v[78:81], v[174:177], v[226:229], v[78:81]
	v_mfma_f32_16x16x32_bf16 v[86:89], v[166:169], v[226:229], v[86:89]
	v_mfma_f32_16x16x32_bf16 v[86:89], v[156:159], v[222:225], v[86:89]
	v_mfma_f32_16x16x32_bf16 v[114:117], v[178:181], v[194:197], v[114:117]
	v_mfma_f32_16x16x32_bf16 v[114:117], v[182:185], v[202:205], v[114:117]
	v_mfma_f32_16x16x32_bf16 v[106:109], v[190:193], v[202:205], v[106:109]
	v_mfma_f32_16x16x32_bf16 v[106:109], v[186:189], v[194:197], v[106:109]
	v_mfma_f32_16x16x32_bf16 v[90:93], v[186:189], v[206:209], v[90:93]
	v_mfma_f32_16x16x32_bf16 v[90:93], v[190:193], v[210:213], v[90:93]
	v_mfma_f32_16x16x32_bf16 v[98:101], v[182:185], v[210:213], v[98:101]
	v_mfma_f32_16x16x32_bf16 v[98:101], v[178:181], v[206:209], v[98:101]
	v_mfma_f32_16x16x32_bf16 v[82:85], v[178:181], v[214:217], v[82:85]
	v_mfma_f32_16x16x32_bf16 v[82:85], v[182:185], v[218:221], v[82:85]
	v_mfma_f32_16x16x32_bf16 v[74:77], v[190:193], v[218:221], v[74:77]
	v_mfma_f32_16x16x32_bf16 v[74:77], v[186:189], v[214:217], v[74:77]
	v_mfma_f32_16x16x32_bf16 v[66:69], v[186:189], v[222:225], v[66:69]
	v_mfma_f32_16x16x32_bf16 v[66:69], v[190:193], v[226:229], v[66:69]
	v_mfma_f32_16x16x32_bf16 v[70:73], v[182:185], v[226:229], v[70:73]
	v_mfma_f32_16x16x32_bf16 v[70:73], v[178:181], v[222:225], v[70:73]
	s_setprio 0
	s_barrier
	s_add_i32 s36, s36, s38
	v_lshl_add_u64 v[160:161], v[160:161], 0, s[16:17]
	s_mov_b32 m0, s36
	ds_read_b128 v[194:197], v155 offset:49152
	ds_read_b128 v[202:205], v155 offset:50176
	ds_read_b128 v[206:209], v155 offset:51200
	ds_read_b128 v[210:213], v155 offset:52224
	ds_read_b128 v[214:217], v155 offset:53248
	ds_read_b128 v[218:221], v155 offset:54272
	ds_read_b128 v[222:225], v155 offset:55296
	ds_read_b128 v[226:229], v155 offset:56320
	global_load_lds_dwordx4 v[160:161], off
	s_add_i32 m0, s36, 0x2000
	s_add_u32 s58, s58, 0x100080
	v_lshl_add_u64 v[160:161], v[198:199], 0, s[16:17]
	s_addc_u32 s59, s59, 0
	s_add_i32 s36, s37, s38
	global_load_lds_dwordx4 v[160:161], off
	v_lshl_add_u64 v[160:161], s[58:59], 0, v[136:137]
	s_mov_b32 m0, s36
	s_nop 0
	global_load_lds_dwordx4 v[160:161], off
	v_lshl_add_u64 v[160:161], s[58:59], 0, v[132:133]
	s_add_i32 m0, s36, 0x2000
	s_nop 0
	global_load_lds_dwordx4 v[160:161], off
	v_lshl_add_u64 v[160:161], v[230:231], 0, s[16:17]
	s_mov_b32 m0, s66
	s_nop 0
	global_load_lds_dwordx4 v[160:161], off
	v_lshl_add_u64 v[160:161], v[232:233], 0, s[16:17]
	s_mov_b32 m0, s67
	s_nop 0
	global_load_lds_dwordx4 v[160:161], off
	s_waitcnt vmcnt(8)
	s_waitcnt lgkmcnt(0)
	s_barrier
	s_setprio 1
	v_mfma_f32_16x16x32_bf16 v[62:65], v[156:159], v[194:197], v[62:65]
	v_mfma_f32_16x16x32_bf16 v[62:65], v[166:169], v[202:205], v[62:65]
	v_mfma_f32_16x16x32_bf16 v[58:61], v[174:177], v[202:205], v[58:61]
	v_mfma_f32_16x16x32_bf16 v[58:61], v[170:173], v[194:197], v[58:61]
	v_mfma_f32_16x16x32_bf16 v[46:49], v[170:173], v[206:209], v[46:49]
	v_mfma_f32_16x16x32_bf16 v[46:49], v[174:177], v[210:213], v[46:49]
	v_mfma_f32_16x16x32_bf16 v[54:57], v[166:169], v[210:213], v[54:57]
	v_mfma_f32_16x16x32_bf16 v[54:57], v[156:159], v[206:209], v[54:57]
	v_mfma_f32_16x16x32_bf16 v[38:41], v[156:159], v[214:217], v[38:41]
	v_mfma_f32_16x16x32_bf16 v[38:41], v[166:169], v[218:221], v[38:41]
	v_mfma_f32_16x16x32_bf16 v[30:33], v[174:177], v[218:221], v[30:33]
	v_mfma_f32_16x16x32_bf16 v[30:33], v[170:173], v[214:217], v[30:33]
	v_mfma_f32_16x16x32_bf16 v[14:17], v[170:173], v[222:225], v[14:17]
	v_mfma_f32_16x16x32_bf16 v[14:17], v[174:177], v[226:229], v[14:17]
	v_mfma_f32_16x16x32_bf16 v[22:25], v[166:169], v[226:229], v[22:25]
	v_mfma_f32_16x16x32_bf16 v[22:25], v[156:159], v[222:225], v[22:25]
	v_mfma_f32_16x16x32_bf16 v[50:53], v[178:181], v[194:197], v[50:53]
	v_mfma_f32_16x16x32_bf16 v[50:53], v[182:185], v[202:205], v[50:53]
	v_mfma_f32_16x16x32_bf16 v[42:45], v[190:193], v[202:205], v[42:45]
	v_mfma_f32_16x16x32_bf16 v[42:45], v[186:189], v[194:197], v[42:45]
	v_mfma_f32_16x16x32_bf16 v[26:29], v[186:189], v[206:209], v[26:29]
	v_mfma_f32_16x16x32_bf16 v[26:29], v[190:193], v[210:213], v[26:29]
	v_mfma_f32_16x16x32_bf16 v[34:37], v[182:185], v[210:213], v[34:37]
	v_mfma_f32_16x16x32_bf16 v[34:37], v[178:181], v[206:209], v[34:37]
	v_mfma_f32_16x16x32_bf16 v[18:21], v[178:181], v[214:217], v[18:21]
	v_mfma_f32_16x16x32_bf16 v[18:21], v[182:185], v[218:221], v[18:21]
	v_mfma_f32_16x16x32_bf16 v[10:13], v[190:193], v[218:221], v[10:13]
	v_mfma_f32_16x16x32_bf16 v[10:13], v[186:189], v[214:217], v[10:13]
	v_mfma_f32_16x16x32_bf16 v[2:5], v[186:189], v[222:225], v[2:5]
	v_mfma_f32_16x16x32_bf16 v[2:5], v[190:193], v[226:229], v[2:5]
	v_mfma_f32_16x16x32_bf16 v[6:9], v[182:185], v[226:229], v[6:9]
	v_mfma_f32_16x16x32_bf16 v[6:9], v[178:181], v[222:225], v[6:9]
	s_setprio 0
	s_barrier
	s_add_i32 s78, s78, 2
	s_add_u32 s56, s56, 0x100
	s_addc_u32 s57, s57, 0
	s_add_u32 s76, s76, 0x100
	s_addc_u32 s77, s77, 0
	s_cmp_gt_u32 s78, 61
	s_cbranch_scc0 .LBB0_1685
	s_and_b64 vcc, exec, s[18:19]
	s_cbranch_vccz .LBB0_1688
	s_barrier

.LBB0_1701:
	s_add_u32 s36, s56, s44
	s_addc_u32 s37, s57, 0
	s_add_u32 s64, s36, 0x100
	s_addc_u32 s65, s37, 0
	s_and_b64 s[62:63], s[60:61], exec
	s_cselect_b32 s65, s21, s65
	s_cselect_b32 s64, s86, s64
	s_add_u32 s44, s54, s44
	s_addc_u32 s62, s55, 0
	s_add_u32 s44, s44, 0x100
	s_addc_u32 s62, s62, 0
	s_and_b64 s[60:61], s[60:61], exec
	s_cselect_b32 s67, s25, s62
	s_cselect_b32 s66, s87, s44
	s_add_u32 s70, s36, 0x10080
	s_addc_u32 s71, s37, 0
	s_add_i32 s97, s81, s39
	ds_read_b128 v[152:155], v147
	ds_read_b128 v[156:159], v147 offset:1024
	ds_read_b128 v[166:169], v147 offset:2048
	ds_read_b128 v[170:173], v147 offset:3072
	ds_read_b128 v[174:177], v150
	ds_read_b128 v[178:181], v150 offset:1024
	ds_read_b128 v[182:185], v150 offset:2048
	ds_read_b128 v[186:189], v150 offset:3072
	s_add_i32 m0, s74, 0xc000
	s_add_i32 vcc_lo, s74, 0xe000
	s_add_i32 s94, s97, 0x2000
	s_add_u32 s68, s66, 0x10000
	s_addc_u32 s69, s67, 0
	s_add_i32 s96, s82, s39
	s_add_i32 s95, s96, 0x2000
	s_add_i32 s93, 0, 0x18000
	s_add_i32 s92, 0, 0x1c000
	s_add_u32 s62, s64, 0x10000
	s_addc_u32 s63, s65, 0
	s_add_i32 s91, s93, s39
	s_add_i32 s89, s91, 0x2000
	s_add_u32 s60, s66, 0x10080
	s_addc_u32 s61, s67, 0
	s_add_i32 s90, s92, s39
	s_add_i32 s44, s90, 0x2000
	v_lshl_add_u64 v[160:161], s[70:71], 0, v[138:139]
	ds_read_b128 v[190:193], v151
	ds_read_b128 v[194:197], v151 offset:1024
	ds_read_b128 v[202:205], v151 offset:2048
	ds_read_b128 v[206:209], v151 offset:3072
	ds_read_b128 v[210:213], v151 offset:4096
	ds_read_b128 v[214:217], v151 offset:5120
	ds_read_b128 v[218:221], v151 offset:6144
	ds_read_b128 v[222:225], v151 offset:7168
	global_load_lds_dwordx4 v[160:161], off
	v_lshl_add_u64 v[160:161], s[70:71], 0, v[134:135]
	s_mov_b32 m0, vcc_lo
	s_nop 0
	global_load_lds_dwordx4 v[160:161], off
	s_waitcnt vmcnt(8)
	s_waitcnt lgkmcnt(0)
	s_barrier
	s_setprio 1
	v_mfma_f32_16x16x32_bf16 v[126:129], v[152:155], v[190:193], v[126:129]
	v_mfma_f32_16x16x32_bf16 v[126:129], v[156:159], v[194:197], v[126:129]
	v_mfma_f32_16x16x32_bf16 v[122:125], v[170:173], v[194:197], v[122:125]
	v_mfma_f32_16x16x32_bf16 v[122:125], v[166:169], v[190:193], v[122:125]
	v_mfma_f32_16x16x32_bf16 v[110:113], v[166:169], v[202:205], v[110:113]
	v_mfma_f32_16x16x32_bf16 v[110:113], v[170:173], v[206:209], v[110:113]
	v_mfma_f32_16x16x32_bf16 v[118:121], v[156:159], v[206:209], v[118:121]
	v_mfma_f32_16x16x32_bf16 v[118:121], v[152:155], v[202:205], v[118:121]
	v_mfma_f32_16x16x32_bf16 v[102:105], v[152:155], v[210:213], v[102:105]
	v_mfma_f32_16x16x32_bf16 v[102:105], v[156:159], v[214:217], v[102:105]
	v_mfma_f32_16x16x32_bf16 v[94:97], v[170:173], v[214:217], v[94:97]
	v_mfma_f32_16x16x32_bf16 v[94:97], v[166:169], v[210:213], v[94:97]
	v_mfma_f32_16x16x32_bf16 v[78:81], v[166:169], v[218:221], v[78:81]
	v_mfma_f32_16x16x32_bf16 v[78:81], v[170:173], v[222:225], v[78:81]
	v_mfma_f32_16x16x32_bf16 v[86:89], v[156:159], v[222:225], v[86:89]
	v_mfma_f32_16x16x32_bf16 v[86:89], v[152:155], v[218:221], v[86:89]
	v_mfma_f32_16x16x32_bf16 v[114:117], v[174:177], v[190:193], v[114:117]
	v_mfma_f32_16x16x32_bf16 v[114:117], v[178:181], v[194:197], v[114:117]
	v_mfma_f32_16x16x32_bf16 v[106:109], v[186:189], v[194:197], v[106:109]
	v_mfma_f32_16x16x32_bf16 v[106:109], v[182:185], v[190:193], v[106:109]
	v_mfma_f32_16x16x32_bf16 v[90:93], v[182:185], v[202:205], v[90:93]
	v_mfma_f32_16x16x32_bf16 v[90:93], v[186:189], v[206:209], v[90:93]
	v_mfma_f32_16x16x32_bf16 v[98:101], v[178:181], v[206:209], v[98:101]
	v_mfma_f32_16x16x32_bf16 v[98:101], v[174:177], v[202:205], v[98:101]
	v_mfma_f32_16x16x32_bf16 v[82:85], v[174:177], v[210:213], v[82:85]
	v_mfma_f32_16x16x32_bf16 v[82:85], v[178:181], v[214:217], v[82:85]
	v_mfma_f32_16x16x32_bf16 v[74:77], v[186:189], v[214:217], v[74:77]
	v_mfma_f32_16x16x32_bf16 v[74:77], v[182:185], v[210:213], v[74:77]
	v_mfma_f32_16x16x32_bf16 v[66:69], v[182:185], v[218:221], v[66:69]
	v_mfma_f32_16x16x32_bf16 v[66:69], v[186:189], v[222:225], v[66:69]
	v_mfma_f32_16x16x32_bf16 v[70:73], v[178:181], v[222:225], v[70:73]
	v_mfma_f32_16x16x32_bf16 v[70:73], v[174:177], v[218:221], v[70:73]
	s_setprio 0
	s_barrier
	s_mov_b32 m0, s97
	v_lshl_add_u64 v[160:161], s[66:67], 0, v[136:137]
	ds_read_b128 v[190:193], v151 offset:16384
	ds_read_b128 v[194:197], v151 offset:17408
	ds_read_b128 v[202:205], v151 offset:18432
	ds_read_b128 v[206:209], v151 offset:19456
	ds_read_b128 v[210:213], v151 offset:20480
	ds_read_b128 v[214:217], v151 offset:21504
	ds_read_b128 v[218:221], v151 offset:22528
	ds_read_b128 v[222:225], v151 offset:23552
	global_load_lds_dwordx4 v[160:161], off
	v_lshl_add_u64 v[198:199], s[66:67], 0, v[132:133]
	s_mov_b32 m0, s94
	v_lshl_add_u64 v[226:227], s[68:69], 0, v[136:137]
	global_load_lds_dwordx4 v[198:199], off
	s_mov_b32 m0, s96
	v_lshl_add_u64 v[228:229], s[64:65], 0, v[134:135]
	global_load_lds_dwordx4 v[226:227], off
	v_lshl_add_u64 v[226:227], s[68:69], 0, v[132:133]
	s_mov_b32 m0, s95
	s_nop 0
	global_load_lds_dwordx4 v[226:227], off
	v_lshl_add_u64 v[226:227], s[64:65], 0, v[138:139]
	s_mov_b32 m0, s74
	s_nop 0
	global_load_lds_dwordx4 v[226:227], off
	s_mov_b32 m0, s75
	s_nop 0
	global_load_lds_dwordx4 v[228:229], off
	s_waitcnt vmcnt(8)
	s_waitcnt lgkmcnt(0)
	s_barrier
	s_setprio 1
	v_mfma_f32_16x16x32_bf16 v[62:65], v[152:155], v[190:193], v[62:65]
	v_mfma_f32_16x16x32_bf16 v[62:65], v[156:159], v[194:197], v[62:65]
	v_mfma_f32_16x16x32_bf16 v[58:61], v[170:173], v[194:197], v[58:61]
	v_mfma_f32_16x16x32_bf16 v[58:61], v[166:169], v[190:193], v[58:61]
	v_mfma_f32_16x16x32_bf16 v[46:49], v[166:169], v[202:205], v[46:49]
	v_mfma_f32_16x16x32_bf16 v[46:49], v[170:173], v[206:209], v[46:49]
	v_mfma_f32_16x16x32_bf16 v[54:57], v[156:159], v[206:209], v[54:57]
	v_mfma_f32_16x16x32_bf16 v[54:57], v[152:155], v[202:205], v[54:57]
	v_mfma_f32_16x16x32_bf16 v[38:41], v[152:155], v[210:213], v[38:41]
	v_mfma_f32_16x16x32_bf16 v[38:41], v[156:159], v[214:217], v[38:41]
	v_mfma_f32_16x16x32_bf16 v[30:33], v[170:173], v[214:217], v[30:33]
	v_mfma_f32_16x16x32_bf16 v[30:33], v[166:169], v[210:213], v[30:33]
	v_mfma_f32_16x16x32_bf16 v[14:17], v[166:169], v[218:221], v[14:17]
	v_mfma_f32_16x16x32_bf16 v[14:17], v[170:173], v[222:225], v[14:17]
	v_mfma_f32_16x16x32_bf16 v[22:25], v[156:159], v[222:225], v[22:25]
	v_mfma_f32_16x16x32_bf16 v[22:25], v[152:155], v[218:221], v[22:25]
	v_mfma_f32_16x16x32_bf16 v[50:53], v[174:177], v[190:193], v[50:53]
	v_mfma_f32_16x16x32_bf16 v[50:53], v[178:181], v[194:197], v[50:53]
	v_mfma_f32_16x16x32_bf16 v[42:45], v[186:189], v[194:197], v[42:45]
	v_mfma_f32_16x16x32_bf16 v[42:45], v[182:185], v[190:193], v[42:45]
	v_mfma_f32_16x16x32_bf16 v[26:29], v[182:185], v[202:205], v[26:29]
	v_mfma_f32_16x16x32_bf16 v[26:29], v[186:189], v[206:209], v[26:29]
	v_mfma_f32_16x16x32_bf16 v[34:37], v[178:181], v[206:209], v[34:37]
	v_mfma_f32_16x16x32_bf16 v[34:37], v[174:177], v[202:205], v[34:37]
	v_mfma_f32_16x16x32_bf16 v[18:21], v[174:177], v[210:213], v[18:21]
	v_mfma_f32_16x16x32_bf16 v[18:21], v[178:181], v[214:217], v[18:21]
	v_mfma_f32_16x16x32_bf16 v[10:13], v[186:189], v[214:217], v[10:13]
	v_mfma_f32_16x16x32_bf16 v[10:13], v[182:185], v[210:213], v[10:13]
	v_mfma_f32_16x16x32_bf16 v[2:5], v[182:185], v[218:221], v[2:5]
	v_mfma_f32_16x16x32_bf16 v[2:5], v[186:189], v[222:225], v[2:5]
	v_mfma_f32_16x16x32_bf16 v[6:9], v[178:181], v[222:225], v[6:9]
	v_mfma_f32_16x16x32_bf16 v[6:9], v[174:177], v[218:221], v[6:9]
	s_setprio 0
	s_barrier
	v_add_u32_e32 v165, s93, v145
	ds_read_b128 v[152:155], v165
	ds_read_b128 v[156:159], v165 offset:1024
	ds_read_b128 v[166:169], v165 offset:2048
	ds_read_b128 v[170:173], v165 offset:3072
	v_add_u32_e32 v165, s92, v145
	ds_read_b128 v[174:177], v165
	ds_read_b128 v[178:181], v165 offset:1024
	ds_read_b128 v[182:185], v165 offset:2048
	ds_read_b128 v[186:189], v165 offset:3072
	s_mov_b32 m0, s76
	v_lshl_add_u64 v[230:231], s[62:63], 0, v[138:139]
	ds_read_b128 v[190:193], v151 offset:32768
	ds_read_b128 v[194:197], v151 offset:33792
	ds_read_b128 v[202:205], v151 offset:34816
	ds_read_b128 v[206:209], v151 offset:35840
	ds_read_b128 v[210:213], v151 offset:36864
	ds_read_b128 v[214:217], v151 offset:37888
	ds_read_b128 v[218:221], v151 offset:38912
	ds_read_b128 v[222:225], v151 offset:39936
	global_load_lds_dwordx4 v[230:231], off
	v_lshl_add_u64 v[230:231], s[62:63], 0, v[134:135]
	s_mov_b32 m0, s77
	s_nop 0
	global_load_lds_dwordx4 v[230:231], off
	s_waitcnt vmcnt(8)
	s_waitcnt lgkmcnt(0)
	s_barrier
	s_setprio 1
	v_mfma_f32_16x16x32_bf16 v[126:129], v[152:155], v[190:193], v[126:129]
	v_mfma_f32_16x16x32_bf16 v[126:129], v[156:159], v[194:197], v[126:129]
	v_mfma_f32_16x16x32_bf16 v[122:125], v[170:173], v[194:197], v[122:125]
	v_mfma_f32_16x16x32_bf16 v[122:125], v[166:169], v[190:193], v[122:125]
	v_mfma_f32_16x16x32_bf16 v[110:113], v[166:169], v[202:205], v[110:113]
	v_mfma_f32_16x16x32_bf16 v[110:113], v[170:173], v[206:209], v[110:113]
	v_mfma_f32_16x16x32_bf16 v[118:121], v[156:159], v[206:209], v[118:121]
	v_mfma_f32_16x16x32_bf16 v[118:121], v[152:155], v[202:205], v[118:121]
	v_mfma_f32_16x16x32_bf16 v[102:105], v[152:155], v[210:213], v[102:105]
	v_mfma_f32_16x16x32_bf16 v[102:105], v[156:159], v[214:217], v[102:105]
	v_mfma_f32_16x16x32_bf16 v[94:97], v[170:173], v[214:217], v[94:97]
	v_mfma_f32_16x16x32_bf16 v[94:97], v[166:169], v[210:213], v[94:97]
	v_mfma_f32_16x16x32_bf16 v[78:81], v[166:169], v[218:221], v[78:81]
	v_mfma_f32_16x16x32_bf16 v[78:81], v[170:173], v[222:225], v[78:81]
	v_mfma_f32_16x16x32_bf16 v[86:89], v[156:159], v[222:225], v[86:89]
	v_mfma_f32_16x16x32_bf16 v[86:89], v[152:155], v[218:221], v[86:89]
	v_mfma_f32_16x16x32_bf16 v[114:117], v[174:177], v[190:193], v[114:117]
	v_mfma_f32_16x16x32_bf16 v[114:117], v[178:181], v[194:197], v[114:117]
	v_mfma_f32_16x16x32_bf16 v[106:109], v[186:189], v[194:197], v[106:109]
	v_mfma_f32_16x16x32_bf16 v[106:109], v[182:185], v[190:193], v[106:109]
	v_mfma_f32_16x16x32_bf16 v[90:93], v[182:185], v[202:205], v[90:93]
	v_mfma_f32_16x16x32_bf16 v[90:93], v[186:189], v[206:209], v[90:93]
	v_mfma_f32_16x16x32_bf16 v[98:101], v[178:181], v[206:209], v[98:101]
	v_mfma_f32_16x16x32_bf16 v[98:101], v[174:177], v[202:205], v[98:101]
	v_mfma_f32_16x16x32_bf16 v[82:85], v[174:177], v[210:213], v[82:85]
	v_mfma_f32_16x16x32_bf16 v[82:85], v[178:181], v[214:217], v[82:85]
	v_mfma_f32_16x16x32_bf16 v[74:77], v[186:189], v[214:217], v[74:77]
	v_mfma_f32_16x16x32_bf16 v[74:77], v[182:185], v[210:213], v[74:77]
	v_mfma_f32_16x16x32_bf16 v[66:69], v[182:185], v[218:221], v[66:69]
	v_mfma_f32_16x16x32_bf16 v[66:69], v[186:189], v[222:225], v[66:69]
	v_mfma_f32_16x16x32_bf16 v[70:73], v[178:181], v[222:225], v[70:73]
	v_mfma_f32_16x16x32_bf16 v[70:73], v[174:177], v[218:221], v[70:73]
	s_setprio 0
	s_barrier
	s_mov_b32 m0, s91
	v_lshl_add_u64 v[160:161], v[160:161], 0, s[14:15]
	ds_read_b128 v[190:193], v151 offset:49152
	ds_read_b128 v[194:197], v151 offset:50176
	ds_read_b128 v[202:205], v151 offset:51200
	ds_read_b128 v[206:209], v151 offset:52224
	ds_read_b128 v[210:213], v151 offset:53248
	ds_read_b128 v[214:217], v151 offset:54272
	ds_read_b128 v[218:221], v151 offset:55296
	ds_read_b128 v[222:225], v151 offset:56320
	global_load_lds_dwordx4 v[160:161], off
	v_lshl_add_u64 v[160:161], v[198:199], 0, s[14:15]
	s_mov_b32 m0, s89
	s_nop 0
	global_load_lds_dwordx4 v[160:161], off
	v_lshl_add_u64 v[160:161], s[60:61], 0, v[136:137]
	s_mov_b32 m0, s90
	s_nop 0
	global_load_lds_dwordx4 v[160:161], off
	v_lshl_add_u64 v[160:161], s[60:61], 0, v[132:133]
	s_mov_b32 m0, s44
	s_nop 0
	global_load_lds_dwordx4 v[160:161], off
	v_lshl_add_u64 v[160:161], v[226:227], 0, s[14:15]
	s_mov_b32 m0, s79
	s_nop 0
	global_load_lds_dwordx4 v[160:161], off
	v_lshl_add_u64 v[160:161], v[228:229], 0, s[14:15]
	s_mov_b32 m0, s80
	s_nop 0
	global_load_lds_dwordx4 v[160:161], off
	s_waitcnt vmcnt(8)
	s_waitcnt lgkmcnt(0)
	s_barrier
	s_setprio 1
	v_mfma_f32_16x16x32_bf16 v[62:65], v[152:155], v[190:193], v[62:65]
	v_mfma_f32_16x16x32_bf16 v[62:65], v[156:159], v[194:197], v[62:65]
	v_mfma_f32_16x16x32_bf16 v[58:61], v[170:173], v[194:197], v[58:61]
	v_mfma_f32_16x16x32_bf16 v[58:61], v[166:169], v[190:193], v[58:61]
	v_mfma_f32_16x16x32_bf16 v[46:49], v[166:169], v[202:205], v[46:49]
	v_mfma_f32_16x16x32_bf16 v[46:49], v[170:173], v[206:209], v[46:49]
	v_mfma_f32_16x16x32_bf16 v[54:57], v[156:159], v[206:209], v[54:57]
	v_mfma_f32_16x16x32_bf16 v[54:57], v[152:155], v[202:205], v[54:57]
	v_mfma_f32_16x16x32_bf16 v[38:41], v[152:155], v[210:213], v[38:41]
	v_mfma_f32_16x16x32_bf16 v[38:41], v[156:159], v[214:217], v[38:41]
	v_mfma_f32_16x16x32_bf16 v[30:33], v[170:173], v[214:217], v[30:33]
	v_mfma_f32_16x16x32_bf16 v[30:33], v[166:169], v[210:213], v[30:33]
	v_mfma_f32_16x16x32_bf16 v[14:17], v[166:169], v[218:221], v[14:17]
	v_mfma_f32_16x16x32_bf16 v[14:17], v[170:173], v[222:225], v[14:17]
	v_mfma_f32_16x16x32_bf16 v[22:25], v[156:159], v[222:225], v[22:25]
	v_mfma_f32_16x16x32_bf16 v[22:25], v[152:155], v[218:221], v[22:25]
	v_mfma_f32_16x16x32_bf16 v[50:53], v[174:177], v[190:193], v[50:53]
	v_mfma_f32_16x16x32_bf16 v[50:53], v[178:181], v[194:197], v[50:53]
	v_mfma_f32_16x16x32_bf16 v[42:45], v[186:189], v[194:197], v[42:45]
	v_mfma_f32_16x16x32_bf16 v[42:45], v[182:185], v[190:193], v[42:45]
	v_mfma_f32_16x16x32_bf16 v[26:29], v[182:185], v[202:205], v[26:29]
	v_mfma_f32_16x16x32_bf16 v[26:29], v[186:189], v[206:209], v[26:29]
	v_mfma_f32_16x16x32_bf16 v[34:37], v[178:181], v[206:209], v[34:37]
	v_mfma_f32_16x16x32_bf16 v[34:37], v[174:177], v[202:205], v[34:37]
	v_mfma_f32_16x16x32_bf16 v[18:21], v[174:177], v[210:213], v[18:21]
	v_mfma_f32_16x16x32_bf16 v[18:21], v[178:181], v[214:217], v[18:21]
	v_mfma_f32_16x16x32_bf16 v[10:13], v[186:189], v[214:217], v[10:13]
	v_mfma_f32_16x16x32_bf16 v[10:13], v[182:185], v[210:213], v[10:13]
	v_mfma_f32_16x16x32_bf16 v[2:5], v[182:185], v[218:221], v[2:5]
	v_mfma_f32_16x16x32_bf16 v[2:5], v[186:189], v[222:225], v[2:5]
	v_mfma_f32_16x16x32_bf16 v[6:9], v[178:181], v[222:225], v[6:9]
	v_mfma_f32_16x16x32_bf16 v[6:9], v[174:177], v[218:221], v[6:9]
	s_setprio 0
	s_barrier
	s_movk_i32 s44, 0x100
	s_andn2_b64 vcc, exec, s[58:59]
	s_mov_b64 s[60:61], -1
	s_mov_b64 s[58:59], 0
	s_cbranch_vccz .LBB0_1701
	s_and_b64 vcc, exec, s[16:17]
	s_cbranch_vccz .LBB0_1704
	s_barrier

.LBB0_1902:
	ds_read_b128 v[148:151], v156
	ds_read_b128 v[166:169], v156 offset:1024
	ds_read_b128 v[170:173], v156 offset:2048
	ds_read_b128 v[174:177], v156 offset:3072
	ds_read_b128 v[178:181], v157
	ds_read_b128 v[182:185], v157 offset:1024
	ds_read_b128 v[186:189], v157 offset:2048
	ds_read_b128 v[190:193], v157 offset:3072
	s_add_i32 s92, s58, 2
	s_add_u32 s36, s56, 0xffd50080
	s_addc_u32 s37, s57, -1
	s_cmp_eq_u32 s89, s58
	s_cselect_b32 s58, s54, s90
	s_cselect_b32 s61, s53, s37
	s_cselect_b32 s60, s52, s36
	s_cselect_b32 s59, s55, s91
	v_lshl_add_u64 v[152:153], s[56:57], 0, v[142:143]
	s_add_i32 m0, s67, 0xc000
	ds_read_b128 v[194:197], v158
	ds_read_b128 v[202:205], v158 offset:1024
	ds_read_b128 v[206:209], v158 offset:2048
	ds_read_b128 v[210:213], v158 offset:3072
	ds_read_b128 v[214:217], v158 offset:4096
	ds_read_b128 v[218:221], v158 offset:5120
	ds_read_b128 v[222:225], v158 offset:6144
	ds_read_b128 v[226:229], v158 offset:7168
	global_load_lds_dwordx4 v[152:153], off
	v_lshl_add_u64 v[152:153], s[56:57], 0, v[144:145]
	s_add_i32 m0, s67, 0xe000
	s_nop 0
	global_load_lds_dwordx4 v[152:153], off
	s_waitcnt vmcnt(8)
	s_waitcnt lgkmcnt(0)
	s_barrier
	s_setprio 1
	v_mfma_f32_16x16x32_bf16 v[126:129], v[148:151], v[194:197], v[126:129]
	v_mfma_f32_16x16x32_bf16 v[126:129], v[166:169], v[202:205], v[126:129]
	v_mfma_f32_16x16x32_bf16 v[122:125], v[174:177], v[202:205], v[122:125]
	v_mfma_f32_16x16x32_bf16 v[122:125], v[170:173], v[194:197], v[122:125]
	v_mfma_f32_16x16x32_bf16 v[106:109], v[170:173], v[206:209], v[106:109]
	v_mfma_f32_16x16x32_bf16 v[106:109], v[174:177], v[210:213], v[106:109]
	v_mfma_f32_16x16x32_bf16 v[110:113], v[166:169], v[210:213], v[110:113]
	v_mfma_f32_16x16x32_bf16 v[110:113], v[148:151], v[206:209], v[110:113]
	v_mfma_f32_16x16x32_bf16 v[94:97], v[148:151], v[214:217], v[94:97]
	v_mfma_f32_16x16x32_bf16 v[94:97], v[166:169], v[218:221], v[94:97]
	v_mfma_f32_16x16x32_bf16 v[90:93], v[174:177], v[218:221], v[90:93]
	v_mfma_f32_16x16x32_bf16 v[90:93], v[170:173], v[214:217], v[90:93]
	v_mfma_f32_16x16x32_bf16 v[74:77], v[170:173], v[222:225], v[74:77]
	v_mfma_f32_16x16x32_bf16 v[74:77], v[174:177], v[226:229], v[74:77]
	v_mfma_f32_16x16x32_bf16 v[78:81], v[166:169], v[226:229], v[78:81]
	v_mfma_f32_16x16x32_bf16 v[78:81], v[148:151], v[222:225], v[78:81]
	v_mfma_f32_16x16x32_bf16 v[118:121], v[178:181], v[194:197], v[118:121]
	v_mfma_f32_16x16x32_bf16 v[118:121], v[182:185], v[202:205], v[118:121]
	v_mfma_f32_16x16x32_bf16 v[114:117], v[190:193], v[202:205], v[114:117]
	v_mfma_f32_16x16x32_bf16 v[114:117], v[186:189], v[194:197], v[114:117]
	v_mfma_f32_16x16x32_bf16 v[98:101], v[186:189], v[206:209], v[98:101]
	v_mfma_f32_16x16x32_bf16 v[98:101], v[190:193], v[210:213], v[98:101]
	v_mfma_f32_16x16x32_bf16 v[102:105], v[182:185], v[210:213], v[102:105]
	v_mfma_f32_16x16x32_bf16 v[102:105], v[178:181], v[206:209], v[102:105]
	v_mfma_f32_16x16x32_bf16 v[86:89], v[178:181], v[214:217], v[86:89]
	v_mfma_f32_16x16x32_bf16 v[86:89], v[182:185], v[218:221], v[86:89]
	v_mfma_f32_16x16x32_bf16 v[82:85], v[190:193], v[218:221], v[82:85]
	v_mfma_f32_16x16x32_bf16 v[82:85], v[186:189], v[214:217], v[82:85]
	v_mfma_f32_16x16x32_bf16 v[66:69], v[186:189], v[222:225], v[66:69]
	v_mfma_f32_16x16x32_bf16 v[66:69], v[190:193], v[226:229], v[66:69]
	v_mfma_f32_16x16x32_bf16 v[70:73], v[182:185], v[226:229], v[70:73]
	v_mfma_f32_16x16x32_bf16 v[70:73], v[178:181], v[222:225], v[70:73]
	s_setprio 0
	s_barrier
	s_add_i32 s36, s77, s64
	v_lshl_add_u64 v[152:153], s[58:59], 0, v[134:135]
	s_mov_b32 m0, s36
	ds_read_b128 v[194:197], v158 offset:16384
	ds_read_b128 v[202:205], v158 offset:17408
	ds_read_b128 v[206:209], v158 offset:18432
	ds_read_b128 v[210:213], v158 offset:19456
	ds_read_b128 v[214:217], v158 offset:20480
	ds_read_b128 v[218:221], v158 offset:21504
	ds_read_b128 v[222:225], v158 offset:22528
	ds_read_b128 v[226:229], v158 offset:23552
	global_load_lds_dwordx4 v[152:153], off
	s_add_i32 m0, s36, 0x2000
	s_add_u32 s94, s58, 0x2b0000
	v_lshl_add_u64 v[160:161], s[58:59], 0, v[138:139]
	s_addc_u32 s95, s59, 0
	s_add_i32 s36, s78, s64
	global_load_lds_dwordx4 v[160:161], off
	v_lshl_add_u64 v[198:199], s[94:95], 0, v[134:135]
	s_mov_b32 m0, s36
	v_lshl_add_u64 v[230:231], s[60:61], 0, v[136:137]
	global_load_lds_dwordx4 v[198:199], off
	v_lshl_add_u64 v[198:199], s[94:95], 0, v[138:139]
	s_add_i32 m0, s36, 0x2000
	s_nop 0
	global_load_lds_dwordx4 v[198:199], off
	v_lshl_add_u64 v[198:199], s[60:61], 0, v[132:133]
	s_mov_b32 m0, s67
	s_nop 0
	global_load_lds_dwordx4 v[198:199], off
	s_mov_b32 m0, s68
	s_nop 0
	global_load_lds_dwordx4 v[230:231], off
	s_waitcnt vmcnt(8)
	s_waitcnt lgkmcnt(0)
	s_barrier
	s_setprio 1
	v_mfma_f32_16x16x32_bf16 v[62:65], v[148:151], v[194:197], v[62:65]
	v_mfma_f32_16x16x32_bf16 v[62:65], v[166:169], v[202:205], v[62:65]
	v_mfma_f32_16x16x32_bf16 v[58:61], v[174:177], v[202:205], v[58:61]
	v_mfma_f32_16x16x32_bf16 v[58:61], v[170:173], v[194:197], v[58:61]
	v_mfma_f32_16x16x32_bf16 v[42:45], v[170:173], v[206:209], v[42:45]
	v_mfma_f32_16x16x32_bf16 v[42:45], v[174:177], v[210:213], v[42:45]
	v_mfma_f32_16x16x32_bf16 v[46:49], v[166:169], v[210:213], v[46:49]
	v_mfma_f32_16x16x32_bf16 v[46:49], v[148:151], v[206:209], v[46:49]
	v_mfma_f32_16x16x32_bf16 v[30:33], v[148:151], v[214:217], v[30:33]
	v_mfma_f32_16x16x32_bf16 v[30:33], v[166:169], v[218:221], v[30:33]
	v_mfma_f32_16x16x32_bf16 v[26:29], v[174:177], v[218:221], v[26:29]
	v_mfma_f32_16x16x32_bf16 v[26:29], v[170:173], v[214:217], v[26:29]
	v_mfma_f32_16x16x32_bf16 v[10:13], v[170:173], v[222:225], v[10:13]
	v_mfma_f32_16x16x32_bf16 v[10:13], v[174:177], v[226:229], v[10:13]
	v_mfma_f32_16x16x32_bf16 v[14:17], v[166:169], v[226:229], v[14:17]
	v_mfma_f32_16x16x32_bf16 v[14:17], v[148:151], v[222:225], v[14:17]
	v_mfma_f32_16x16x32_bf16 v[54:57], v[178:181], v[194:197], v[54:57]
	v_mfma_f32_16x16x32_bf16 v[54:57], v[182:185], v[202:205], v[54:57]
	v_mfma_f32_16x16x32_bf16 v[50:53], v[190:193], v[202:205], v[50:53]
	v_mfma_f32_16x16x32_bf16 v[50:53], v[186:189], v[194:197], v[50:53]
	v_mfma_f32_16x16x32_bf16 v[34:37], v[186:189], v[206:209], v[34:37]
	v_mfma_f32_16x16x32_bf16 v[34:37], v[190:193], v[210:213], v[34:37]
	v_mfma_f32_16x16x32_bf16 v[38:41], v[182:185], v[210:213], v[38:41]
	v_mfma_f32_16x16x32_bf16 v[38:41], v[178:181], v[206:209], v[38:41]
	v_mfma_f32_16x16x32_bf16 v[22:25], v[178:181], v[214:217], v[22:25]
	v_mfma_f32_16x16x32_bf16 v[22:25], v[182:185], v[218:221], v[22:25]
	v_mfma_f32_16x16x32_bf16 v[18:21], v[190:193], v[218:221], v[18:21]
	v_mfma_f32_16x16x32_bf16 v[18:21], v[186:189], v[214:217], v[18:21]
	v_mfma_f32_16x16x32_bf16 v[2:5], v[186:189], v[222:225], v[2:5]
	v_mfma_f32_16x16x32_bf16 v[2:5], v[190:193], v[226:229], v[2:5]
	v_mfma_f32_16x16x32_bf16 v[6:9], v[182:185], v[226:229], v[6:9]
	v_mfma_f32_16x16x32_bf16 v[6:9], v[178:181], v[222:225], v[6:9]
	s_setprio 0
	s_barrier
	s_add_i32 s36, 0, 0x18000
	v_add_u32_e32 v140, s36, v154
	s_add_i32 s37, 0, 0x1c000
	ds_read_b128 v[148:151], v140
	ds_read_b128 v[166:169], v140 offset:1024
	ds_read_b128 v[170:173], v140 offset:2048
	ds_read_b128 v[174:177], v140 offset:3072
	v_add_u32_e32 v140, s37, v154
	ds_read_b128 v[178:181], v140
	ds_read_b128 v[182:185], v140 offset:1024
	ds_read_b128 v[186:189], v140 offset:2048
	ds_read_b128 v[190:193], v140 offset:3072
	s_add_u32 s60, s60, 0x2b0000
	s_addc_u32 s61, s61, 0
	s_mov_b32 m0, s69
	v_lshl_add_u64 v[232:233], s[60:61], 0, v[132:133]
	ds_read_b128 v[194:197], v158 offset:32768
	ds_read_b128 v[202:205], v158 offset:33792
	ds_read_b128 v[206:209], v158 offset:34816
	ds_read_b128 v[210:213], v158 offset:35840
	ds_read_b128 v[214:217], v158 offset:36864
	ds_read_b128 v[218:221], v158 offset:37888
	ds_read_b128 v[222:225], v158 offset:38912
	ds_read_b128 v[226:229], v158 offset:39936
	global_load_lds_dwordx4 v[232:233], off
	v_lshl_add_u64 v[232:233], s[60:61], 0, v[136:137]
	s_mov_b32 m0, s70
	s_nop 0
	global_load_lds_dwordx4 v[232:233], off
	s_waitcnt vmcnt(8)
	s_waitcnt lgkmcnt(0)
	s_barrier
	s_setprio 1
	v_mfma_f32_16x16x32_bf16 v[126:129], v[148:151], v[194:197], v[126:129]
	v_mfma_f32_16x16x32_bf16 v[126:129], v[166:169], v[202:205], v[126:129]
	v_mfma_f32_16x16x32_bf16 v[122:125], v[174:177], v[202:205], v[122:125]
	v_mfma_f32_16x16x32_bf16 v[122:125], v[170:173], v[194:197], v[122:125]
	v_mfma_f32_16x16x32_bf16 v[106:109], v[170:173], v[206:209], v[106:109]
	v_mfma_f32_16x16x32_bf16 v[106:109], v[174:177], v[210:213], v[106:109]
	v_mfma_f32_16x16x32_bf16 v[110:113], v[166:169], v[210:213], v[110:113]
	v_mfma_f32_16x16x32_bf16 v[110:113], v[148:151], v[206:209], v[110:113]
	v_mfma_f32_16x16x32_bf16 v[94:97], v[148:151], v[214:217], v[94:97]
	v_mfma_f32_16x16x32_bf16 v[94:97], v[166:169], v[218:221], v[94:97]
	v_mfma_f32_16x16x32_bf16 v[90:93], v[174:177], v[218:221], v[90:93]
	v_mfma_f32_16x16x32_bf16 v[90:93], v[170:173], v[214:217], v[90:93]
	v_mfma_f32_16x16x32_bf16 v[74:77], v[170:173], v[222:225], v[74:77]
	v_mfma_f32_16x16x32_bf16 v[74:77], v[174:177], v[226:229], v[74:77]
	v_mfma_f32_16x16x32_bf16 v[78:81], v[166:169], v[226:229], v[78:81]
	v_mfma_f32_16x16x32_bf16 v[78:81], v[148:151], v[222:225], v[78:81]
	v_mfma_f32_16x16x32_bf16 v[118:121], v[178:181], v[194:197], v[118:121]
	v_mfma_f32_16x16x32_bf16 v[118:121], v[182:185], v[202:205], v[118:121]
	v_mfma_f32_16x16x32_bf16 v[114:117], v[190:193], v[202:205], v[114:117]
	v_mfma_f32_16x16x32_bf16 v[114:117], v[186:189], v[194:197], v[114:117]
	v_mfma_f32_16x16x32_bf16 v[98:101], v[186:189], v[206:209], v[98:101]
	v_mfma_f32_16x16x32_bf16 v[98:101], v[190:193], v[210:213], v[98:101]
	v_mfma_f32_16x16x32_bf16 v[102:105], v[182:185], v[210:213], v[102:105]
	v_mfma_f32_16x16x32_bf16 v[102:105], v[178:181], v[206:209], v[102:105]
	v_mfma_f32_16x16x32_bf16 v[86:89], v[178:181], v[214:217], v[86:89]
	v_mfma_f32_16x16x32_bf16 v[86:89], v[182:185], v[218:221], v[86:89]
	v_mfma_f32_16x16x32_bf16 v[82:85], v[190:193], v[218:221], v[82:85]
	v_mfma_f32_16x16x32_bf16 v[82:85], v[186:189], v[214:217], v[82:85]
	v_mfma_f32_16x16x32_bf16 v[66:69], v[186:189], v[222:225], v[66:69]
	v_mfma_f32_16x16x32_bf16 v[66:69], v[190:193], v[226:229], v[66:69]
	v_mfma_f32_16x16x32_bf16 v[70:73], v[182:185], v[226:229], v[70:73]
	v_mfma_f32_16x16x32_bf16 v[70:73], v[178:181], v[222:225], v[70:73]
	s_setprio 0
	s_barrier
	s_add_i32 s36, s36, s64
	v_lshl_add_u64 v[152:153], v[152:153], 0, s[20:21]
	s_mov_b32 m0, s36
	ds_read_b128 v[194:197], v158 offset:49152
	ds_read_b128 v[202:205], v158 offset:50176
	ds_read_b128 v[206:209], v158 offset:51200
	ds_read_b128 v[210:213], v158 offset:52224
	ds_read_b128 v[214:217], v158 offset:53248
	ds_read_b128 v[218:221], v158 offset:54272
	ds_read_b128 v[222:225], v158 offset:55296
	ds_read_b128 v[226:229], v158 offset:56320
	global_load_lds_dwordx4 v[152:153], off
	s_add_i32 m0, s36, 0x2000
	s_add_u32 s58, s58, 0x2b0080
	v_lshl_add_u64 v[152:153], v[160:161], 0, s[20:21]
	s_addc_u32 s59, s59, 0
	s_add_i32 s36, s37, s64
	global_load_lds_dwordx4 v[152:153], off
	v_lshl_add_u64 v[152:153], s[58:59], 0, v[134:135]
	s_mov_b32 m0, s36
	s_nop 0
	global_load_lds_dwordx4 v[152:153], off
	v_lshl_add_u64 v[152:153], s[58:59], 0, v[138:139]
	s_add_i32 m0, s36, 0x2000
	s_nop 0
	global_load_lds_dwordx4 v[152:153], off
	v_lshl_add_u64 v[152:153], v[198:199], 0, s[20:21]
	s_mov_b32 m0, s73
	s_nop 0
	global_load_lds_dwordx4 v[152:153], off
	v_lshl_add_u64 v[152:153], v[230:231], 0, s[20:21]
	s_mov_b32 m0, s74
	s_nop 0
	global_load_lds_dwordx4 v[152:153], off
	s_waitcnt vmcnt(8)
	s_waitcnt lgkmcnt(0)
	s_barrier
	s_setprio 1
	v_mfma_f32_16x16x32_bf16 v[62:65], v[148:151], v[194:197], v[62:65]
	v_mfma_f32_16x16x32_bf16 v[62:65], v[166:169], v[202:205], v[62:65]
	v_mfma_f32_16x16x32_bf16 v[58:61], v[174:177], v[202:205], v[58:61]
	v_mfma_f32_16x16x32_bf16 v[58:61], v[170:173], v[194:197], v[58:61]
	v_mfma_f32_16x16x32_bf16 v[42:45], v[170:173], v[206:209], v[42:45]
	v_mfma_f32_16x16x32_bf16 v[42:45], v[174:177], v[210:213], v[42:45]
	v_mfma_f32_16x16x32_bf16 v[46:49], v[166:169], v[210:213], v[46:49]
	v_mfma_f32_16x16x32_bf16 v[46:49], v[148:151], v[206:209], v[46:49]
	v_mfma_f32_16x16x32_bf16 v[30:33], v[148:151], v[214:217], v[30:33]
	v_mfma_f32_16x16x32_bf16 v[30:33], v[166:169], v[218:221], v[30:33]
	v_mfma_f32_16x16x32_bf16 v[26:29], v[174:177], v[218:221], v[26:29]
	v_mfma_f32_16x16x32_bf16 v[26:29], v[170:173], v[214:217], v[26:29]
	v_mfma_f32_16x16x32_bf16 v[10:13], v[170:173], v[222:225], v[10:13]
	v_mfma_f32_16x16x32_bf16 v[10:13], v[174:177], v[226:229], v[10:13]
	v_mfma_f32_16x16x32_bf16 v[14:17], v[166:169], v[226:229], v[14:17]
	v_mfma_f32_16x16x32_bf16 v[14:17], v[148:151], v[222:225], v[14:17]
	v_mfma_f32_16x16x32_bf16 v[54:57], v[178:181], v[194:197], v[54:57]
	v_mfma_f32_16x16x32_bf16 v[54:57], v[182:185], v[202:205], v[54:57]
	v_mfma_f32_16x16x32_bf16 v[50:53], v[190:193], v[202:205], v[50:53]
	v_mfma_f32_16x16x32_bf16 v[50:53], v[186:189], v[194:197], v[50:53]
	v_mfma_f32_16x16x32_bf16 v[34:37], v[186:189], v[206:209], v[34:37]
	v_mfma_f32_16x16x32_bf16 v[34:37], v[190:193], v[210:213], v[34:37]
	v_mfma_f32_16x16x32_bf16 v[38:41], v[182:185], v[210:213], v[38:41]
	v_mfma_f32_16x16x32_bf16 v[38:41], v[178:181], v[206:209], v[38:41]
	v_mfma_f32_16x16x32_bf16 v[22:25], v[178:181], v[214:217], v[22:25]
	v_mfma_f32_16x16x32_bf16 v[22:25], v[182:185], v[218:221], v[22:25]
	v_mfma_f32_16x16x32_bf16 v[18:21], v[190:193], v[218:221], v[18:21]
	v_mfma_f32_16x16x32_bf16 v[18:21], v[186:189], v[214:217], v[18:21]
	v_mfma_f32_16x16x32_bf16 v[2:5], v[186:189], v[222:225], v[2:5]
	v_mfma_f32_16x16x32_bf16 v[2:5], v[190:193], v[226:229], v[2:5]
	v_mfma_f32_16x16x32_bf16 v[6:9], v[182:185], v[226:229], v[6:9]
	v_mfma_f32_16x16x32_bf16 v[6:9], v[178:181], v[222:225], v[6:9]
	s_setprio 0
	s_barrier
	s_add_u32 s56, s56, 0x100
	s_addc_u32 s57, s57, 0
	s_add_u32 s90, s90, 0x100
	s_addc_u32 s91, s91, 0
	s_cmp_ge_i32 s92, s39
	s_mov_b32 s58, s92
	s_cbranch_scc0 .LBB0_1902
	s_and_b64 vcc, exec, s[24:25]
	s_cbranch_vccz .LBB0_1905

.LBB0_2138:
	ds_read_b128 v[146:149], v157
	ds_read_b128 v[164:167], v157 offset:1024
	ds_read_b128 v[168:171], v157 offset:2048
	ds_read_b128 v[172:175], v157 offset:3072
	ds_read_b128 v[176:179], v158
	ds_read_b128 v[180:183], v158 offset:1024
	ds_read_b128 v[184:187], v158 offset:2048
	ds_read_b128 v[188:191], v158 offset:3072
	s_add_u32 s24, s22, 0xfff00080
	s_addc_u32 s25, s23, -1
	s_cmp_eq_u32 s54, 60
	s_cselect_b32 s35, s15, s25
	s_cselect_b32 s34, s50, s24
	s_cselect_b32 s25, s13, s53
	s_cselect_b32 s24, s51, s52
	v_lshl_add_u64 v[150:151], s[22:23], 0, v[138:139]
	s_add_i32 m0, s21, 0xc000
	ds_read_b128 v[192:195], v159
	ds_read_b128 v[196:199], v159 offset:1024
	ds_read_b128 v[200:203], v159 offset:2048
	ds_read_b128 v[204:207], v159 offset:3072
	ds_read_b128 v[208:211], v159 offset:4096
	ds_read_b128 v[212:215], v159 offset:5120
	ds_read_b128 v[216:219], v159 offset:6144
	ds_read_b128 v[220:223], v159 offset:7168
	global_load_lds_dwordx4 v[150:151], off
	v_lshl_add_u64 v[150:151], s[22:23], 0, v[140:141]
	s_add_i32 m0, s21, 0xe000
	s_nop 0
	global_load_lds_dwordx4 v[150:151], off
	s_waitcnt vmcnt(8)
	s_waitcnt lgkmcnt(0)
	s_barrier
	s_setprio 1
	v_mfma_f32_16x16x32_bf16 v[126:129], v[146:149], v[192:195], v[126:129]
	v_mfma_f32_16x16x32_bf16 v[126:129], v[164:167], v[196:199], v[126:129]
	v_mfma_f32_16x16x32_bf16 v[122:125], v[172:175], v[196:199], v[122:125]
	v_mfma_f32_16x16x32_bf16 v[122:125], v[168:171], v[192:195], v[122:125]
	v_mfma_f32_16x16x32_bf16 v[106:109], v[168:171], v[200:203], v[106:109]
	v_mfma_f32_16x16x32_bf16 v[106:109], v[172:175], v[204:207], v[106:109]
	v_mfma_f32_16x16x32_bf16 v[110:113], v[164:167], v[204:207], v[110:113]
	v_mfma_f32_16x16x32_bf16 v[110:113], v[146:149], v[200:203], v[110:113]
	v_mfma_f32_16x16x32_bf16 v[94:97], v[146:149], v[208:211], v[94:97]
	v_mfma_f32_16x16x32_bf16 v[94:97], v[164:167], v[212:215], v[94:97]
	v_mfma_f32_16x16x32_bf16 v[90:93], v[172:175], v[212:215], v[90:93]
	v_mfma_f32_16x16x32_bf16 v[90:93], v[168:171], v[208:211], v[90:93]
	v_mfma_f32_16x16x32_bf16 v[74:77], v[168:171], v[216:219], v[74:77]
	v_mfma_f32_16x16x32_bf16 v[74:77], v[172:175], v[220:223], v[74:77]
	v_mfma_f32_16x16x32_bf16 v[78:81], v[164:167], v[220:223], v[78:81]
	v_mfma_f32_16x16x32_bf16 v[78:81], v[146:149], v[216:219], v[78:81]
	v_mfma_f32_16x16x32_bf16 v[118:121], v[176:179], v[192:195], v[118:121]
	v_mfma_f32_16x16x32_bf16 v[118:121], v[180:183], v[196:199], v[118:121]
	v_mfma_f32_16x16x32_bf16 v[114:117], v[188:191], v[196:199], v[114:117]
	v_mfma_f32_16x16x32_bf16 v[114:117], v[184:187], v[192:195], v[114:117]
	v_mfma_f32_16x16x32_bf16 v[98:101], v[184:187], v[200:203], v[98:101]
	v_mfma_f32_16x16x32_bf16 v[98:101], v[188:191], v[204:207], v[98:101]
	v_mfma_f32_16x16x32_bf16 v[102:105], v[180:183], v[204:207], v[102:105]
	v_mfma_f32_16x16x32_bf16 v[102:105], v[176:179], v[200:203], v[102:105]
	v_mfma_f32_16x16x32_bf16 v[86:89], v[176:179], v[208:211], v[86:89]
	v_mfma_f32_16x16x32_bf16 v[86:89], v[180:183], v[212:215], v[86:89]
	v_mfma_f32_16x16x32_bf16 v[82:85], v[188:191], v[212:215], v[82:85]
	v_mfma_f32_16x16x32_bf16 v[82:85], v[184:187], v[208:211], v[82:85]
	v_mfma_f32_16x16x32_bf16 v[66:69], v[184:187], v[216:219], v[66:69]
	v_mfma_f32_16x16x32_bf16 v[66:69], v[188:191], v[220:223], v[66:69]
	v_mfma_f32_16x16x32_bf16 v[70:73], v[180:183], v[220:223], v[70:73]
	v_mfma_f32_16x16x32_bf16 v[70:73], v[176:179], v[216:219], v[70:73]
	s_setprio 0
	s_barrier
	s_add_i32 s55, s47, s27
	v_lshl_add_u64 v[150:151], s[24:25], 0, v[134:135]
	s_mov_b32 m0, s55
	ds_read_b128 v[192:195], v159 offset:16384
	ds_read_b128 v[196:199], v159 offset:17408
	ds_read_b128 v[200:203], v159 offset:18432
	ds_read_b128 v[204:207], v159 offset:19456
	ds_read_b128 v[208:211], v159 offset:20480
	ds_read_b128 v[212:215], v159 offset:21504
	ds_read_b128 v[216:219], v159 offset:22528
	ds_read_b128 v[220:223], v159 offset:23552
	global_load_lds_dwordx4 v[150:151], off
	s_add_i32 m0, s55, 0x2000
	s_add_u32 s56, s24, 0x100000
	v_lshl_add_u64 v[160:161], s[24:25], 0, v[130:131]
	s_addc_u32 s57, s25, 0
	s_add_i32 s55, s48, s27
	global_load_lds_dwordx4 v[160:161], off
	v_lshl_add_u64 v[224:225], s[56:57], 0, v[134:135]
	s_mov_b32 m0, s55
	v_lshl_add_u64 v[226:227], s[34:35], 0, v[132:133]
	global_load_lds_dwordx4 v[224:225], off
	v_lshl_add_u64 v[224:225], s[56:57], 0, v[130:131]
	s_add_i32 m0, s55, 0x2000
	s_nop 0
	global_load_lds_dwordx4 v[224:225], off
	v_lshl_add_u64 v[224:225], s[34:35], 0, v[136:137]
	s_mov_b32 m0, s21
	s_nop 0
	global_load_lds_dwordx4 v[224:225], off
	s_mov_b32 m0, s40
	s_nop 0
	global_load_lds_dwordx4 v[226:227], off
	s_waitcnt vmcnt(8)
	s_waitcnt lgkmcnt(0)
	s_barrier
	s_setprio 1
	v_mfma_f32_16x16x32_bf16 v[62:65], v[146:149], v[192:195], v[62:65]
	v_mfma_f32_16x16x32_bf16 v[62:65], v[164:167], v[196:199], v[62:65]
	v_mfma_f32_16x16x32_bf16 v[58:61], v[172:175], v[196:199], v[58:61]
	v_mfma_f32_16x16x32_bf16 v[58:61], v[168:171], v[192:195], v[58:61]
	v_mfma_f32_16x16x32_bf16 v[42:45], v[168:171], v[200:203], v[42:45]
	v_mfma_f32_16x16x32_bf16 v[42:45], v[172:175], v[204:207], v[42:45]
	v_mfma_f32_16x16x32_bf16 v[46:49], v[164:167], v[204:207], v[46:49]
	v_mfma_f32_16x16x32_bf16 v[46:49], v[146:149], v[200:203], v[46:49]
	v_mfma_f32_16x16x32_bf16 v[30:33], v[146:149], v[208:211], v[30:33]
	v_mfma_f32_16x16x32_bf16 v[30:33], v[164:167], v[212:215], v[30:33]
	v_mfma_f32_16x16x32_bf16 v[26:29], v[172:175], v[212:215], v[26:29]
	v_mfma_f32_16x16x32_bf16 v[26:29], v[168:171], v[208:211], v[26:29]
	v_mfma_f32_16x16x32_bf16 v[10:13], v[168:171], v[216:219], v[10:13]
	v_mfma_f32_16x16x32_bf16 v[10:13], v[172:175], v[220:223], v[10:13]
	v_mfma_f32_16x16x32_bf16 v[14:17], v[164:167], v[220:223], v[14:17]
	v_mfma_f32_16x16x32_bf16 v[14:17], v[146:149], v[216:219], v[14:17]
	v_mfma_f32_16x16x32_bf16 v[54:57], v[176:179], v[192:195], v[54:57]
	v_mfma_f32_16x16x32_bf16 v[54:57], v[180:183], v[196:199], v[54:57]
	v_mfma_f32_16x16x32_bf16 v[50:53], v[188:191], v[196:199], v[50:53]
	v_mfma_f32_16x16x32_bf16 v[50:53], v[184:187], v[192:195], v[50:53]
	v_mfma_f32_16x16x32_bf16 v[34:37], v[184:187], v[200:203], v[34:37]
	v_mfma_f32_16x16x32_bf16 v[34:37], v[188:191], v[204:207], v[34:37]
	v_mfma_f32_16x16x32_bf16 v[38:41], v[180:183], v[204:207], v[38:41]
	v_mfma_f32_16x16x32_bf16 v[38:41], v[176:179], v[200:203], v[38:41]
	v_mfma_f32_16x16x32_bf16 v[22:25], v[176:179], v[208:211], v[22:25]
	v_mfma_f32_16x16x32_bf16 v[22:25], v[180:183], v[212:215], v[22:25]
	v_mfma_f32_16x16x32_bf16 v[18:21], v[188:191], v[212:215], v[18:21]
	v_mfma_f32_16x16x32_bf16 v[18:21], v[184:187], v[208:211], v[18:21]
	v_mfma_f32_16x16x32_bf16 v[2:5], v[184:187], v[216:219], v[2:5]
	v_mfma_f32_16x16x32_bf16 v[2:5], v[188:191], v[220:223], v[2:5]
	v_mfma_f32_16x16x32_bf16 v[6:9], v[180:183], v[220:223], v[6:9]
	v_mfma_f32_16x16x32_bf16 v[6:9], v[176:179], v[216:219], v[6:9]
	s_setprio 0
	s_barrier
	s_add_i32 s55, 0, 0x18000
	v_add_u32_e32 v162, s55, v155
	s_add_i32 s56, 0, 0x1c000
	ds_read_b128 v[146:149], v162
	ds_read_b128 v[164:167], v162 offset:1024
	ds_read_b128 v[168:171], v162 offset:2048
	ds_read_b128 v[172:175], v162 offset:3072
	v_add_u32_e32 v162, s56, v155
	ds_read_b128 v[176:179], v162
	ds_read_b128 v[180:183], v162 offset:1024
	ds_read_b128 v[184:187], v162 offset:2048
	ds_read_b128 v[188:191], v162 offset:3072
	s_add_u32 s34, s34, 0x100000
	s_addc_u32 s35, s35, 0
	s_mov_b32 m0, s41
	v_lshl_add_u64 v[228:229], s[34:35], 0, v[136:137]
	ds_read_b128 v[192:195], v159 offset:32768
	ds_read_b128 v[196:199], v159 offset:33792
	ds_read_b128 v[200:203], v159 offset:34816
	ds_read_b128 v[204:207], v159 offset:35840
	ds_read_b128 v[208:211], v159 offset:36864
	ds_read_b128 v[212:215], v159 offset:37888
	ds_read_b128 v[216:219], v159 offset:38912
	ds_read_b128 v[220:223], v159 offset:39936
	global_load_lds_dwordx4 v[228:229], off
	v_lshl_add_u64 v[228:229], s[34:35], 0, v[132:133]
	s_mov_b32 m0, s42
	s_nop 0
	global_load_lds_dwordx4 v[228:229], off
	s_waitcnt vmcnt(8)
	s_waitcnt lgkmcnt(0)
	s_barrier
	s_setprio 1
	v_mfma_f32_16x16x32_bf16 v[126:129], v[146:149], v[192:195], v[126:129]
	v_mfma_f32_16x16x32_bf16 v[126:129], v[164:167], v[196:199], v[126:129]
	v_mfma_f32_16x16x32_bf16 v[122:125], v[172:175], v[196:199], v[122:125]
	v_mfma_f32_16x16x32_bf16 v[122:125], v[168:171], v[192:195], v[122:125]
	v_mfma_f32_16x16x32_bf16 v[106:109], v[168:171], v[200:203], v[106:109]
	v_mfma_f32_16x16x32_bf16 v[106:109], v[172:175], v[204:207], v[106:109]
	v_mfma_f32_16x16x32_bf16 v[110:113], v[164:167], v[204:207], v[110:113]
	v_mfma_f32_16x16x32_bf16 v[110:113], v[146:149], v[200:203], v[110:113]
	v_mfma_f32_16x16x32_bf16 v[94:97], v[146:149], v[208:211], v[94:97]
	v_mfma_f32_16x16x32_bf16 v[94:97], v[164:167], v[212:215], v[94:97]
	v_mfma_f32_16x16x32_bf16 v[90:93], v[172:175], v[212:215], v[90:93]
	v_mfma_f32_16x16x32_bf16 v[90:93], v[168:171], v[208:211], v[90:93]
	v_mfma_f32_16x16x32_bf16 v[74:77], v[168:171], v[216:219], v[74:77]
	v_mfma_f32_16x16x32_bf16 v[74:77], v[172:175], v[220:223], v[74:77]
	v_mfma_f32_16x16x32_bf16 v[78:81], v[164:167], v[220:223], v[78:81]
	v_mfma_f32_16x16x32_bf16 v[78:81], v[146:149], v[216:219], v[78:81]
	v_mfma_f32_16x16x32_bf16 v[118:121], v[176:179], v[192:195], v[118:121]
	v_mfma_f32_16x16x32_bf16 v[118:121], v[180:183], v[196:199], v[118:121]
	v_mfma_f32_16x16x32_bf16 v[114:117], v[188:191], v[196:199], v[114:117]
	v_mfma_f32_16x16x32_bf16 v[114:117], v[184:187], v[192:195], v[114:117]
	v_mfma_f32_16x16x32_bf16 v[98:101], v[184:187], v[200:203], v[98:101]
	v_mfma_f32_16x16x32_bf16 v[98:101], v[188:191], v[204:207], v[98:101]
	v_mfma_f32_16x16x32_bf16 v[102:105], v[180:183], v[204:207], v[102:105]
	v_mfma_f32_16x16x32_bf16 v[102:105], v[176:179], v[200:203], v[102:105]
	v_mfma_f32_16x16x32_bf16 v[86:89], v[176:179], v[208:211], v[86:89]
	v_mfma_f32_16x16x32_bf16 v[86:89], v[180:183], v[212:215], v[86:89]
	v_mfma_f32_16x16x32_bf16 v[82:85], v[188:191], v[212:215], v[82:85]
	v_mfma_f32_16x16x32_bf16 v[82:85], v[184:187], v[208:211], v[82:85]
	v_mfma_f32_16x16x32_bf16 v[66:69], v[184:187], v[216:219], v[66:69]
	v_mfma_f32_16x16x32_bf16 v[66:69], v[188:191], v[220:223], v[66:69]
	v_mfma_f32_16x16x32_bf16 v[70:73], v[180:183], v[220:223], v[70:73]
	v_mfma_f32_16x16x32_bf16 v[70:73], v[176:179], v[216:219], v[70:73]
	s_setprio 0
	s_barrier
	s_add_i32 s34, s55, s27
	v_lshl_add_u64 v[150:151], v[150:151], 0, s[8:9]
	s_mov_b32 m0, s34
	ds_read_b128 v[192:195], v159 offset:49152
	ds_read_b128 v[196:199], v159 offset:50176
	ds_read_b128 v[200:203], v159 offset:51200
	ds_read_b128 v[204:207], v159 offset:52224
	ds_read_b128 v[208:211], v159 offset:53248
	ds_read_b128 v[212:215], v159 offset:54272
	ds_read_b128 v[216:219], v159 offset:55296
	ds_read_b128 v[220:223], v159 offset:56320
	global_load_lds_dwordx4 v[150:151], off
	s_add_i32 m0, s34, 0x2000
	s_add_u32 s24, s24, 0x100080
	v_lshl_add_u64 v[150:151], v[160:161], 0, s[8:9]
	s_addc_u32 s25, s25, 0
	s_add_i32 s34, s56, s27
	global_load_lds_dwordx4 v[150:151], off
	v_lshl_add_u64 v[150:151], s[24:25], 0, v[134:135]
	s_mov_b32 m0, s34
	s_nop 0
	global_load_lds_dwordx4 v[150:151], off
	v_lshl_add_u64 v[150:151], s[24:25], 0, v[130:131]
	s_add_i32 m0, s34, 0x2000
	s_nop 0
	global_load_lds_dwordx4 v[150:151], off
	v_lshl_add_u64 v[150:151], v[224:225], 0, s[8:9]
	s_mov_b32 m0, s44
	s_nop 0
	global_load_lds_dwordx4 v[150:151], off
	v_lshl_add_u64 v[150:151], v[226:227], 0, s[8:9]
	s_mov_b32 m0, s45
	s_nop 0
	global_load_lds_dwordx4 v[150:151], off
	s_waitcnt vmcnt(8)
	s_waitcnt lgkmcnt(0)
	s_barrier
	s_setprio 1
	v_mfma_f32_16x16x32_bf16 v[62:65], v[146:149], v[192:195], v[62:65]
	v_mfma_f32_16x16x32_bf16 v[62:65], v[164:167], v[196:199], v[62:65]
	v_mfma_f32_16x16x32_bf16 v[58:61], v[172:175], v[196:199], v[58:61]
	v_mfma_f32_16x16x32_bf16 v[58:61], v[168:171], v[192:195], v[58:61]
	v_mfma_f32_16x16x32_bf16 v[42:45], v[168:171], v[200:203], v[42:45]
	v_mfma_f32_16x16x32_bf16 v[42:45], v[172:175], v[204:207], v[42:45]
	v_mfma_f32_16x16x32_bf16 v[46:49], v[164:167], v[204:207], v[46:49]
	v_mfma_f32_16x16x32_bf16 v[46:49], v[146:149], v[200:203], v[46:49]
	v_mfma_f32_16x16x32_bf16 v[30:33], v[146:149], v[208:211], v[30:33]
	v_mfma_f32_16x16x32_bf16 v[30:33], v[164:167], v[212:215], v[30:33]
	v_mfma_f32_16x16x32_bf16 v[26:29], v[172:175], v[212:215], v[26:29]
	v_mfma_f32_16x16x32_bf16 v[26:29], v[168:171], v[208:211], v[26:29]
	v_mfma_f32_16x16x32_bf16 v[10:13], v[168:171], v[216:219], v[10:13]
	v_mfma_f32_16x16x32_bf16 v[10:13], v[172:175], v[220:223], v[10:13]
	v_mfma_f32_16x16x32_bf16 v[14:17], v[164:167], v[220:223], v[14:17]
	v_mfma_f32_16x16x32_bf16 v[14:17], v[146:149], v[216:219], v[14:17]
	v_mfma_f32_16x16x32_bf16 v[54:57], v[176:179], v[192:195], v[54:57]
	v_mfma_f32_16x16x32_bf16 v[54:57], v[180:183], v[196:199], v[54:57]
	v_mfma_f32_16x16x32_bf16 v[50:53], v[188:191], v[196:199], v[50:53]
	v_mfma_f32_16x16x32_bf16 v[50:53], v[184:187], v[192:195], v[50:53]
	v_mfma_f32_16x16x32_bf16 v[34:37], v[184:187], v[200:203], v[34:37]
	v_mfma_f32_16x16x32_bf16 v[34:37], v[188:191], v[204:207], v[34:37]
	v_mfma_f32_16x16x32_bf16 v[38:41], v[180:183], v[204:207], v[38:41]
	v_mfma_f32_16x16x32_bf16 v[38:41], v[176:179], v[200:203], v[38:41]
	v_mfma_f32_16x16x32_bf16 v[22:25], v[176:179], v[208:211], v[22:25]
	v_mfma_f32_16x16x32_bf16 v[22:25], v[180:183], v[212:215], v[22:25]
	v_mfma_f32_16x16x32_bf16 v[18:21], v[188:191], v[212:215], v[18:21]
	v_mfma_f32_16x16x32_bf16 v[18:21], v[184:187], v[208:211], v[18:21]
	v_mfma_f32_16x16x32_bf16 v[2:5], v[184:187], v[216:219], v[2:5]
	v_mfma_f32_16x16x32_bf16 v[2:5], v[188:191], v[220:223], v[2:5]
	v_mfma_f32_16x16x32_bf16 v[6:9], v[180:183], v[220:223], v[6:9]
	v_mfma_f32_16x16x32_bf16 v[6:9], v[176:179], v[216:219], v[6:9]
	s_setprio 0
	s_barrier
	s_add_i32 s54, s54, 2
	s_add_u32 s22, s22, 0x100
	s_addc_u32 s23, s23, 0
	s_add_u32 s52, s52, 0x100
	s_addc_u32 s53, s53, 0
	s_cmp_gt_u32 s54, 61
	s_cbranch_scc0 .LBB0_2138
	s_and_b64 vcc, exec, s[10:11]
	s_cbranch_vccz .LBB0_2141
	s_barrier

.LBB0_2158:
	ds_read_b128 v[146:149], v157
	ds_read_b128 v[164:167], v157 offset:1024
	ds_read_b128 v[168:171], v157 offset:2048
	ds_read_b128 v[172:175], v157 offset:3072
	ds_read_b128 v[176:179], v158
	ds_read_b128 v[180:183], v158 offset:1024
	ds_read_b128 v[184:187], v158 offset:2048
	ds_read_b128 v[188:191], v158 offset:3072
	s_add_u32 s26, s24, 0xfff00080
	s_addc_u32 s27, s25, -1
	s_cmp_eq_u32 s52, 60
	s_cselect_b32 s35, s17, s27
	s_cselect_b32 s34, s48, s26
	s_cselect_b32 s27, s15, s51
	s_cselect_b32 s26, s49, s50
	v_lshl_add_u64 v[150:151], s[24:25], 0, v[138:139]
	s_add_i32 m0, s23, 0xc000
	ds_read_b128 v[192:195], v159
	ds_read_b128 v[196:199], v159 offset:1024
	ds_read_b128 v[200:203], v159 offset:2048
	ds_read_b128 v[204:207], v159 offset:3072
	ds_read_b128 v[208:211], v159 offset:4096
	ds_read_b128 v[212:215], v159 offset:5120
	ds_read_b128 v[216:219], v159 offset:6144
	ds_read_b128 v[220:223], v159 offset:7168
	global_load_lds_dwordx4 v[150:151], off
	v_lshl_add_u64 v[150:151], s[24:25], 0, v[140:141]
	s_add_i32 m0, s23, 0xe000
	s_nop 0
	global_load_lds_dwordx4 v[150:151], off
	s_waitcnt vmcnt(8)
	s_waitcnt lgkmcnt(0)
	s_barrier
	s_setprio 1
	v_mfma_f32_16x16x32_bf16 v[126:129], v[146:149], v[192:195], v[126:129]
	v_mfma_f32_16x16x32_bf16 v[126:129], v[164:167], v[196:199], v[126:129]
	v_mfma_f32_16x16x32_bf16 v[122:125], v[172:175], v[196:199], v[122:125]
	v_mfma_f32_16x16x32_bf16 v[122:125], v[168:171], v[192:195], v[122:125]
	v_mfma_f32_16x16x32_bf16 v[106:109], v[168:171], v[200:203], v[106:109]
	v_mfma_f32_16x16x32_bf16 v[106:109], v[172:175], v[204:207], v[106:109]
	v_mfma_f32_16x16x32_bf16 v[110:113], v[164:167], v[204:207], v[110:113]
	v_mfma_f32_16x16x32_bf16 v[110:113], v[146:149], v[200:203], v[110:113]
	v_mfma_f32_16x16x32_bf16 v[94:97], v[146:149], v[208:211], v[94:97]
	v_mfma_f32_16x16x32_bf16 v[94:97], v[164:167], v[212:215], v[94:97]
	v_mfma_f32_16x16x32_bf16 v[90:93], v[172:175], v[212:215], v[90:93]
	v_mfma_f32_16x16x32_bf16 v[90:93], v[168:171], v[208:211], v[90:93]
	v_mfma_f32_16x16x32_bf16 v[74:77], v[168:171], v[216:219], v[74:77]
	v_mfma_f32_16x16x32_bf16 v[74:77], v[172:175], v[220:223], v[74:77]
	v_mfma_f32_16x16x32_bf16 v[78:81], v[164:167], v[220:223], v[78:81]
	v_mfma_f32_16x16x32_bf16 v[78:81], v[146:149], v[216:219], v[78:81]
	v_mfma_f32_16x16x32_bf16 v[118:121], v[176:179], v[192:195], v[118:121]
	v_mfma_f32_16x16x32_bf16 v[118:121], v[180:183], v[196:199], v[118:121]
	v_mfma_f32_16x16x32_bf16 v[114:117], v[188:191], v[196:199], v[114:117]
	v_mfma_f32_16x16x32_bf16 v[114:117], v[184:187], v[192:195], v[114:117]
	v_mfma_f32_16x16x32_bf16 v[98:101], v[184:187], v[200:203], v[98:101]
	v_mfma_f32_16x16x32_bf16 v[98:101], v[188:191], v[204:207], v[98:101]
	v_mfma_f32_16x16x32_bf16 v[102:105], v[180:183], v[204:207], v[102:105]
	v_mfma_f32_16x16x32_bf16 v[102:105], v[176:179], v[200:203], v[102:105]
	v_mfma_f32_16x16x32_bf16 v[86:89], v[176:179], v[208:211], v[86:89]
	v_mfma_f32_16x16x32_bf16 v[86:89], v[180:183], v[212:215], v[86:89]
	v_mfma_f32_16x16x32_bf16 v[82:85], v[188:191], v[212:215], v[82:85]
	v_mfma_f32_16x16x32_bf16 v[82:85], v[184:187], v[208:211], v[82:85]
	v_mfma_f32_16x16x32_bf16 v[66:69], v[184:187], v[216:219], v[66:69]
	v_mfma_f32_16x16x32_bf16 v[66:69], v[188:191], v[220:223], v[66:69]
	v_mfma_f32_16x16x32_bf16 v[70:73], v[180:183], v[220:223], v[70:73]
	v_mfma_f32_16x16x32_bf16 v[70:73], v[176:179], v[216:219], v[70:73]
	s_setprio 0
	s_barrier
	s_add_i32 s53, s45, s38
	v_lshl_add_u64 v[150:151], s[26:27], 0, v[132:133]
	s_mov_b32 m0, s53
	ds_read_b128 v[192:195], v159 offset:16384
	ds_read_b128 v[196:199], v159 offset:17408
	ds_read_b128 v[200:203], v159 offset:18432
	ds_read_b128 v[204:207], v159 offset:19456
	ds_read_b128 v[208:211], v159 offset:20480
	ds_read_b128 v[212:215], v159 offset:21504
	ds_read_b128 v[216:219], v159 offset:22528
	ds_read_b128 v[220:223], v159 offset:23552
	global_load_lds_dwordx4 v[150:151], off
	s_add_i32 m0, s53, 0x2000
	s_add_u32 s54, s26, 0x100000
	v_lshl_add_u64 v[160:161], s[26:27], 0, v[134:135]
	s_addc_u32 s55, s27, 0
	s_add_i32 s53, s46, s38
	global_load_lds_dwordx4 v[160:161], off
	v_lshl_add_u64 v[224:225], s[54:55], 0, v[132:133]
	s_mov_b32 m0, s53
	v_lshl_add_u64 v[226:227], s[34:35], 0, v[136:137]
	global_load_lds_dwordx4 v[224:225], off
	v_lshl_add_u64 v[224:225], s[54:55], 0, v[134:135]
	s_add_i32 m0, s53, 0x2000
	s_nop 0
	global_load_lds_dwordx4 v[224:225], off
	v_lshl_add_u64 v[224:225], s[34:35], 0, v[130:131]
	s_mov_b32 m0, s23
	s_nop 0
	global_load_lds_dwordx4 v[224:225], off
	s_mov_b32 m0, s40
	s_nop 0
	global_load_lds_dwordx4 v[226:227], off
	s_waitcnt vmcnt(8)
	s_waitcnt lgkmcnt(0)
	s_barrier
	s_setprio 1
	v_mfma_f32_16x16x32_bf16 v[62:65], v[146:149], v[192:195], v[62:65]
	v_mfma_f32_16x16x32_bf16 v[62:65], v[164:167], v[196:199], v[62:65]
	v_mfma_f32_16x16x32_bf16 v[58:61], v[172:175], v[196:199], v[58:61]
	v_mfma_f32_16x16x32_bf16 v[58:61], v[168:171], v[192:195], v[58:61]
	v_mfma_f32_16x16x32_bf16 v[42:45], v[168:171], v[200:203], v[42:45]
	v_mfma_f32_16x16x32_bf16 v[42:45], v[172:175], v[204:207], v[42:45]
	v_mfma_f32_16x16x32_bf16 v[46:49], v[164:167], v[204:207], v[46:49]
	v_mfma_f32_16x16x32_bf16 v[46:49], v[146:149], v[200:203], v[46:49]
	v_mfma_f32_16x16x32_bf16 v[30:33], v[146:149], v[208:211], v[30:33]
	v_mfma_f32_16x16x32_bf16 v[30:33], v[164:167], v[212:215], v[30:33]
	v_mfma_f32_16x16x32_bf16 v[26:29], v[172:175], v[212:215], v[26:29]
	v_mfma_f32_16x16x32_bf16 v[26:29], v[168:171], v[208:211], v[26:29]
	v_mfma_f32_16x16x32_bf16 v[10:13], v[168:171], v[216:219], v[10:13]
	v_mfma_f32_16x16x32_bf16 v[10:13], v[172:175], v[220:223], v[10:13]
	v_mfma_f32_16x16x32_bf16 v[14:17], v[164:167], v[220:223], v[14:17]
	v_mfma_f32_16x16x32_bf16 v[14:17], v[146:149], v[216:219], v[14:17]
	v_mfma_f32_16x16x32_bf16 v[54:57], v[176:179], v[192:195], v[54:57]
	v_mfma_f32_16x16x32_bf16 v[54:57], v[180:183], v[196:199], v[54:57]
	v_mfma_f32_16x16x32_bf16 v[50:53], v[188:191], v[196:199], v[50:53]
	v_mfma_f32_16x16x32_bf16 v[50:53], v[184:187], v[192:195], v[50:53]
	v_mfma_f32_16x16x32_bf16 v[34:37], v[184:187], v[200:203], v[34:37]
	v_mfma_f32_16x16x32_bf16 v[34:37], v[188:191], v[204:207], v[34:37]
	v_mfma_f32_16x16x32_bf16 v[38:41], v[180:183], v[204:207], v[38:41]
	v_mfma_f32_16x16x32_bf16 v[38:41], v[176:179], v[200:203], v[38:41]
	v_mfma_f32_16x16x32_bf16 v[22:25], v[176:179], v[208:211], v[22:25]
	v_mfma_f32_16x16x32_bf16 v[22:25], v[180:183], v[212:215], v[22:25]
	v_mfma_f32_16x16x32_bf16 v[18:21], v[188:191], v[212:215], v[18:21]
	v_mfma_f32_16x16x32_bf16 v[18:21], v[184:187], v[208:211], v[18:21]
	v_mfma_f32_16x16x32_bf16 v[2:5], v[184:187], v[216:219], v[2:5]
	v_mfma_f32_16x16x32_bf16 v[2:5], v[188:191], v[220:223], v[2:5]
	v_mfma_f32_16x16x32_bf16 v[6:9], v[180:183], v[220:223], v[6:9]
	v_mfma_f32_16x16x32_bf16 v[6:9], v[176:179], v[216:219], v[6:9]
	s_setprio 0
	s_barrier
	s_add_i32 s53, 0, 0x18000
	v_add_u32_e32 v162, s53, v155
	s_add_i32 s54, 0, 0x1c000
	ds_read_b128 v[146:149], v162
	ds_read_b128 v[164:167], v162 offset:1024
	ds_read_b128 v[168:171], v162 offset:2048
	ds_read_b128 v[172:175], v162 offset:3072
	v_add_u32_e32 v162, s54, v155
	ds_read_b128 v[176:179], v162
	ds_read_b128 v[180:183], v162 offset:1024
	ds_read_b128 v[184:187], v162 offset:2048
	ds_read_b128 v[188:191], v162 offset:3072
	s_add_u32 s34, s34, 0x100000
	s_addc_u32 s35, s35, 0
	s_mov_b32 m0, s41
	v_lshl_add_u64 v[228:229], s[34:35], 0, v[130:131]
	ds_read_b128 v[192:195], v159 offset:32768
	ds_read_b128 v[196:199], v159 offset:33792
	ds_read_b128 v[200:203], v159 offset:34816
	ds_read_b128 v[204:207], v159 offset:35840
	ds_read_b128 v[208:211], v159 offset:36864
	ds_read_b128 v[212:215], v159 offset:37888
	ds_read_b128 v[216:219], v159 offset:38912
	ds_read_b128 v[220:223], v159 offset:39936
	global_load_lds_dwordx4 v[228:229], off
	v_lshl_add_u64 v[228:229], s[34:35], 0, v[136:137]
	s_mov_b32 m0, s42
	s_nop 0
	global_load_lds_dwordx4 v[228:229], off
	s_waitcnt vmcnt(8)
	s_waitcnt lgkmcnt(0)
	s_barrier
	s_setprio 1
	v_mfma_f32_16x16x32_bf16 v[126:129], v[146:149], v[192:195], v[126:129]
	v_mfma_f32_16x16x32_bf16 v[126:129], v[164:167], v[196:199], v[126:129]
	v_mfma_f32_16x16x32_bf16 v[122:125], v[172:175], v[196:199], v[122:125]
	v_mfma_f32_16x16x32_bf16 v[122:125], v[168:171], v[192:195], v[122:125]
	v_mfma_f32_16x16x32_bf16 v[106:109], v[168:171], v[200:203], v[106:109]
	v_mfma_f32_16x16x32_bf16 v[106:109], v[172:175], v[204:207], v[106:109]
	v_mfma_f32_16x16x32_bf16 v[110:113], v[164:167], v[204:207], v[110:113]
	v_mfma_f32_16x16x32_bf16 v[110:113], v[146:149], v[200:203], v[110:113]
	v_mfma_f32_16x16x32_bf16 v[94:97], v[146:149], v[208:211], v[94:97]
	v_mfma_f32_16x16x32_bf16 v[94:97], v[164:167], v[212:215], v[94:97]
	v_mfma_f32_16x16x32_bf16 v[90:93], v[172:175], v[212:215], v[90:93]
	v_mfma_f32_16x16x32_bf16 v[90:93], v[168:171], v[208:211], v[90:93]
	v_mfma_f32_16x16x32_bf16 v[74:77], v[168:171], v[216:219], v[74:77]
	v_mfma_f32_16x16x32_bf16 v[74:77], v[172:175], v[220:223], v[74:77]
	v_mfma_f32_16x16x32_bf16 v[78:81], v[164:167], v[220:223], v[78:81]
	v_mfma_f32_16x16x32_bf16 v[78:81], v[146:149], v[216:219], v[78:81]
	v_mfma_f32_16x16x32_bf16 v[118:121], v[176:179], v[192:195], v[118:121]
	v_mfma_f32_16x16x32_bf16 v[118:121], v[180:183], v[196:199], v[118:121]
	v_mfma_f32_16x16x32_bf16 v[114:117], v[188:191], v[196:199], v[114:117]
	v_mfma_f32_16x16x32_bf16 v[114:117], v[184:187], v[192:195], v[114:117]
	v_mfma_f32_16x16x32_bf16 v[98:101], v[184:187], v[200:203], v[98:101]
	v_mfma_f32_16x16x32_bf16 v[98:101], v[188:191], v[204:207], v[98:101]
	v_mfma_f32_16x16x32_bf16 v[102:105], v[180:183], v[204:207], v[102:105]
	v_mfma_f32_16x16x32_bf16 v[102:105], v[176:179], v[200:203], v[102:105]
	v_mfma_f32_16x16x32_bf16 v[86:89], v[176:179], v[208:211], v[86:89]
	v_mfma_f32_16x16x32_bf16 v[86:89], v[180:183], v[212:215], v[86:89]
	v_mfma_f32_16x16x32_bf16 v[82:85], v[188:191], v[212:215], v[82:85]
	v_mfma_f32_16x16x32_bf16 v[82:85], v[184:187], v[208:211], v[82:85]
	v_mfma_f32_16x16x32_bf16 v[66:69], v[184:187], v[216:219], v[66:69]
	v_mfma_f32_16x16x32_bf16 v[66:69], v[188:191], v[220:223], v[66:69]
	v_mfma_f32_16x16x32_bf16 v[70:73], v[180:183], v[220:223], v[70:73]
	v_mfma_f32_16x16x32_bf16 v[70:73], v[176:179], v[216:219], v[70:73]
	s_setprio 0
	s_barrier
	s_add_i32 s34, s53, s38
	v_lshl_add_u64 v[150:151], v[150:151], 0, s[10:11]
	s_mov_b32 m0, s34
	ds_read_b128 v[192:195], v159 offset:49152
	ds_read_b128 v[196:199], v159 offset:50176
	ds_read_b128 v[200:203], v159 offset:51200
	ds_read_b128 v[204:207], v159 offset:52224
	ds_read_b128 v[208:211], v159 offset:53248
	ds_read_b128 v[212:215], v159 offset:54272
	ds_read_b128 v[216:219], v159 offset:55296
	ds_read_b128 v[220:223], v159 offset:56320
	global_load_lds_dwordx4 v[150:151], off
	s_add_i32 m0, s34, 0x2000
	s_add_u32 s26, s26, 0x100080
	v_lshl_add_u64 v[150:151], v[160:161], 0, s[10:11]
	s_addc_u32 s27, s27, 0
	s_add_i32 s34, s54, s38
	global_load_lds_dwordx4 v[150:151], off
	v_lshl_add_u64 v[150:151], s[26:27], 0, v[132:133]
	s_mov_b32 m0, s34
	s_nop 0
	global_load_lds_dwordx4 v[150:151], off
	v_lshl_add_u64 v[150:151], s[26:27], 0, v[134:135]
	s_add_i32 m0, s34, 0x2000
	s_nop 0
	global_load_lds_dwordx4 v[150:151], off
	v_lshl_add_u64 v[150:151], v[224:225], 0, s[10:11]
	s_mov_b32 m0, s43
	s_nop 0
	global_load_lds_dwordx4 v[150:151], off
	v_lshl_add_u64 v[150:151], v[226:227], 0, s[10:11]
	s_mov_b32 m0, s44
	s_nop 0
	global_load_lds_dwordx4 v[150:151], off
	s_waitcnt vmcnt(8)
	s_waitcnt lgkmcnt(0)
	s_barrier
	s_setprio 1
	v_mfma_f32_16x16x32_bf16 v[62:65], v[146:149], v[192:195], v[62:65]
	v_mfma_f32_16x16x32_bf16 v[62:65], v[164:167], v[196:199], v[62:65]
	v_mfma_f32_16x16x32_bf16 v[58:61], v[172:175], v[196:199], v[58:61]
	v_mfma_f32_16x16x32_bf16 v[58:61], v[168:171], v[192:195], v[58:61]
	v_mfma_f32_16x16x32_bf16 v[42:45], v[168:171], v[200:203], v[42:45]
	v_mfma_f32_16x16x32_bf16 v[42:45], v[172:175], v[204:207], v[42:45]
	v_mfma_f32_16x16x32_bf16 v[46:49], v[164:167], v[204:207], v[46:49]
	v_mfma_f32_16x16x32_bf16 v[46:49], v[146:149], v[200:203], v[46:49]
	v_mfma_f32_16x16x32_bf16 v[30:33], v[146:149], v[208:211], v[30:33]
	v_mfma_f32_16x16x32_bf16 v[30:33], v[164:167], v[212:215], v[30:33]
	v_mfma_f32_16x16x32_bf16 v[26:29], v[172:175], v[212:215], v[26:29]
	v_mfma_f32_16x16x32_bf16 v[26:29], v[168:171], v[208:211], v[26:29]
	v_mfma_f32_16x16x32_bf16 v[10:13], v[168:171], v[216:219], v[10:13]
	v_mfma_f32_16x16x32_bf16 v[10:13], v[172:175], v[220:223], v[10:13]
	v_mfma_f32_16x16x32_bf16 v[14:17], v[164:167], v[220:223], v[14:17]
	v_mfma_f32_16x16x32_bf16 v[14:17], v[146:149], v[216:219], v[14:17]
	v_mfma_f32_16x16x32_bf16 v[54:57], v[176:179], v[192:195], v[54:57]
	v_mfma_f32_16x16x32_bf16 v[54:57], v[180:183], v[196:199], v[54:57]
	v_mfma_f32_16x16x32_bf16 v[50:53], v[188:191], v[196:199], v[50:53]
	v_mfma_f32_16x16x32_bf16 v[50:53], v[184:187], v[192:195], v[50:53]
	v_mfma_f32_16x16x32_bf16 v[34:37], v[184:187], v[200:203], v[34:37]
	v_mfma_f32_16x16x32_bf16 v[34:37], v[188:191], v[204:207], v[34:37]
	v_mfma_f32_16x16x32_bf16 v[38:41], v[180:183], v[204:207], v[38:41]
	v_mfma_f32_16x16x32_bf16 v[38:41], v[176:179], v[200:203], v[38:41]
	v_mfma_f32_16x16x32_bf16 v[22:25], v[176:179], v[208:211], v[22:25]
	v_mfma_f32_16x16x32_bf16 v[22:25], v[180:183], v[212:215], v[22:25]
	v_mfma_f32_16x16x32_bf16 v[18:21], v[188:191], v[212:215], v[18:21]
	v_mfma_f32_16x16x32_bf16 v[18:21], v[184:187], v[208:211], v[18:21]
	v_mfma_f32_16x16x32_bf16 v[2:5], v[184:187], v[216:219], v[2:5]
	v_mfma_f32_16x16x32_bf16 v[2:5], v[188:191], v[220:223], v[2:5]
	v_mfma_f32_16x16x32_bf16 v[6:9], v[180:183], v[220:223], v[6:9]
	v_mfma_f32_16x16x32_bf16 v[6:9], v[176:179], v[216:219], v[6:9]
	s_setprio 0
	s_barrier
	s_add_i32 s52, s52, 2
	s_add_u32 s24, s24, 0x100
	s_addc_u32 s25, s25, 0
	s_add_u32 s50, s50, 0x100
	s_addc_u32 s51, s51, 0
	s_cmp_gt_u32 s52, 61
	s_cbranch_scc0 .LBB0_2158
	s_and_b64 vcc, exec, s[12:13]
	s_cbranch_vccz .LBB0_2161
	s_barrier
